# deferred weight copies moved onto the waves that idle during the scan step loop (8k x 16n pieces, full-line bf16 stores), removed from the attention queue
# baseline (speedup 1.0000x reference)
; __device__ __forceinline__ int tidx() { int t = threadIdx.x; asm volatile("" : "+v"(t)); return t; }
; __device__ __forceinline__ const float* kin(int i) { KArgs* k = (KArgs*)__builtin_amdgcn_kernarg_segment_ptr(); return *(const float* const volatile __attribute__((address_space(4)))*)&k->in[i]; }
; __device__ __forceinline__ unsigned char* kws() { KArgs* k = (KArgs*)__builtin_amdgcn_kernarg_segment_ptr(); return *(unsigned char* const volatile __attribute__((address_space(4)))*)&k->ws; }
; __device__ __forceinline__ float* kout() { KArgs* k = (KArgs*)__builtin_amdgcn_kernarg_segment_ptr(); return *(float* const volatile __attribute__((address_space(4)))*)&k->out; }
; __device__ __forceinline__ void scan_block(unsigned char* shm, int sid, int half) {
;     const int tid = tidx(), lane = tid & 63, wid = __builtin_amdgcn_readfirstlane(tid >> 6), nr = lane >> 4, g = lane & 15, rowl = wid * 4 + nr;
;     const int dir = sid >> 6, b = (sid >> 4) & 3, h = sid & 15;
;     const bf16_t* XR = (const bf16_t*)(kws() + WS_XR); const bf16_t* XK = (const bf16_t*)(kws() + WS_XK); const bf16_t* XV = (const bf16_t*)(kws() + WS_XV); const bf16_t* KK = (const bf16_t*)(kws() + WS_KK);
;     const bf16_t* Z = (const bf16_t*)(kws() + WS_P);
;     bf16_t* Y = (bf16_t*)((unsigned char*)kout() + (dir ? DO_YB : DO_YF));
;     constexpr int TS = 32, NCH = (CTX + SEQ) / TS;
;     float* bufs = (float*)shm;
;     float* yst = (float*)(shm + 98304);
;     const int ss = tid >> 4, part = tid & 15;
;     float ka[4];
; #pragma unroll
;     for (int e = 0; e < 4; ++e) ka[e] = kin(20)[h * 64 + 4 * part + e];
;     u32x2 lr, lk, lv, lkk, le, li;
;     ...
;     SCAN_LOAD(0); SCAN_STORE(0);
;     __syncthreads();
.LBB0_782:
	s_lshl_b32 s2, s7, 4
	s_and_b32 s2, s2, 0x70
	s_ashr_i32 s18, s7, 4
	s_add_i32 s2, s2, s18
	v_mov_b32_e32 v4, v219
	s_cmp_lt_u32 s2, 64
	s_load_dwordx2 s[4:5], s[72:73], 0x140
	s_load_dwordx2 s[12:13], s[72:73], 0x140
	s_load_dwordx2 s[14:15], s[72:73], 0x140
	s_load_dwordx2 s[10:11], s[72:73], 0x140
	s_load_dwordx2 s[8:9], s[72:73], 0x140
	s_load_dwordx2 s[16:17], s[72:73], 0x138
	s_cselect_b64 s[38:39], -1, 0
	s_lshl_b32 s20, s18, 6
	s_load_dwordx2 s[18:19], s[72:73], 0xa0
	v_and_b32_e32 v1, 15, v4
	s_and_b32 s20, s20, 0x3c0
	v_lshlrev_b32_e32 v0, 2, v1
	v_or_b32_e32 v66, s20, v0
	v_lshlrev_b32_e32 v2, 2, v66
	s_waitcnt lgkmcnt(0)
	global_load_dword v68, v2, s[18:19]
	s_load_dwordx2 s[18:19], s[72:73], 0xa0
	v_ashrrev_i32_e32 v95, 4, v4
	v_readfirstlane_b32 s21, v4
	s_bfe_u32 s22, s2, 0x20004
	v_cmp_lt_i32_e32 vcc, s0, v95
	s_waitcnt lgkmcnt(0)
	global_load_dword v69, v2, s[18:19] offset:4
	s_load_dwordx2 s[18:19], s[72:73], 0xa0
	s_waitcnt lgkmcnt(0)
	global_load_dword v70, v2, s[18:19] offset:8
	s_load_dwordx2 s[18:19], s[72:73], 0xa0
	s_waitcnt lgkmcnt(0)
	global_load_dword v71, v2, s[18:19] offset:12
	s_and_saveexec_b64 s[18:19], vcc
	s_xor_b64 s[18:19], exec, s[18:19]
	v_sub_u32_e32 v2, 0x10ff, v95
	v_add_u32_e32 v3, 0xffffff00, v95
	s_lshl_b32 s24, s22, 8
	s_lshl_b32 s23, s22, 12
	v_cndmask_b32_e64 v2, v2, v3, s[38:39]
	s_bitset1_b32 s24, 14
	v_add_u32_e32 v2, s23, v2
	v_mov_b32_e32 v67, s24
	v_mov_b32_e32 v94, s23
	s_andn2_saveexec_b64 s[18:19], s[18:19]
	s_lshl_b32 s23, s22, 8
	v_sub_u32_e32 v2, 0xff, v95
	s_bitset1_b32 s23, 14
	v_cndmask_b32_e64 v2, v2, v95, s[38:39]
	s_lshl_b32 s22, s22, 12
	v_add_u32_e32 v2, s23, v2
	v_mov_b32_e32 v67, s23
	v_mov_b32_e32 v94, s22
	s_or_b64 exec, exec, s[18:19]
	s_ashr_i32 s21, s21, 4
	s_and_b64 s[18:19], s[38:39], exec
	s_cselect_b32 s18, 0, 0x2200000
	s_add_u32 s18, s16, s18
	s_addc_u32 s17, s17, 0
	s_add_u32 s4, s4, 0x1ba00000
	s_addc_u32 s5, s5, 0
	s_add_u32 s12, s12, 0x1dc00000
	s_addc_u32 s13, s13, 0
	s_add_u32 s40, s14, 0x1fe00000
	s_addc_u32 s41, s15, 0
	v_ashrrev_i32_e32 v3, 31, v2
	s_add_u32 s42, s10, 0x22000000
	v_lshlrev_b64 v[6:7], 11, v[2:3]
	v_lshl_or_b32 v6, v66, 1, v6
	s_addc_u32 s43, s11, 0
	v_lshl_add_u64 v[8:9], s[4:5], 0, v[6:7]
	s_add_u32 s8, s8, 0x11000000
	global_load_dwordx2 v[72:73], v[8:9], off
	s_addc_u32 s9, s9, 0
	v_lshl_add_u64 v[8:9], s[12:13], 0, v[6:7]
	s_lshl_b32 s2, s2, 4
	global_load_dwordx2 v[74:75], v[8:9], off
	s_and_b32 s10, s2, 0xfffffc00
	v_lshl_add_u64 v[8:9], s[40:41], 0, v[6:7]
	v_lshl_add_u64 v[6:7], s[42:43], 0, v[6:7]
	s_ashr_i32 s11, s10, 31
	global_load_dwordx2 v[78:79], v[6:7], off
	v_mov_b64_e32 v[6:7], s[8:9]
	v_mad_i64_i32 v[2:3], s[14:15], v2, s1, v[6:7]
	s_lshl_b64 s[10:11], s[10:11], 1
	v_lshl_add_u64 v[2:3], v[2:3], 0, s[10:11]
	s_lshl_b32 s2, s20, 1
	v_lshl_add_u64 v[2:3], v[2:3], 0, s[2:3]
	v_lshlrev_b32_e32 v64, 1, v0
	global_load_dwordx2 v[76:77], v[8:9], off
	v_lshl_add_u64 v[2:3], v[2:3], 0, v[64:65]
	s_movk_i32 s14, 0x1000
	global_load_dwordx2 v[80:81], v[2:3], off
	v_add_co_u32_e32 v2, vcc, s14, v2
	v_lshlrev_b32_e32 v5, 2, v0
	s_nop 0
	v_addc_co_u32_e32 v3, vcc, 0, v3, vcc
	global_load_dwordx2 v[82:83], v[2:3], off
	v_lshrrev_b32_e32 v2, 4, v4
	v_lshlrev_b32_e32 v3, 8, v95
	v_lshlrev_b32_e32 v4, 2, v4
	s_waitcnt vmcnt(17)
	v_bfi_b32 v18, -4, s21, v2
	v_add3_u32 v96, 0, v3, v5
	v_and_b32_e32 v97, 60, v4
	s_add_u32 s8, s8, s10
	s_addc_u32 s9, s9, s11
	s_add_u32 s8, s8, s2
	s_addc_u32 s9, s9, 0
	s_lshl_b32 s10, s7, 2
	s_and_b32 s10, s10, 32
	s_add_u32 s2, s18, s2
	v_lshl_add_u64 v[84:85], s[8:9], 0, v[64:65]
	s_addc_u32 s9, s17, 0
	s_lshl_b32 s8, s10, 1
	s_add_u32 s8, s2, s8
	s_addc_u32 s9, s9, 0
	s_mov_b32 s16, 0
	v_lshlrev_b32_e32 v98, 7, v95
	v_sub_u32_e32 v99, 0, v95
	v_lshlrev_b32_e32 v100, 2, v18
	s_lshl_b32 s2, s10, 2
	s_mov_b32 s11, 0
	s_waitcnt vmcnt(5)
	v_lshlrev_b32_e32 v2, 16, v72
	v_and_b32_e32 v3, 0xffff0000, v72
	v_lshlrev_b32_e32 v4, 16, v73
	v_and_b32_e32 v5, 0xffff0000, v73
	ds_write_b128 v96, v[2:5] offset:32768
	s_waitcnt vmcnt(4)
	v_lshlrev_b32_e32 v6, 16, v74
	v_and_b32_e32 v7, 0xffff0000, v74
	v_lshlrev_b32_e32 v8, 16, v75
	v_and_b32_e32 v9, 0xffff0000, v75
	s_waitcnt vmcnt(3)
	v_lshlrev_b32_e32 v10, 16, v78
	v_and_b32_e32 v11, 0xffff0000, v78
	v_lshlrev_b32_e32 v12, 16, v79
	v_and_b32_e32 v13, 0xffff0000, v79
	s_waitcnt vmcnt(2)
	v_lshlrev_b32_e32 v2, 16, v76
	v_and_b32_e32 v3, 0xffff0000, v76
	v_lshlrev_b32_e32 v4, 16, v77
	v_and_b32_e32 v5, 0xffff0000, v77
	ds_write_b128 v96, v[2:5] offset:40960
	v_xor_b32_e32 v5, 0x80000000, v13
	v_xor_b32_e32 v4, 0x80000000, v12
	v_xor_b32_e32 v3, 0x80000000, v11
	v_xor_b32_e32 v2, 0x80000000, v10
	ds_write_b128 v96, v[2:5] offset:8192
	s_waitcnt vmcnt(1)
	v_lshlrev_b32_e32 v2, 16, v80
	v_and_b32_e32 v3, 0xffff0000, v80
	v_lshlrev_b32_e32 v4, 16, v81
	v_and_b32_e32 v5, 0xffff0000, v81
	s_waitcnt vmcnt(0)
	v_lshlrev_b32_e32 v14, 16, v82
	v_and_b32_e32 v15, 0xffff0000, v82
	v_lshlrev_b32_e32 v16, 16, v83
	v_and_b32_e32 v17, 0xffff0000, v83
	v_sub_f32_e32 v5, 1.0, v5
	v_sub_f32_e32 v4, 1.0, v4
	v_sub_f32_e32 v3, 1.0, v3
	v_sub_f32_e32 v2, 1.0, v2
	ds_write_b128 v96, v[2:5]
	v_pk_mul_f32 v[4:5], v[12:13], v[16:17]
	v_pk_mul_f32 v[2:3], v[10:11], v[14:15]
	v_pk_add_f32 v[10:11], v[16:17], -1.0 op_sel_hi:[1,0]
	v_pk_add_f32 v[12:13], v[14:15], -1.0 op_sel_hi:[1,0]
	ds_write_b128 v96, v[2:5] offset:16384
	v_pk_fma_f32 v[2:3], v[68:69], v[12:13], 1.0 op_sel_hi:[1,1,0]
	v_pk_fma_f32 v[4:5], v[70:71], v[10:11], 1.0 op_sel_hi:[1,1,0]
	v_pk_mul_f32 v[2:3], v[2:3], v[6:7]
	v_pk_mul_f32 v[4:5], v[4:5], v[8:9]
	ds_write_b128 v96, v[2:5] offset:24576
	v_lshlrev_b32_e32 v2, 1, v1
	v_mov_b32_e32 v1, v65
	v_lshl_add_u64 v[86:87], s[8:9], 0, v[0:1]
	v_mov_b32_e32 v0, 0
	v_lshlrev_b32_e32 v101, 2, v2
	v_mov_b32_e32 v1, v0
	v_mov_b32_e32 v2, v0
	v_mov_b32_e32 v3, v0
	v_mov_b32_e32 v6, v0
	v_mov_b32_e32 v7, v0
	v_mov_b32_e32 v8, v0
	v_readfirstlane_b32 s44, v219
	s_lshr_b32 s44, s44, 6
	v_and_b32_e32 v136, 63, v219
	v_and_b32_e32 v130, 7, v136
	v_lshlrev_b32_e32 v130, 5, v130
	v_lshrrev_b32_e32 v131, 3, v136
	v_lshl_add_u32 v131, s44, 3, v131
	v_lshlrev_b32_e32 v131, 2, v131
	v_bfe_u32 v132, v136, 2, 1
	v_lshlrev_b32_e32 v132, 7, v132
	v_mov_b32_e32 v122, 0
	v_mov_b32_e32 v123, 0
	v_mov_b32_e32 v124, 0
	v_mov_b32_e32 v125, 0
	v_mov_b32_e32 v126, 0
	v_mov_b32_e32 v127, 0
	v_mov_b32_e32 v128, 0
	v_mov_b32_e32 v129, 0
	s_mov_b32 s45, 0
	s_cmpk_lg_i32 s76, 0x100
	s_cbranch_scc1 .Ltr_setup_done
; __device__ __forceinline__ unsigned pk2(float lo, float hi) { return f2bf(lo) | (f2bf(hi) << 16); }
; #define c opq(blockIdx.x)
; __device__ __forceinline__ void transpose_item(const float* W, int K, int N, bf16_t* WT, float* scr, int item, int lane) {
;     const int nblk = N / 32, kb = item / nblk, nb = item % nblk, k0 = 64 * kb, n0 = 32 * nb;
;     const int r = lane >> 3, c4 = lane & 7;
;     f32x4 v[8];
; #pragma unroll
;     for (int i = 0; i < 8; ++i) v[i] = __builtin_nontemporal_load((const f32x4*)(W + (size_t)(k0 + 8 * i + r) * N + n0 + 4 * c4));
; #pragma unroll
;     for (int i = 0; i < 8; ++i) { float* d = scr + (8 * i + r) * 33 + 4 * c4; d[0] = v[i].x; d[1] = v[i].y; d[2] = v[i].z; d[3] = v[i].w; }
;     __builtin_amdgcn_wave_barrier(); asm volatile("s_waitcnt lgkmcnt(0)" ::: "memory");
;     const int c = lane & 7;
; #pragma unroll
;     for (int j = 0; j < 4; ++j) { const int n = (lane >> 3) + 8 * j; const float* s = scr + (8 * c) * 33 + n;
;         u32x4 o; o.x = pk2(s[0 * 33], s[1 * 33]); o.y = pk2(s[2 * 33], s[3 * 33]); o.z = pk2(s[4 * 33], s[5 * 33]); o.w = pk2(s[6 * 33], s[7 * 33]);
;         *(u32x4*)(WT + (size_t)(n0 + n) * K + k0 + 8 * c) = o; }
;     __builtin_amdgcn_wave_barrier(); asm volatile("s_waitcnt lgkmcnt(0)" ::: "memory");
; }
; __device__ __forceinline__ void transpose_deferred(int r, float* scr, int lane) {
;     constexpr int I_O = 32 * 64, I_W1 = 32 * 256, I_W2 = 128 * 64, I_QKV = 32 * 192;
;     if (r < I_O) { transpose_item(kin(26), 2048, 2048, (bf16_t*)(kws() + WS_WO0), scr, r, lane); return; } r -= I_O;
;     if (r < I_W1) { transpose_item(kin(27), 2048, 8192, (bf16_t*)(kws() + WS_W10), scr, r, lane); return; } r -= I_W1;
;     if (r < I_W2) { transpose_item(kin(28), 8192, 2048, (bf16_t*)(kws() + WS_W20), scr, r, lane); return; } r -= I_W2;
;     if (r < I_QKV) { transpose_item(kin(33), 2048, 6144, (bf16_t*)(kws() + WS_WQKV), scr, r, lane); return; } r -= I_QKV;
;     if (r < I_O) { transpose_item(kin(35), 2048, 2048, (bf16_t*)(kws() + WS_WO1), scr, r, lane); return; } r -= I_O;
;     if (r < I_W1) { transpose_item(kin(36), 2048, 8192, (bf16_t*)(kws() + WS_W11), scr, r, lane); return; } r -= I_W1;
;     transpose_item(kin(37), 8192, 2048, (bf16_t*)(kws() + WS_W21), scr, r, lane);
	s_cmp_lt_u32 s44, 4
	s_cbranch_scc1 .Ltr_setup_done
	s_lshl_b32 s46, s74, 2
	s_add_i32 s47, s44, s46
	s_sub_i32 s47, s47, 4
	s_cmpk_ge_u32 s47, 0x2a0
	s_cbranch_scc1 .Ltr_setup_done
	s_mov_b32 s45, 1
	s_mov_b32 s64, s47
	s_movk_i32 s46, 0x128
	s_mov_b32 s47, 0xa600000
	s_mov_b32 s48, 7
	s_movk_i32 s49, 0x800
	s_movk_i32 s50, 0x220
	s_cmpk_lt_u32 s64, 0x220
	s_cselect_b32 s46, 0x120, s46
	s_cselect_b32 s47, 0x8600000, s47
	s_cselect_b32 s48, 5, s48
	s_cselect_b32 s49, 0x2000, s49
	s_cselect_b32 s50, 0x1a0, s50
	s_cmpk_lt_u32 s64, 0x1a0
	s_cselect_b32 s46, 0x118, s46
	s_cselect_b32 s47, 0x7e00000, s47
	s_cselect_b32 s48, 5, s48
	s_cselect_b32 s49, 0x800, s49
	s_cselect_b32 s50, 0x180, s50
	s_cmpk_lt_u32 s64, 0x180
	s_cselect_b32 s46, 0x108, s46
	s_cselect_b32 s47, 0x6600000, s47
	s_cselect_b32 s48, 5, s48
	s_cselect_b32 s49, 0x1800, s49
	s_cselect_b32 s50, 0x120, s50
	s_cmpk_lt_u32 s64, 0x120
	s_cselect_b32 s46, 0xe0, s46
	s_cselect_b32 s47, 0x4600000, s47
	s_cselect_b32 s48, 7, s48
	s_cselect_b32 s49, 0x800, s49
	s_cselect_b32 s50, 0xa0, s50
	s_cmpk_lt_u32 s64, 0xa0
	s_cselect_b32 s46, 0xd8, s46
	s_cselect_b32 s47, 0x2600000, s47
	s_cselect_b32 s48, 5, s48
	s_cselect_b32 s49, 0x2000, s49
	s_cselect_b32 s50, 0x20, s50
	s_cmpk_lt_u32 s64, 0x20
	s_cselect_b32 s46, 0xd0, s46
	s_cselect_b32 s47, 0x1e00000, s47
	s_cselect_b32 s48, 5, s48
	s_cselect_b32 s49, 0x800, s49
	s_cselect_b32 s50, 0x0, s50
	s_sub_i32 s64, s64, s50
	s_lshl_b32 s52, 1, s48
	s_sub_i32 s52, s52, 1
	s_and_b32 s52, s64, s52
	s_lshl_b32 s52, s52, 6
	s_lshr_b32 s51, s64, s48
	s_lshl_b32 s51, s51, 11
	s_add_i32 s53, s48, 6
	s_mul_i32 s54, s52, s49
	s_add_i32 s54, s54, s51
	s_lshl_b32 s54, s54, 2
	s_load_dwordx2 s[56:57], s[72:73], s46
	s_load_dwordx2 s[58:59], s[72:73], 0x140
	s_waitcnt lgkmcnt(0)
	s_add_u32 s56, s56, s54
	s_addc_u32 s57, s57, 0
	s_lshl_b32 s60, s51, s53
	s_add_i32 s60, s60, s52
	s_lshl_b32 s60, s60, 1
	s_add_u32 s60, s60, s47
	s_add_u32 s58, s58, s60
	s_addc_u32 s59, s59, 0
	v_and_b32_e32 v118, 63, v219
	v_and_b32_e32 v106, 7, v118
	v_lshrrev_b32_e32 v107, 3, v118
	s_lshl_b32 s61, s49, 5
	v_mul_u32_u24_e32 v118, s61, v106
	v_lshl_add_u32 v118, v107, 2, v118
	v_mov_b32_e32 v119, 0
	v_lshl_add_u64 v[210:211], s[56:57], 0, v[118:119]
	s_add_i32 s61, s53, 1
	v_lshlrev_b32_e32 v120, s61, v107
	v_lshl_add_u32 v120, v106, 4, v120
	v_mov_b32_e32 v121, 0
	v_lshl_add_u64 v[212:213], s[58:59], 0, v[120:121]
	s_lshl_b32 s54, s49, 2
	s_mov_b32 s55, 0
	s_mul_i32 s58, s54, 7
	s_sub_u32 s58, 64, s58
	s_mov_b32 s59, -1
	s_lshl_b32 s56, 16, s53
	s_mov_b32 s57, 0
.Ltr_setup_done:
	s_waitcnt lgkmcnt(0)
	s_barrier
	s_branch .LBB0_788

; template <int CTRL> __device__ __forceinline__ float dppf(float x) { return __builtin_bit_cast(float, __builtin_amdgcn_mov_dpp(__builtin_bit_cast(int, x), CTRL, 0xf, 0xf, true)); }
; #define LDOPS(s_) do { const float* p_ = bb + (s_) * 64; w4[(s_) % 3] = *(const f32x4*)(p_); a4[(s_) % 3] = *(const f32x4*)(p_ + 2048); b4[(s_) % 3] = *(const f32x4*)(p_ + 4096); k4[(s_) % 3] = *(const f32x4*)(p_ + 6144); \
;               r4[(s_) % 3] = *(const f32x4*)(p_ + 8192); vv[(s_) % 3] = vb[(s_) * 64]; } while (0)
; #define c opq(blockIdx.x)
; __device__ __forceinline__ void scan_block(unsigned char* shm, int sid, int half) {
;     ...
;     for (int c = 0; c < NCH; ++c) {
;         if (c + 1 < NCH) SCAN_LOAD(c + 1);
;         { const float* bb = bufs + (c & 1) * 12288 + 4 * g; float* ys = yst + (c & 1) * 1024 + rowl; const float* vb = bufs + (c & 1) * 12288 + 5 * 2048 + half * 32 + rowl;
;           f32x4 w4[3], a4[3], b4[3], k4[3], r4[3]; float vv[3];
;     ...
;           LDOPS(0); LDOPS(1);
; #pragma unroll
;           for (int s = 0; s < TS; ++s) {
;               const f32x4 a_ = a4[s % 3], w_ = w4[s % 3], b_ = b4[s % 3], k_ = k4[s % 3], r_ = r4[s % 3];
;               const float av[4] = {a_.x, a_.y, a_.z, a_.w}, wv[4] = {w_.x, w_.y, w_.z, w_.w}, bv[4] = {b_.x, b_.y, b_.z, b_.w}, kv[4] = {k_.x, k_.y, k_.z, k_.w}, rv[4] = {r_.x, r_.y, r_.z, r_.w};
;               const float v1 = vv[s % 3];
;               if (s + 2 < TS) LDOPS(s + 2);
;               float t = S[0] * av[0]; t = fmaf(S[1], av[1], t); t = fmaf(S[2], av[2], t); t = fmaf(S[3], av[3], t);
;               t += dppf<0xB1>(t); t += dppf<0x4E>(t); t += dppf<0x141>(t); t += dppf<0x140>(t);
; #pragma unroll
;               for (int q = 0; q < 4; ++q) S[q] = fmaf(S[q], wv[q], fmaf(bv[q], t, kv[q] * v1));
;               float u = S[0] * rv[0]; u = fmaf(S[1], rv[1], u); u = fmaf(S[2], rv[2], u); u = fmaf(S[3], rv[3], u);
;               u += dppf<0xB1>(u); u += dppf<0x4E>(u); u += dppf<0x141>(u); u += dppf<0x140>(u);
;               ys[s * 32] = u;
;           }
.LBB0_794:
	s_and_b32 s8, s11, 1
	s_mul_i32 s9, s8, 0xc000
	s_add_i32 s9, s9, 0
	v_add_u32_e32 v133, s9, v130
	s_add_i32 s9, s9, s2
	v_add_u32_e32 v134, s9, v131
	s_lshl_b32 s8, s8, 12
	s_add_i32 s8, s8, 0
	s_add_i32 s8, s8, 0x18000
	v_add3_u32 v135, s8, v131, v132
	s_add_i32 s10, s11, 1
	s_andn2_b64 vcc, exec, s[14:15]
	s_cmp_ge_u32 s44, 4
	s_cbranch_scc1 .Ltr_loads
	ds_read_b128 v[140:143], v133 offset:8192
	ds_read_b128 v[144:147], v133 offset:8208
	ds_read_b128 v[148:151], v133 offset:24576
	ds_read_b128 v[152:155], v133 offset:24592
	ds_read2st64_b32 v[106:107], v134 offset0:160 offset1:161
	ds_read_b128 v[176:179], v133 offset:0
	ds_read_b128 v[180:183], v133 offset:16
	ds_read_b128 v[184:187], v133 offset:16384
	ds_read_b128 v[188:191], v133 offset:16400
	ds_read_b128 v[192:195], v133 offset:32768
	ds_read_b128 v[196:199], v133 offset:32784
	ds_read_b128 v[158:161], v133 offset:8448
	ds_read_b128 v[162:165], v133 offset:8464
	ds_read_b128 v[166:169], v133 offset:24832
	ds_read_b128 v[170:173], v133 offset:24848
	s_waitcnt lgkmcnt(10)
	v_mul_f32_e32 v136, v122, v140
	v_mul_f32_e32 v112, v148, v106
	v_fmac_f32_e32 v136, v123, v141
	v_mul_f32_e32 v113, v149, v106
	v_fmac_f32_e32 v136, v124, v142
	v_mul_f32_e32 v114, v150, v106
	v_fmac_f32_e32 v136, v125, v143
	v_mul_f32_e32 v115, v151, v106
	v_fmac_f32_e32 v136, v126, v144
	v_mul_f32_e32 v116, v152, v106
	v_fmac_f32_e32 v136, v127, v145
	v_mul_f32_e32 v117, v153, v106
	v_fmac_f32_e32 v136, v128, v146
	v_mul_f32_e32 v118, v154, v106
	v_fmac_f32_e32 v136, v129, v147
	v_mul_f32_e32 v119, v155, v106
	s_nop 0
	v_add_f32_dpp v136, v136, v136 quad_perm:[1,0,3,2] row_mask:0xf bank_mask:0xf bound_ctrl:1
	s_nop 1
	v_add_f32_dpp v136, v136, v136 quad_perm:[2,3,0,1] row_mask:0xf bank_mask:0xf bound_ctrl:1
	s_nop 1
	v_add_f32_dpp v136, v136, v136 row_half_mirror row_mask:0xf bank_mask:0xf bound_ctrl:1
	ds_read_b128 v[140:143], v133 offset:8704
	ds_read_b128 v[144:147], v133 offset:8720
	ds_read_b128 v[148:151], v133 offset:25088
	ds_read_b128 v[152:155], v133 offset:25104
	ds_read2st64_b32 v[108:109], v134 offset0:162 offset1:163
	ds_read_b128 v[32:35], v133 offset:256
	ds_read_b128 v[36:39], v133 offset:272
	ds_read_b128 v[40:43], v133 offset:16640
	ds_read_b128 v[44:47], v133 offset:16656
	ds_read_b128 v[48:51], v133 offset:33024
	ds_read_b128 v[52:55], v133 offset:33040
	s_waitcnt lgkmcnt(11)
	v_fmac_f32_e32 v112, v184, v136
	v_fmac_f32_e32 v113, v185, v136
	v_fmac_f32_e32 v114, v186, v136
	v_fmac_f32_e32 v115, v187, v136
	v_fmac_f32_e32 v116, v188, v136
	v_fmac_f32_e32 v117, v189, v136
	v_fmac_f32_e32 v118, v190, v136
	v_fmac_f32_e32 v119, v191, v136
	v_fma_f32 v122, v122, v176, v112
	v_fma_f32 v123, v123, v177, v113
	v_fma_f32 v124, v124, v178, v114
	v_fma_f32 v125, v125, v179, v115
	v_fma_f32 v126, v126, v180, v116
	v_fma_f32 v127, v127, v181, v117
	v_fma_f32 v128, v128, v182, v118
	v_fma_f32 v129, v129, v183, v119
	v_mul_f32_e32 v136, v122, v158
	v_mul_f32_e32 v137, v192, v122
	v_fmac_f32_e32 v136, v123, v159
	v_fmac_f32_e32 v137, v123, v193
	v_fmac_f32_e32 v136, v124, v160
	v_fmac_f32_e32 v137, v124, v194
	v_fmac_f32_e32 v136, v125, v161
	v_fmac_f32_e32 v137, v125, v195
	v_fmac_f32_e32 v136, v126, v162
	v_fmac_f32_e32 v137, v126, v196
	v_fmac_f32_e32 v136, v127, v163
	v_fmac_f32_e32 v137, v127, v197
	v_fmac_f32_e32 v136, v128, v164
	v_fmac_f32_e32 v137, v128, v198
	v_fmac_f32_e32 v136, v129, v165
	v_fmac_f32_e32 v137, v129, v199
	v_mul_f32_e32 v112, v166, v107
	v_mul_f32_e32 v113, v167, v107
	v_add_f32_dpp v136, v136, v136 quad_perm:[1,0,3,2] row_mask:0xf bank_mask:0xf bound_ctrl:1
	v_mul_f32_e32 v114, v168, v107
	v_mul_f32_e32 v115, v169, v107
	v_add_f32_dpp v136, v136, v136 quad_perm:[2,3,0,1] row_mask:0xf bank_mask:0xf bound_ctrl:1
	v_mul_f32_e32 v116, v170, v107
	v_mul_f32_e32 v117, v171, v107
	v_add_f32_dpp v136, v136, v136 row_half_mirror row_mask:0xf bank_mask:0xf bound_ctrl:1
	v_mul_f32_e32 v118, v172, v107
	v_mul_f32_e32 v119, v173, v107
	ds_read_b128 v[158:161], v133 offset:8960
	ds_read_b128 v[162:165], v133 offset:8976
	ds_read_b128 v[166:169], v133 offset:25344
	ds_read_b128 v[170:173], v133 offset:25360
	ds_read_b128 v[176:179], v133 offset:512
	ds_read_b128 v[180:183], v133 offset:528
	ds_read_b128 v[184:187], v133 offset:16896
	ds_read_b128 v[188:191], v133 offset:16912
	ds_read_b128 v[192:195], v133 offset:33280
	ds_read_b128 v[196:199], v133 offset:33296
	s_waitcnt lgkmcnt(10)
; template <int CTRL> __device__ __forceinline__ float dppf(float x) { return __builtin_bit_cast(float, __builtin_amdgcn_mov_dpp(__builtin_bit_cast(int, x), CTRL, 0xf, 0xf, true)); }
; #define LDOPS(s_) do { const float* p_ = bb + (s_) * 64; w4[(s_) % 3] = *(const f32x4*)(p_); a4[(s_) % 3] = *(const f32x4*)(p_ + 2048); b4[(s_) % 3] = *(const f32x4*)(p_ + 4096); k4[(s_) % 3] = *(const f32x4*)(p_ + 6144); \
;               r4[(s_) % 3] = *(const f32x4*)(p_ + 8192); vv[(s_) % 3] = vb[(s_) * 64]; } while (0)
; __device__ __forceinline__ void scan_block(unsigned char* shm, int sid, int half) {
;     ...
;           for (int s = 0; s < TS; ++s) {
;               const f32x4 a_ = a4[s % 3], w_ = w4[s % 3], b_ = b4[s % 3], k_ = k4[s % 3], r_ = r4[s % 3];
;               const float av[4] = {a_.x, a_.y, a_.z, a_.w}, wv[4] = {w_.x, w_.y, w_.z, w_.w}, bv[4] = {b_.x, b_.y, b_.z, b_.w}, kv[4] = {k_.x, k_.y, k_.z, k_.w}, rv[4] = {r_.x, r_.y, r_.z, r_.w};
;               const float v1 = vv[s % 3];
;               if (s + 2 < TS) LDOPS(s + 2);
;               float t = S[0] * av[0]; t = fmaf(S[1], av[1], t); t = fmaf(S[2], av[2], t); t = fmaf(S[3], av[3], t);
;               t += dppf<0xB1>(t); t += dppf<0x4E>(t); t += dppf<0x141>(t); t += dppf<0x140>(t);
; #pragma unroll
;               for (int q = 0; q < 4; ++q) S[q] = fmaf(S[q], wv[q], fmaf(bv[q], t, kv[q] * v1));
;               float u = S[0] * rv[0]; u = fmaf(S[1], rv[1], u); u = fmaf(S[2], rv[2], u); u = fmaf(S[3], rv[3], u);
;               u += dppf<0xB1>(u); u += dppf<0x4E>(u); u += dppf<0x141>(u); u += dppf<0x140>(u);
;               ys[s * 32] = u;
;           }
	v_fmac_f32_e32 v112, v40, v136
	v_fmac_f32_e32 v113, v41, v136
	v_fmac_f32_e32 v114, v42, v136
	v_fmac_f32_e32 v115, v43, v136
	v_fmac_f32_e32 v116, v44, v136
	v_fmac_f32_e32 v117, v45, v136
	v_fmac_f32_e32 v118, v46, v136
	v_fmac_f32_e32 v119, v47, v136
	v_fma_f32 v122, v122, v32, v112
	v_fma_f32 v123, v123, v33, v113
	v_fma_f32 v124, v124, v34, v114
	v_fma_f32 v125, v125, v35, v115
	v_fma_f32 v126, v126, v36, v116
	v_fma_f32 v127, v127, v37, v117
	v_fma_f32 v128, v128, v38, v118
	v_fma_f32 v129, v129, v39, v119
	v_mul_f32_e32 v136, v122, v140
	v_mul_f32_e32 v138, v48, v122
	v_fmac_f32_e32 v136, v123, v141
	v_fmac_f32_e32 v138, v123, v49
	v_fmac_f32_e32 v136, v124, v142
	v_fmac_f32_e32 v138, v124, v50
	v_fmac_f32_e32 v136, v125, v143
	v_fmac_f32_e32 v138, v125, v51
	v_fmac_f32_e32 v136, v126, v144
	v_fmac_f32_e32 v138, v126, v52
	v_fmac_f32_e32 v136, v127, v145
	v_fmac_f32_e32 v138, v127, v53
	v_fmac_f32_e32 v136, v128, v146
	v_fmac_f32_e32 v138, v128, v54
	v_fmac_f32_e32 v136, v129, v147
	v_fmac_f32_e32 v138, v129, v55
	v_mul_f32_e32 v112, v148, v108
	v_mul_f32_e32 v113, v149, v108
	v_add_f32_dpp v136, v136, v136 quad_perm:[1,0,3,2] row_mask:0xf bank_mask:0xf bound_ctrl:1
	v_add_f32_dpp v139, v137, v137 row_half_mirror row_mask:0xf bank_mask:0xf bound_ctrl:1
	v_add_f32_dpp v139, v138, v138 row_half_mirror row_mask:0xf bank_mask:0xa
	v_add_f32_dpp v136, v136, v136 quad_perm:[2,3,0,1] row_mask:0xf bank_mask:0xf bound_ctrl:1
	v_mul_f32_e32 v114, v150, v108
	v_mul_f32_e32 v115, v151, v108
	v_add_f32_dpp v139, v139, v139 quad_perm:[2,3,0,1] row_mask:0xf bank_mask:0xf bound_ctrl:1
	v_add_f32_dpp v136, v136, v136 row_half_mirror row_mask:0xf bank_mask:0xf bound_ctrl:1
	v_mul_f32_e32 v116, v152, v108
	v_mul_f32_e32 v117, v153, v108
	v_add_f32_dpp v139, v139, v139 quad_perm:[1,0,3,2] row_mask:0xf bank_mask:0xf bound_ctrl:1
	v_mul_f32_e32 v118, v154, v108
	v_mul_f32_e32 v119, v155, v108
	ds_write_b32 v135, v139 offset:0
	ds_read_b128 v[140:143], v133 offset:9216
	ds_read_b128 v[144:147], v133 offset:9232
	ds_read_b128 v[148:151], v133 offset:25600
	ds_read_b128 v[152:155], v133 offset:25616
	ds_read2st64_b32 v[106:107], v134 offset0:164 offset1:165
	ds_read_b128 v[32:35], v133 offset:768
	ds_read_b128 v[36:39], v133 offset:784
	ds_read_b128 v[40:43], v133 offset:17152
	ds_read_b128 v[44:47], v133 offset:17168
	ds_read_b128 v[48:51], v133 offset:33536
	ds_read_b128 v[52:55], v133 offset:33552
	s_waitcnt lgkmcnt(11)
	v_fmac_f32_e32 v112, v184, v136
	v_fmac_f32_e32 v113, v185, v136
	v_fmac_f32_e32 v114, v186, v136
	v_fmac_f32_e32 v115, v187, v136
	v_fmac_f32_e32 v116, v188, v136
	v_fmac_f32_e32 v117, v189, v136
	v_fmac_f32_e32 v118, v190, v136
	v_fmac_f32_e32 v119, v191, v136
	v_fma_f32 v122, v122, v176, v112
	v_fma_f32 v123, v123, v177, v113
	v_fma_f32 v124, v124, v178, v114
	v_fma_f32 v125, v125, v179, v115
	v_fma_f32 v126, v126, v180, v116
	v_fma_f32 v127, v127, v181, v117
	v_fma_f32 v128, v128, v182, v118
	v_fma_f32 v129, v129, v183, v119
	v_mul_f32_e32 v136, v122, v158
	v_mul_f32_e32 v137, v192, v122
	v_fmac_f32_e32 v136, v123, v159
	v_fmac_f32_e32 v137, v123, v193
	v_fmac_f32_e32 v136, v124, v160
	v_fmac_f32_e32 v137, v124, v194
	v_fmac_f32_e32 v136, v125, v161
	v_fmac_f32_e32 v137, v125, v195
	v_fmac_f32_e32 v136, v126, v162
	v_fmac_f32_e32 v137, v126, v196
	v_fmac_f32_e32 v136, v127, v163
	v_fmac_f32_e32 v137, v127, v197
	v_fmac_f32_e32 v136, v128, v164
	v_fmac_f32_e32 v137, v128, v198
	v_fmac_f32_e32 v136, v129, v165
	v_fmac_f32_e32 v137, v129, v199
	v_mul_f32_e32 v112, v166, v109
	v_mul_f32_e32 v113, v167, v109
	v_add_f32_dpp v136, v136, v136 quad_perm:[1,0,3,2] row_mask:0xf bank_mask:0xf bound_ctrl:1
	v_mul_f32_e32 v114, v168, v109
	v_mul_f32_e32 v115, v169, v109
	v_add_f32_dpp v136, v136, v136 quad_perm:[2,3,0,1] row_mask:0xf bank_mask:0xf bound_ctrl:1
	v_mul_f32_e32 v116, v170, v109
	v_mul_f32_e32 v117, v171, v109
	v_add_f32_dpp v136, v136, v136 row_half_mirror row_mask:0xf bank_mask:0xf bound_ctrl:1
	v_mul_f32_e32 v118, v172, v109
	v_mul_f32_e32 v119, v173, v109
	ds_read_b128 v[158:161], v133 offset:9472
	ds_read_b128 v[162:165], v133 offset:9488
	ds_read_b128 v[166:169], v133 offset:25856
	ds_read_b128 v[170:173], v133 offset:25872
	ds_read_b128 v[176:179], v133 offset:1024
	ds_read_b128 v[180:183], v133 offset:1040
	ds_read_b128 v[184:187], v133 offset:17408
	ds_read_b128 v[188:191], v133 offset:17424
	ds_read_b128 v[192:195], v133 offset:33792
	ds_read_b128 v[196:199], v133 offset:33808
	s_waitcnt lgkmcnt(10)
; template <int CTRL> __device__ __forceinline__ float dppf(float x) { return __builtin_bit_cast(float, __builtin_amdgcn_mov_dpp(__builtin_bit_cast(int, x), CTRL, 0xf, 0xf, true)); }
; #define LDOPS(s_) do { const float* p_ = bb + (s_) * 64; w4[(s_) % 3] = *(const f32x4*)(p_); a4[(s_) % 3] = *(const f32x4*)(p_ + 2048); b4[(s_) % 3] = *(const f32x4*)(p_ + 4096); k4[(s_) % 3] = *(const f32x4*)(p_ + 6144); \
;               r4[(s_) % 3] = *(const f32x4*)(p_ + 8192); vv[(s_) % 3] = vb[(s_) * 64]; } while (0)
; __device__ __forceinline__ void scan_block(unsigned char* shm, int sid, int half) {
;     ...
;           for (int s = 0; s < TS; ++s) {
;               const f32x4 a_ = a4[s % 3], w_ = w4[s % 3], b_ = b4[s % 3], k_ = k4[s % 3], r_ = r4[s % 3];
;               const float av[4] = {a_.x, a_.y, a_.z, a_.w}, wv[4] = {w_.x, w_.y, w_.z, w_.w}, bv[4] = {b_.x, b_.y, b_.z, b_.w}, kv[4] = {k_.x, k_.y, k_.z, k_.w}, rv[4] = {r_.x, r_.y, r_.z, r_.w};
;               const float v1 = vv[s % 3];
;               if (s + 2 < TS) LDOPS(s + 2);
;               float t = S[0] * av[0]; t = fmaf(S[1], av[1], t); t = fmaf(S[2], av[2], t); t = fmaf(S[3], av[3], t);
;               t += dppf<0xB1>(t); t += dppf<0x4E>(t); t += dppf<0x141>(t); t += dppf<0x140>(t);
; #pragma unroll
;               for (int q = 0; q < 4; ++q) S[q] = fmaf(S[q], wv[q], fmaf(bv[q], t, kv[q] * v1));
;               float u = S[0] * rv[0]; u = fmaf(S[1], rv[1], u); u = fmaf(S[2], rv[2], u); u = fmaf(S[3], rv[3], u);
;               u += dppf<0xB1>(u); u += dppf<0x4E>(u); u += dppf<0x141>(u); u += dppf<0x140>(u);
;               ys[s * 32] = u;
;           }
	v_fmac_f32_e32 v112, v40, v136
	v_fmac_f32_e32 v113, v41, v136
	v_fmac_f32_e32 v114, v42, v136
	v_fmac_f32_e32 v115, v43, v136
	v_fmac_f32_e32 v116, v44, v136
	v_fmac_f32_e32 v117, v45, v136
	v_fmac_f32_e32 v118, v46, v136
	v_fmac_f32_e32 v119, v47, v136
	v_fma_f32 v122, v122, v32, v112
	v_fma_f32 v123, v123, v33, v113
	v_fma_f32 v124, v124, v34, v114
	v_fma_f32 v125, v125, v35, v115
	v_fma_f32 v126, v126, v36, v116
	v_fma_f32 v127, v127, v37, v117
	v_fma_f32 v128, v128, v38, v118
	v_fma_f32 v129, v129, v39, v119
	v_mul_f32_e32 v136, v122, v140
	v_mul_f32_e32 v138, v48, v122
	v_fmac_f32_e32 v136, v123, v141
	v_fmac_f32_e32 v138, v123, v49
	v_fmac_f32_e32 v136, v124, v142
	v_fmac_f32_e32 v138, v124, v50
	v_fmac_f32_e32 v136, v125, v143
	v_fmac_f32_e32 v138, v125, v51
	v_fmac_f32_e32 v136, v126, v144
	v_fmac_f32_e32 v138, v126, v52
	v_fmac_f32_e32 v136, v127, v145
	v_fmac_f32_e32 v138, v127, v53
	v_fmac_f32_e32 v136, v128, v146
	v_fmac_f32_e32 v138, v128, v54
	v_fmac_f32_e32 v136, v129, v147
	v_fmac_f32_e32 v138, v129, v55
	v_mul_f32_e32 v112, v148, v106
	v_mul_f32_e32 v113, v149, v106
	v_add_f32_dpp v136, v136, v136 quad_perm:[1,0,3,2] row_mask:0xf bank_mask:0xf bound_ctrl:1
	v_add_f32_dpp v139, v137, v137 row_half_mirror row_mask:0xf bank_mask:0xf bound_ctrl:1
	v_add_f32_dpp v139, v138, v138 row_half_mirror row_mask:0xf bank_mask:0xa
	v_add_f32_dpp v136, v136, v136 quad_perm:[2,3,0,1] row_mask:0xf bank_mask:0xf bound_ctrl:1
	v_mul_f32_e32 v114, v150, v106
	v_mul_f32_e32 v115, v151, v106
	v_add_f32_dpp v139, v139, v139 quad_perm:[2,3,0,1] row_mask:0xf bank_mask:0xf bound_ctrl:1
	v_add_f32_dpp v136, v136, v136 row_half_mirror row_mask:0xf bank_mask:0xf bound_ctrl:1
	v_mul_f32_e32 v116, v152, v106
	v_mul_f32_e32 v117, v153, v106
	v_add_f32_dpp v139, v139, v139 quad_perm:[1,0,3,2] row_mask:0xf bank_mask:0xf bound_ctrl:1
	v_mul_f32_e32 v118, v154, v106
	v_mul_f32_e32 v119, v155, v106
	ds_write_b32 v135, v139 offset:256
	ds_read_b128 v[140:143], v133 offset:9728
	ds_read_b128 v[144:147], v133 offset:9744
	ds_read_b128 v[148:151], v133 offset:26112
	ds_read_b128 v[152:155], v133 offset:26128
	ds_read2st64_b32 v[108:109], v134 offset0:166 offset1:167
	ds_read_b128 v[32:35], v133 offset:1280
	ds_read_b128 v[36:39], v133 offset:1296
	ds_read_b128 v[40:43], v133 offset:17664
	ds_read_b128 v[44:47], v133 offset:17680
	ds_read_b128 v[48:51], v133 offset:34048
	ds_read_b128 v[52:55], v133 offset:34064
	s_waitcnt lgkmcnt(11)
	v_fmac_f32_e32 v112, v184, v136
	v_fmac_f32_e32 v113, v185, v136
	v_fmac_f32_e32 v114, v186, v136
	v_fmac_f32_e32 v115, v187, v136
	v_fmac_f32_e32 v116, v188, v136
	v_fmac_f32_e32 v117, v189, v136
	v_fmac_f32_e32 v118, v190, v136
	v_fmac_f32_e32 v119, v191, v136
	v_fma_f32 v122, v122, v176, v112
	v_fma_f32 v123, v123, v177, v113
	v_fma_f32 v124, v124, v178, v114
	v_fma_f32 v125, v125, v179, v115
	v_fma_f32 v126, v126, v180, v116
	v_fma_f32 v127, v127, v181, v117
	v_fma_f32 v128, v128, v182, v118
	v_fma_f32 v129, v129, v183, v119
	v_mul_f32_e32 v136, v122, v158
	v_mul_f32_e32 v137, v192, v122
	v_fmac_f32_e32 v136, v123, v159
	v_fmac_f32_e32 v137, v123, v193
	v_fmac_f32_e32 v136, v124, v160
	v_fmac_f32_e32 v137, v124, v194
	v_fmac_f32_e32 v136, v125, v161
	v_fmac_f32_e32 v137, v125, v195
	v_fmac_f32_e32 v136, v126, v162
	v_fmac_f32_e32 v137, v126, v196
	v_fmac_f32_e32 v136, v127, v163
	v_fmac_f32_e32 v137, v127, v197
	v_fmac_f32_e32 v136, v128, v164
	v_fmac_f32_e32 v137, v128, v198
	v_fmac_f32_e32 v136, v129, v165
	v_fmac_f32_e32 v137, v129, v199
	v_mul_f32_e32 v112, v166, v107
	v_mul_f32_e32 v113, v167, v107
	v_add_f32_dpp v136, v136, v136 quad_perm:[1,0,3,2] row_mask:0xf bank_mask:0xf bound_ctrl:1
	v_mul_f32_e32 v114, v168, v107
	v_mul_f32_e32 v115, v169, v107
	v_add_f32_dpp v136, v136, v136 quad_perm:[2,3,0,1] row_mask:0xf bank_mask:0xf bound_ctrl:1
	v_mul_f32_e32 v116, v170, v107
	v_mul_f32_e32 v117, v171, v107
	v_add_f32_dpp v136, v136, v136 row_half_mirror row_mask:0xf bank_mask:0xf bound_ctrl:1
	v_mul_f32_e32 v118, v172, v107
	v_mul_f32_e32 v119, v173, v107
	ds_read_b128 v[158:161], v133 offset:9984
	ds_read_b128 v[162:165], v133 offset:10000
	ds_read_b128 v[166:169], v133 offset:26368
	ds_read_b128 v[170:173], v133 offset:26384
	ds_read_b128 v[176:179], v133 offset:1536
	ds_read_b128 v[180:183], v133 offset:1552
	ds_read_b128 v[184:187], v133 offset:17920
	ds_read_b128 v[188:191], v133 offset:17936
	ds_read_b128 v[192:195], v133 offset:34304
	ds_read_b128 v[196:199], v133 offset:34320
	s_waitcnt lgkmcnt(10)
; template <int CTRL> __device__ __forceinline__ float dppf(float x) { return __builtin_bit_cast(float, __builtin_amdgcn_mov_dpp(__builtin_bit_cast(int, x), CTRL, 0xf, 0xf, true)); }
; #define LDOPS(s_) do { const float* p_ = bb + (s_) * 64; w4[(s_) % 3] = *(const f32x4*)(p_); a4[(s_) % 3] = *(const f32x4*)(p_ + 2048); b4[(s_) % 3] = *(const f32x4*)(p_ + 4096); k4[(s_) % 3] = *(const f32x4*)(p_ + 6144); \
;               r4[(s_) % 3] = *(const f32x4*)(p_ + 8192); vv[(s_) % 3] = vb[(s_) * 64]; } while (0)
; __device__ __forceinline__ void scan_block(unsigned char* shm, int sid, int half) {
;     ...
;           for (int s = 0; s < TS; ++s) {
;               const f32x4 a_ = a4[s % 3], w_ = w4[s % 3], b_ = b4[s % 3], k_ = k4[s % 3], r_ = r4[s % 3];
;               const float av[4] = {a_.x, a_.y, a_.z, a_.w}, wv[4] = {w_.x, w_.y, w_.z, w_.w}, bv[4] = {b_.x, b_.y, b_.z, b_.w}, kv[4] = {k_.x, k_.y, k_.z, k_.w}, rv[4] = {r_.x, r_.y, r_.z, r_.w};
;               const float v1 = vv[s % 3];
;               if (s + 2 < TS) LDOPS(s + 2);
;               float t = S[0] * av[0]; t = fmaf(S[1], av[1], t); t = fmaf(S[2], av[2], t); t = fmaf(S[3], av[3], t);
;               t += dppf<0xB1>(t); t += dppf<0x4E>(t); t += dppf<0x141>(t); t += dppf<0x140>(t);
; #pragma unroll
;               for (int q = 0; q < 4; ++q) S[q] = fmaf(S[q], wv[q], fmaf(bv[q], t, kv[q] * v1));
;               float u = S[0] * rv[0]; u = fmaf(S[1], rv[1], u); u = fmaf(S[2], rv[2], u); u = fmaf(S[3], rv[3], u);
;               u += dppf<0xB1>(u); u += dppf<0x4E>(u); u += dppf<0x141>(u); u += dppf<0x140>(u);
;               ys[s * 32] = u;
;           }
	v_fmac_f32_e32 v112, v40, v136
	v_fmac_f32_e32 v113, v41, v136
	v_fmac_f32_e32 v114, v42, v136
	v_fmac_f32_e32 v115, v43, v136
	v_fmac_f32_e32 v116, v44, v136
	v_fmac_f32_e32 v117, v45, v136
	v_fmac_f32_e32 v118, v46, v136
	v_fmac_f32_e32 v119, v47, v136
	v_fma_f32 v122, v122, v32, v112
	v_fma_f32 v123, v123, v33, v113
	v_fma_f32 v124, v124, v34, v114
	v_fma_f32 v125, v125, v35, v115
	v_fma_f32 v126, v126, v36, v116
	v_fma_f32 v127, v127, v37, v117
	v_fma_f32 v128, v128, v38, v118
	v_fma_f32 v129, v129, v39, v119
	v_mul_f32_e32 v136, v122, v140
	v_mul_f32_e32 v138, v48, v122
	v_fmac_f32_e32 v136, v123, v141
	v_fmac_f32_e32 v138, v123, v49
	v_fmac_f32_e32 v136, v124, v142
	v_fmac_f32_e32 v138, v124, v50
	v_fmac_f32_e32 v136, v125, v143
	v_fmac_f32_e32 v138, v125, v51
	v_fmac_f32_e32 v136, v126, v144
	v_fmac_f32_e32 v138, v126, v52
	v_fmac_f32_e32 v136, v127, v145
	v_fmac_f32_e32 v138, v127, v53
	v_fmac_f32_e32 v136, v128, v146
	v_fmac_f32_e32 v138, v128, v54
	v_fmac_f32_e32 v136, v129, v147
	v_fmac_f32_e32 v138, v129, v55
	v_mul_f32_e32 v112, v148, v108
	v_mul_f32_e32 v113, v149, v108
	v_add_f32_dpp v136, v136, v136 quad_perm:[1,0,3,2] row_mask:0xf bank_mask:0xf bound_ctrl:1
	v_add_f32_dpp v139, v137, v137 row_half_mirror row_mask:0xf bank_mask:0xf bound_ctrl:1
	v_add_f32_dpp v139, v138, v138 row_half_mirror row_mask:0xf bank_mask:0xa
	v_add_f32_dpp v136, v136, v136 quad_perm:[2,3,0,1] row_mask:0xf bank_mask:0xf bound_ctrl:1
	v_mul_f32_e32 v114, v150, v108
	v_mul_f32_e32 v115, v151, v108
	v_add_f32_dpp v139, v139, v139 quad_perm:[2,3,0,1] row_mask:0xf bank_mask:0xf bound_ctrl:1
	v_add_f32_dpp v136, v136, v136 row_half_mirror row_mask:0xf bank_mask:0xf bound_ctrl:1
	v_mul_f32_e32 v116, v152, v108
	v_mul_f32_e32 v117, v153, v108
	v_add_f32_dpp v139, v139, v139 quad_perm:[1,0,3,2] row_mask:0xf bank_mask:0xf bound_ctrl:1
	v_mul_f32_e32 v118, v154, v108
	v_mul_f32_e32 v119, v155, v108
	ds_write_b32 v135, v139 offset:512
	ds_read_b128 v[140:143], v133 offset:10240
	ds_read_b128 v[144:147], v133 offset:10256
	ds_read_b128 v[148:151], v133 offset:26624
	ds_read_b128 v[152:155], v133 offset:26640
	ds_read2st64_b32 v[106:107], v134 offset0:168 offset1:169
	ds_read_b128 v[32:35], v133 offset:1792
	ds_read_b128 v[36:39], v133 offset:1808
	ds_read_b128 v[40:43], v133 offset:18176
	ds_read_b128 v[44:47], v133 offset:18192
	ds_read_b128 v[48:51], v133 offset:34560
	ds_read_b128 v[52:55], v133 offset:34576
	s_waitcnt lgkmcnt(11)
	v_fmac_f32_e32 v112, v184, v136
	v_fmac_f32_e32 v113, v185, v136
	v_fmac_f32_e32 v114, v186, v136
	v_fmac_f32_e32 v115, v187, v136
	v_fmac_f32_e32 v116, v188, v136
	v_fmac_f32_e32 v117, v189, v136
	v_fmac_f32_e32 v118, v190, v136
	v_fmac_f32_e32 v119, v191, v136
	v_fma_f32 v122, v122, v176, v112
	v_fma_f32 v123, v123, v177, v113
	v_fma_f32 v124, v124, v178, v114
	v_fma_f32 v125, v125, v179, v115
	v_fma_f32 v126, v126, v180, v116
	v_fma_f32 v127, v127, v181, v117
	v_fma_f32 v128, v128, v182, v118
	v_fma_f32 v129, v129, v183, v119
	v_mul_f32_e32 v136, v122, v158
	v_mul_f32_e32 v137, v192, v122
	v_fmac_f32_e32 v136, v123, v159
	v_fmac_f32_e32 v137, v123, v193
	v_fmac_f32_e32 v136, v124, v160
	v_fmac_f32_e32 v137, v124, v194
	v_fmac_f32_e32 v136, v125, v161
	v_fmac_f32_e32 v137, v125, v195
	v_fmac_f32_e32 v136, v126, v162
	v_fmac_f32_e32 v137, v126, v196
	v_fmac_f32_e32 v136, v127, v163
	v_fmac_f32_e32 v137, v127, v197
	v_fmac_f32_e32 v136, v128, v164
	v_fmac_f32_e32 v137, v128, v198
	v_fmac_f32_e32 v136, v129, v165
	v_fmac_f32_e32 v137, v129, v199
	v_mul_f32_e32 v112, v166, v109
	v_mul_f32_e32 v113, v167, v109
	v_add_f32_dpp v136, v136, v136 quad_perm:[1,0,3,2] row_mask:0xf bank_mask:0xf bound_ctrl:1
	v_mul_f32_e32 v114, v168, v109
	v_mul_f32_e32 v115, v169, v109
	v_add_f32_dpp v136, v136, v136 quad_perm:[2,3,0,1] row_mask:0xf bank_mask:0xf bound_ctrl:1
	v_mul_f32_e32 v116, v170, v109
	v_mul_f32_e32 v117, v171, v109
	v_add_f32_dpp v136, v136, v136 row_half_mirror row_mask:0xf bank_mask:0xf bound_ctrl:1
	v_mul_f32_e32 v118, v172, v109
	v_mul_f32_e32 v119, v173, v109
	ds_read_b128 v[158:161], v133 offset:10496
	ds_read_b128 v[162:165], v133 offset:10512
	ds_read_b128 v[166:169], v133 offset:26880
	ds_read_b128 v[170:173], v133 offset:26896
	ds_read_b128 v[176:179], v133 offset:2048
	ds_read_b128 v[180:183], v133 offset:2064
	ds_read_b128 v[184:187], v133 offset:18432
	ds_read_b128 v[188:191], v133 offset:18448
	ds_read_b128 v[192:195], v133 offset:34816
	ds_read_b128 v[196:199], v133 offset:34832
	s_waitcnt lgkmcnt(10)
; template <int CTRL> __device__ __forceinline__ float dppf(float x) { return __builtin_bit_cast(float, __builtin_amdgcn_mov_dpp(__builtin_bit_cast(int, x), CTRL, 0xf, 0xf, true)); }
; #define LDOPS(s_) do { const float* p_ = bb + (s_) * 64; w4[(s_) % 3] = *(const f32x4*)(p_); a4[(s_) % 3] = *(const f32x4*)(p_ + 2048); b4[(s_) % 3] = *(const f32x4*)(p_ + 4096); k4[(s_) % 3] = *(const f32x4*)(p_ + 6144); \
;               r4[(s_) % 3] = *(const f32x4*)(p_ + 8192); vv[(s_) % 3] = vb[(s_) * 64]; } while (0)
; __device__ __forceinline__ void scan_block(unsigned char* shm, int sid, int half) {
;     ...
;           for (int s = 0; s < TS; ++s) {
;               const f32x4 a_ = a4[s % 3], w_ = w4[s % 3], b_ = b4[s % 3], k_ = k4[s % 3], r_ = r4[s % 3];
;               const float av[4] = {a_.x, a_.y, a_.z, a_.w}, wv[4] = {w_.x, w_.y, w_.z, w_.w}, bv[4] = {b_.x, b_.y, b_.z, b_.w}, kv[4] = {k_.x, k_.y, k_.z, k_.w}, rv[4] = {r_.x, r_.y, r_.z, r_.w};
;               const float v1 = vv[s % 3];
;               if (s + 2 < TS) LDOPS(s + 2);
;               float t = S[0] * av[0]; t = fmaf(S[1], av[1], t); t = fmaf(S[2], av[2], t); t = fmaf(S[3], av[3], t);
;               t += dppf<0xB1>(t); t += dppf<0x4E>(t); t += dppf<0x141>(t); t += dppf<0x140>(t);
; #pragma unroll
;               for (int q = 0; q < 4; ++q) S[q] = fmaf(S[q], wv[q], fmaf(bv[q], t, kv[q] * v1));
;               float u = S[0] * rv[0]; u = fmaf(S[1], rv[1], u); u = fmaf(S[2], rv[2], u); u = fmaf(S[3], rv[3], u);
;               u += dppf<0xB1>(u); u += dppf<0x4E>(u); u += dppf<0x141>(u); u += dppf<0x140>(u);
;               ys[s * 32] = u;
;           }
	v_fmac_f32_e32 v112, v40, v136
	v_fmac_f32_e32 v113, v41, v136
	v_fmac_f32_e32 v114, v42, v136
	v_fmac_f32_e32 v115, v43, v136
	v_fmac_f32_e32 v116, v44, v136
	v_fmac_f32_e32 v117, v45, v136
	v_fmac_f32_e32 v118, v46, v136
	v_fmac_f32_e32 v119, v47, v136
	v_fma_f32 v122, v122, v32, v112
	v_fma_f32 v123, v123, v33, v113
	v_fma_f32 v124, v124, v34, v114
	v_fma_f32 v125, v125, v35, v115
	v_fma_f32 v126, v126, v36, v116
	v_fma_f32 v127, v127, v37, v117
	v_fma_f32 v128, v128, v38, v118
	v_fma_f32 v129, v129, v39, v119
	v_mul_f32_e32 v136, v122, v140
	v_mul_f32_e32 v138, v48, v122
	v_fmac_f32_e32 v136, v123, v141
	v_fmac_f32_e32 v138, v123, v49
	v_fmac_f32_e32 v136, v124, v142
	v_fmac_f32_e32 v138, v124, v50
	v_fmac_f32_e32 v136, v125, v143
	v_fmac_f32_e32 v138, v125, v51
	v_fmac_f32_e32 v136, v126, v144
	v_fmac_f32_e32 v138, v126, v52
	v_fmac_f32_e32 v136, v127, v145
	v_fmac_f32_e32 v138, v127, v53
	v_fmac_f32_e32 v136, v128, v146
	v_fmac_f32_e32 v138, v128, v54
	v_fmac_f32_e32 v136, v129, v147
	v_fmac_f32_e32 v138, v129, v55
	v_mul_f32_e32 v112, v148, v106
	v_mul_f32_e32 v113, v149, v106
	v_add_f32_dpp v136, v136, v136 quad_perm:[1,0,3,2] row_mask:0xf bank_mask:0xf bound_ctrl:1
	v_add_f32_dpp v139, v137, v137 row_half_mirror row_mask:0xf bank_mask:0xf bound_ctrl:1
	v_add_f32_dpp v139, v138, v138 row_half_mirror row_mask:0xf bank_mask:0xa
	v_add_f32_dpp v136, v136, v136 quad_perm:[2,3,0,1] row_mask:0xf bank_mask:0xf bound_ctrl:1
	v_mul_f32_e32 v114, v150, v106
	v_mul_f32_e32 v115, v151, v106
	v_add_f32_dpp v139, v139, v139 quad_perm:[2,3,0,1] row_mask:0xf bank_mask:0xf bound_ctrl:1
	v_add_f32_dpp v136, v136, v136 row_half_mirror row_mask:0xf bank_mask:0xf bound_ctrl:1
	v_mul_f32_e32 v116, v152, v106
	v_mul_f32_e32 v117, v153, v106
	v_add_f32_dpp v139, v139, v139 quad_perm:[1,0,3,2] row_mask:0xf bank_mask:0xf bound_ctrl:1
	v_mul_f32_e32 v118, v154, v106
	v_mul_f32_e32 v119, v155, v106
	ds_write_b32 v135, v139 offset:768
	ds_read_b128 v[140:143], v133 offset:10752
	ds_read_b128 v[144:147], v133 offset:10768
	ds_read_b128 v[148:151], v133 offset:27136
	ds_read_b128 v[152:155], v133 offset:27152
	ds_read2st64_b32 v[108:109], v134 offset0:170 offset1:171
	ds_read_b128 v[32:35], v133 offset:2304
	ds_read_b128 v[36:39], v133 offset:2320
	ds_read_b128 v[40:43], v133 offset:18688
	ds_read_b128 v[44:47], v133 offset:18704
	ds_read_b128 v[48:51], v133 offset:35072
	ds_read_b128 v[52:55], v133 offset:35088
	s_waitcnt lgkmcnt(11)
	v_fmac_f32_e32 v112, v184, v136
	v_fmac_f32_e32 v113, v185, v136
	v_fmac_f32_e32 v114, v186, v136
	v_fmac_f32_e32 v115, v187, v136
	v_fmac_f32_e32 v116, v188, v136
	v_fmac_f32_e32 v117, v189, v136
	v_fmac_f32_e32 v118, v190, v136
	v_fmac_f32_e32 v119, v191, v136
	v_fma_f32 v122, v122, v176, v112
	v_fma_f32 v123, v123, v177, v113
	v_fma_f32 v124, v124, v178, v114
	v_fma_f32 v125, v125, v179, v115
	v_fma_f32 v126, v126, v180, v116
	v_fma_f32 v127, v127, v181, v117
	v_fma_f32 v128, v128, v182, v118
	v_fma_f32 v129, v129, v183, v119
	v_mul_f32_e32 v136, v122, v158
	v_mul_f32_e32 v137, v192, v122
	v_fmac_f32_e32 v136, v123, v159
	v_fmac_f32_e32 v137, v123, v193
	v_fmac_f32_e32 v136, v124, v160
	v_fmac_f32_e32 v137, v124, v194
	v_fmac_f32_e32 v136, v125, v161
	v_fmac_f32_e32 v137, v125, v195
	v_fmac_f32_e32 v136, v126, v162
	v_fmac_f32_e32 v137, v126, v196
	v_fmac_f32_e32 v136, v127, v163
	v_fmac_f32_e32 v137, v127, v197
	v_fmac_f32_e32 v136, v128, v164
	v_fmac_f32_e32 v137, v128, v198
	v_fmac_f32_e32 v136, v129, v165
	v_fmac_f32_e32 v137, v129, v199
	v_mul_f32_e32 v112, v166, v107
	v_mul_f32_e32 v113, v167, v107
	v_add_f32_dpp v136, v136, v136 quad_perm:[1,0,3,2] row_mask:0xf bank_mask:0xf bound_ctrl:1
	v_mul_f32_e32 v114, v168, v107
	v_mul_f32_e32 v115, v169, v107
	v_add_f32_dpp v136, v136, v136 quad_perm:[2,3,0,1] row_mask:0xf bank_mask:0xf bound_ctrl:1
	v_mul_f32_e32 v116, v170, v107
	v_mul_f32_e32 v117, v171, v107
	v_add_f32_dpp v136, v136, v136 row_half_mirror row_mask:0xf bank_mask:0xf bound_ctrl:1
	v_mul_f32_e32 v118, v172, v107
	v_mul_f32_e32 v119, v173, v107
	ds_read_b128 v[158:161], v133 offset:11008
	ds_read_b128 v[162:165], v133 offset:11024
	ds_read_b128 v[166:169], v133 offset:27392
	ds_read_b128 v[170:173], v133 offset:27408
	ds_read_b128 v[176:179], v133 offset:2560
	ds_read_b128 v[180:183], v133 offset:2576
	ds_read_b128 v[184:187], v133 offset:18944
	ds_read_b128 v[188:191], v133 offset:18960
	ds_read_b128 v[192:195], v133 offset:35328
	ds_read_b128 v[196:199], v133 offset:35344
	s_waitcnt lgkmcnt(10)
; template <int CTRL> __device__ __forceinline__ float dppf(float x) { return __builtin_bit_cast(float, __builtin_amdgcn_mov_dpp(__builtin_bit_cast(int, x), CTRL, 0xf, 0xf, true)); }
; #define LDOPS(s_) do { const float* p_ = bb + (s_) * 64; w4[(s_) % 3] = *(const f32x4*)(p_); a4[(s_) % 3] = *(const f32x4*)(p_ + 2048); b4[(s_) % 3] = *(const f32x4*)(p_ + 4096); k4[(s_) % 3] = *(const f32x4*)(p_ + 6144); \
;               r4[(s_) % 3] = *(const f32x4*)(p_ + 8192); vv[(s_) % 3] = vb[(s_) * 64]; } while (0)
; __device__ __forceinline__ void scan_block(unsigned char* shm, int sid, int half) {
;     ...
;           for (int s = 0; s < TS; ++s) {
;               const f32x4 a_ = a4[s % 3], w_ = w4[s % 3], b_ = b4[s % 3], k_ = k4[s % 3], r_ = r4[s % 3];
;               const float av[4] = {a_.x, a_.y, a_.z, a_.w}, wv[4] = {w_.x, w_.y, w_.z, w_.w}, bv[4] = {b_.x, b_.y, b_.z, b_.w}, kv[4] = {k_.x, k_.y, k_.z, k_.w}, rv[4] = {r_.x, r_.y, r_.z, r_.w};
;               const float v1 = vv[s % 3];
;               if (s + 2 < TS) LDOPS(s + 2);
;               float t = S[0] * av[0]; t = fmaf(S[1], av[1], t); t = fmaf(S[2], av[2], t); t = fmaf(S[3], av[3], t);
;               t += dppf<0xB1>(t); t += dppf<0x4E>(t); t += dppf<0x141>(t); t += dppf<0x140>(t);
; #pragma unroll
;               for (int q = 0; q < 4; ++q) S[q] = fmaf(S[q], wv[q], fmaf(bv[q], t, kv[q] * v1));
;               float u = S[0] * rv[0]; u = fmaf(S[1], rv[1], u); u = fmaf(S[2], rv[2], u); u = fmaf(S[3], rv[3], u);
;               u += dppf<0xB1>(u); u += dppf<0x4E>(u); u += dppf<0x141>(u); u += dppf<0x140>(u);
;               ys[s * 32] = u;
;           }
	v_fmac_f32_e32 v112, v40, v136
	v_fmac_f32_e32 v113, v41, v136
	v_fmac_f32_e32 v114, v42, v136
	v_fmac_f32_e32 v115, v43, v136
	v_fmac_f32_e32 v116, v44, v136
	v_fmac_f32_e32 v117, v45, v136
	v_fmac_f32_e32 v118, v46, v136
	v_fmac_f32_e32 v119, v47, v136
	v_fma_f32 v122, v122, v32, v112
	v_fma_f32 v123, v123, v33, v113
	v_fma_f32 v124, v124, v34, v114
	v_fma_f32 v125, v125, v35, v115
	v_fma_f32 v126, v126, v36, v116
	v_fma_f32 v127, v127, v37, v117
	v_fma_f32 v128, v128, v38, v118
	v_fma_f32 v129, v129, v39, v119
	v_mul_f32_e32 v136, v122, v140
	v_mul_f32_e32 v138, v48, v122
	v_fmac_f32_e32 v136, v123, v141
	v_fmac_f32_e32 v138, v123, v49
	v_fmac_f32_e32 v136, v124, v142
	v_fmac_f32_e32 v138, v124, v50
	v_fmac_f32_e32 v136, v125, v143
	v_fmac_f32_e32 v138, v125, v51
	v_fmac_f32_e32 v136, v126, v144
	v_fmac_f32_e32 v138, v126, v52
	v_fmac_f32_e32 v136, v127, v145
	v_fmac_f32_e32 v138, v127, v53
	v_fmac_f32_e32 v136, v128, v146
	v_fmac_f32_e32 v138, v128, v54
	v_fmac_f32_e32 v136, v129, v147
	v_fmac_f32_e32 v138, v129, v55
	v_mul_f32_e32 v112, v148, v108
	v_mul_f32_e32 v113, v149, v108
	v_add_f32_dpp v136, v136, v136 quad_perm:[1,0,3,2] row_mask:0xf bank_mask:0xf bound_ctrl:1
	v_add_f32_dpp v139, v137, v137 row_half_mirror row_mask:0xf bank_mask:0xf bound_ctrl:1
	v_add_f32_dpp v139, v138, v138 row_half_mirror row_mask:0xf bank_mask:0xa
	v_add_f32_dpp v136, v136, v136 quad_perm:[2,3,0,1] row_mask:0xf bank_mask:0xf bound_ctrl:1
	v_mul_f32_e32 v114, v150, v108
	v_mul_f32_e32 v115, v151, v108
	v_add_f32_dpp v139, v139, v139 quad_perm:[2,3,0,1] row_mask:0xf bank_mask:0xf bound_ctrl:1
	v_add_f32_dpp v136, v136, v136 row_half_mirror row_mask:0xf bank_mask:0xf bound_ctrl:1
	v_mul_f32_e32 v116, v152, v108
	v_mul_f32_e32 v117, v153, v108
	v_add_f32_dpp v139, v139, v139 quad_perm:[1,0,3,2] row_mask:0xf bank_mask:0xf bound_ctrl:1
	v_mul_f32_e32 v118, v154, v108
	v_mul_f32_e32 v119, v155, v108
	ds_write_b32 v135, v139 offset:1024
	ds_read_b128 v[140:143], v133 offset:11264
	ds_read_b128 v[144:147], v133 offset:11280
	ds_read_b128 v[148:151], v133 offset:27648
	ds_read_b128 v[152:155], v133 offset:27664
	ds_read2st64_b32 v[106:107], v134 offset0:172 offset1:173
	ds_read_b128 v[32:35], v133 offset:2816
	ds_read_b128 v[36:39], v133 offset:2832
	ds_read_b128 v[40:43], v133 offset:19200
	ds_read_b128 v[44:47], v133 offset:19216
	ds_read_b128 v[48:51], v133 offset:35584
	ds_read_b128 v[52:55], v133 offset:35600
	s_waitcnt lgkmcnt(11)
	v_fmac_f32_e32 v112, v184, v136
	v_fmac_f32_e32 v113, v185, v136
	v_fmac_f32_e32 v114, v186, v136
	v_fmac_f32_e32 v115, v187, v136
	v_fmac_f32_e32 v116, v188, v136
	v_fmac_f32_e32 v117, v189, v136
	v_fmac_f32_e32 v118, v190, v136
	v_fmac_f32_e32 v119, v191, v136
	v_fma_f32 v122, v122, v176, v112
	v_fma_f32 v123, v123, v177, v113
	v_fma_f32 v124, v124, v178, v114
	v_fma_f32 v125, v125, v179, v115
	v_fma_f32 v126, v126, v180, v116
	v_fma_f32 v127, v127, v181, v117
	v_fma_f32 v128, v128, v182, v118
	v_fma_f32 v129, v129, v183, v119
	v_mul_f32_e32 v136, v122, v158
	v_mul_f32_e32 v137, v192, v122
	v_fmac_f32_e32 v136, v123, v159
	v_fmac_f32_e32 v137, v123, v193
	v_fmac_f32_e32 v136, v124, v160
	v_fmac_f32_e32 v137, v124, v194
	v_fmac_f32_e32 v136, v125, v161
	v_fmac_f32_e32 v137, v125, v195
	v_fmac_f32_e32 v136, v126, v162
	v_fmac_f32_e32 v137, v126, v196
	v_fmac_f32_e32 v136, v127, v163
	v_fmac_f32_e32 v137, v127, v197
	v_fmac_f32_e32 v136, v128, v164
	v_fmac_f32_e32 v137, v128, v198
	v_fmac_f32_e32 v136, v129, v165
	v_fmac_f32_e32 v137, v129, v199
	v_mul_f32_e32 v112, v166, v109
	v_mul_f32_e32 v113, v167, v109
	v_add_f32_dpp v136, v136, v136 quad_perm:[1,0,3,2] row_mask:0xf bank_mask:0xf bound_ctrl:1
	v_mul_f32_e32 v114, v168, v109
	v_mul_f32_e32 v115, v169, v109
	v_add_f32_dpp v136, v136, v136 quad_perm:[2,3,0,1] row_mask:0xf bank_mask:0xf bound_ctrl:1
	v_mul_f32_e32 v116, v170, v109
	v_mul_f32_e32 v117, v171, v109
	v_add_f32_dpp v136, v136, v136 row_half_mirror row_mask:0xf bank_mask:0xf bound_ctrl:1
	v_mul_f32_e32 v118, v172, v109
	v_mul_f32_e32 v119, v173, v109
	ds_read_b128 v[158:161], v133 offset:11520
	ds_read_b128 v[162:165], v133 offset:11536
	ds_read_b128 v[166:169], v133 offset:27904
	ds_read_b128 v[170:173], v133 offset:27920
	ds_read_b128 v[176:179], v133 offset:3072
	ds_read_b128 v[180:183], v133 offset:3088
	ds_read_b128 v[184:187], v133 offset:19456
	ds_read_b128 v[188:191], v133 offset:19472
	ds_read_b128 v[192:195], v133 offset:35840
	ds_read_b128 v[196:199], v133 offset:35856
	s_waitcnt lgkmcnt(10)
; template <int CTRL> __device__ __forceinline__ float dppf(float x) { return __builtin_bit_cast(float, __builtin_amdgcn_mov_dpp(__builtin_bit_cast(int, x), CTRL, 0xf, 0xf, true)); }
; #define LDOPS(s_) do { const float* p_ = bb + (s_) * 64; w4[(s_) % 3] = *(const f32x4*)(p_); a4[(s_) % 3] = *(const f32x4*)(p_ + 2048); b4[(s_) % 3] = *(const f32x4*)(p_ + 4096); k4[(s_) % 3] = *(const f32x4*)(p_ + 6144); \
;               r4[(s_) % 3] = *(const f32x4*)(p_ + 8192); vv[(s_) % 3] = vb[(s_) * 64]; } while (0)
; __device__ __forceinline__ void scan_block(unsigned char* shm, int sid, int half) {
;     ...
;           for (int s = 0; s < TS; ++s) {
;               const f32x4 a_ = a4[s % 3], w_ = w4[s % 3], b_ = b4[s % 3], k_ = k4[s % 3], r_ = r4[s % 3];
;               const float av[4] = {a_.x, a_.y, a_.z, a_.w}, wv[4] = {w_.x, w_.y, w_.z, w_.w}, bv[4] = {b_.x, b_.y, b_.z, b_.w}, kv[4] = {k_.x, k_.y, k_.z, k_.w}, rv[4] = {r_.x, r_.y, r_.z, r_.w};
;               const float v1 = vv[s % 3];
;               if (s + 2 < TS) LDOPS(s + 2);
;               float t = S[0] * av[0]; t = fmaf(S[1], av[1], t); t = fmaf(S[2], av[2], t); t = fmaf(S[3], av[3], t);
;               t += dppf<0xB1>(t); t += dppf<0x4E>(t); t += dppf<0x141>(t); t += dppf<0x140>(t);
; #pragma unroll
;               for (int q = 0; q < 4; ++q) S[q] = fmaf(S[q], wv[q], fmaf(bv[q], t, kv[q] * v1));
;               float u = S[0] * rv[0]; u = fmaf(S[1], rv[1], u); u = fmaf(S[2], rv[2], u); u = fmaf(S[3], rv[3], u);
;               u += dppf<0xB1>(u); u += dppf<0x4E>(u); u += dppf<0x141>(u); u += dppf<0x140>(u);
;               ys[s * 32] = u;
;           }
	v_fmac_f32_e32 v112, v40, v136
	v_fmac_f32_e32 v113, v41, v136
	v_fmac_f32_e32 v114, v42, v136
	v_fmac_f32_e32 v115, v43, v136
	v_fmac_f32_e32 v116, v44, v136
	v_fmac_f32_e32 v117, v45, v136
	v_fmac_f32_e32 v118, v46, v136
	v_fmac_f32_e32 v119, v47, v136
	v_fma_f32 v122, v122, v32, v112
	v_fma_f32 v123, v123, v33, v113
	v_fma_f32 v124, v124, v34, v114
	v_fma_f32 v125, v125, v35, v115
	v_fma_f32 v126, v126, v36, v116
	v_fma_f32 v127, v127, v37, v117
	v_fma_f32 v128, v128, v38, v118
	v_fma_f32 v129, v129, v39, v119
	v_mul_f32_e32 v136, v122, v140
	v_mul_f32_e32 v138, v48, v122
	v_fmac_f32_e32 v136, v123, v141
	v_fmac_f32_e32 v138, v123, v49
	v_fmac_f32_e32 v136, v124, v142
	v_fmac_f32_e32 v138, v124, v50
	v_fmac_f32_e32 v136, v125, v143
	v_fmac_f32_e32 v138, v125, v51
	v_fmac_f32_e32 v136, v126, v144
	v_fmac_f32_e32 v138, v126, v52
	v_fmac_f32_e32 v136, v127, v145
	v_fmac_f32_e32 v138, v127, v53
	v_fmac_f32_e32 v136, v128, v146
	v_fmac_f32_e32 v138, v128, v54
	v_fmac_f32_e32 v136, v129, v147
	v_fmac_f32_e32 v138, v129, v55
	v_mul_f32_e32 v112, v148, v106
	v_mul_f32_e32 v113, v149, v106
	v_add_f32_dpp v136, v136, v136 quad_perm:[1,0,3,2] row_mask:0xf bank_mask:0xf bound_ctrl:1
	v_add_f32_dpp v139, v137, v137 row_half_mirror row_mask:0xf bank_mask:0xf bound_ctrl:1
	v_add_f32_dpp v139, v138, v138 row_half_mirror row_mask:0xf bank_mask:0xa
	v_add_f32_dpp v136, v136, v136 quad_perm:[2,3,0,1] row_mask:0xf bank_mask:0xf bound_ctrl:1
	v_mul_f32_e32 v114, v150, v106
	v_mul_f32_e32 v115, v151, v106
	v_add_f32_dpp v139, v139, v139 quad_perm:[2,3,0,1] row_mask:0xf bank_mask:0xf bound_ctrl:1
	v_add_f32_dpp v136, v136, v136 row_half_mirror row_mask:0xf bank_mask:0xf bound_ctrl:1
	v_mul_f32_e32 v116, v152, v106
	v_mul_f32_e32 v117, v153, v106
	v_add_f32_dpp v139, v139, v139 quad_perm:[1,0,3,2] row_mask:0xf bank_mask:0xf bound_ctrl:1
	v_mul_f32_e32 v118, v154, v106
	v_mul_f32_e32 v119, v155, v106
	ds_write_b32 v135, v139 offset:1280
	ds_read_b128 v[140:143], v133 offset:11776
	ds_read_b128 v[144:147], v133 offset:11792
	ds_read_b128 v[148:151], v133 offset:28160
	ds_read_b128 v[152:155], v133 offset:28176
	ds_read2st64_b32 v[108:109], v134 offset0:174 offset1:175
	ds_read_b128 v[32:35], v133 offset:3328
	ds_read_b128 v[36:39], v133 offset:3344
	ds_read_b128 v[40:43], v133 offset:19712
	ds_read_b128 v[44:47], v133 offset:19728
	ds_read_b128 v[48:51], v133 offset:36096
	ds_read_b128 v[52:55], v133 offset:36112
	s_waitcnt lgkmcnt(11)
	v_fmac_f32_e32 v112, v184, v136
	v_fmac_f32_e32 v113, v185, v136
	v_fmac_f32_e32 v114, v186, v136
	v_fmac_f32_e32 v115, v187, v136
	v_fmac_f32_e32 v116, v188, v136
	v_fmac_f32_e32 v117, v189, v136
	v_fmac_f32_e32 v118, v190, v136
	v_fmac_f32_e32 v119, v191, v136
	v_fma_f32 v122, v122, v176, v112
	v_fma_f32 v123, v123, v177, v113
	v_fma_f32 v124, v124, v178, v114
	v_fma_f32 v125, v125, v179, v115
	v_fma_f32 v126, v126, v180, v116
	v_fma_f32 v127, v127, v181, v117
	v_fma_f32 v128, v128, v182, v118
	v_fma_f32 v129, v129, v183, v119
	v_mul_f32_e32 v136, v122, v158
	v_mul_f32_e32 v137, v192, v122
	v_fmac_f32_e32 v136, v123, v159
	v_fmac_f32_e32 v137, v123, v193
	v_fmac_f32_e32 v136, v124, v160
	v_fmac_f32_e32 v137, v124, v194
	v_fmac_f32_e32 v136, v125, v161
	v_fmac_f32_e32 v137, v125, v195
	v_fmac_f32_e32 v136, v126, v162
	v_fmac_f32_e32 v137, v126, v196
	v_fmac_f32_e32 v136, v127, v163
	v_fmac_f32_e32 v137, v127, v197
	v_fmac_f32_e32 v136, v128, v164
	v_fmac_f32_e32 v137, v128, v198
	v_fmac_f32_e32 v136, v129, v165
	v_fmac_f32_e32 v137, v129, v199
	v_mul_f32_e32 v112, v166, v107
	v_mul_f32_e32 v113, v167, v107
	v_add_f32_dpp v136, v136, v136 quad_perm:[1,0,3,2] row_mask:0xf bank_mask:0xf bound_ctrl:1
	v_mul_f32_e32 v114, v168, v107
	v_mul_f32_e32 v115, v169, v107
	v_add_f32_dpp v136, v136, v136 quad_perm:[2,3,0,1] row_mask:0xf bank_mask:0xf bound_ctrl:1
	v_mul_f32_e32 v116, v170, v107
	v_mul_f32_e32 v117, v171, v107
	v_add_f32_dpp v136, v136, v136 row_half_mirror row_mask:0xf bank_mask:0xf bound_ctrl:1
	v_mul_f32_e32 v118, v172, v107
	v_mul_f32_e32 v119, v173, v107
	ds_read_b128 v[158:161], v133 offset:12032
	ds_read_b128 v[162:165], v133 offset:12048
	ds_read_b128 v[166:169], v133 offset:28416
	ds_read_b128 v[170:173], v133 offset:28432
	ds_read_b128 v[176:179], v133 offset:3584
	ds_read_b128 v[180:183], v133 offset:3600
	ds_read_b128 v[184:187], v133 offset:19968
	ds_read_b128 v[188:191], v133 offset:19984
	ds_read_b128 v[192:195], v133 offset:36352
	ds_read_b128 v[196:199], v133 offset:36368
	s_waitcnt lgkmcnt(10)
; template <int CTRL> __device__ __forceinline__ float dppf(float x) { return __builtin_bit_cast(float, __builtin_amdgcn_mov_dpp(__builtin_bit_cast(int, x), CTRL, 0xf, 0xf, true)); }
; #define LDOPS(s_) do { const float* p_ = bb + (s_) * 64; w4[(s_) % 3] = *(const f32x4*)(p_); a4[(s_) % 3] = *(const f32x4*)(p_ + 2048); b4[(s_) % 3] = *(const f32x4*)(p_ + 4096); k4[(s_) % 3] = *(const f32x4*)(p_ + 6144); \
;               r4[(s_) % 3] = *(const f32x4*)(p_ + 8192); vv[(s_) % 3] = vb[(s_) * 64]; } while (0)
; __device__ __forceinline__ void scan_block(unsigned char* shm, int sid, int half) {
;     ...
;           for (int s = 0; s < TS; ++s) {
;               const f32x4 a_ = a4[s % 3], w_ = w4[s % 3], b_ = b4[s % 3], k_ = k4[s % 3], r_ = r4[s % 3];
;               const float av[4] = {a_.x, a_.y, a_.z, a_.w}, wv[4] = {w_.x, w_.y, w_.z, w_.w}, bv[4] = {b_.x, b_.y, b_.z, b_.w}, kv[4] = {k_.x, k_.y, k_.z, k_.w}, rv[4] = {r_.x, r_.y, r_.z, r_.w};
;               const float v1 = vv[s % 3];
;               if (s + 2 < TS) LDOPS(s + 2);
;               float t = S[0] * av[0]; t = fmaf(S[1], av[1], t); t = fmaf(S[2], av[2], t); t = fmaf(S[3], av[3], t);
;               t += dppf<0xB1>(t); t += dppf<0x4E>(t); t += dppf<0x141>(t); t += dppf<0x140>(t);
; #pragma unroll
;               for (int q = 0; q < 4; ++q) S[q] = fmaf(S[q], wv[q], fmaf(bv[q], t, kv[q] * v1));
;               float u = S[0] * rv[0]; u = fmaf(S[1], rv[1], u); u = fmaf(S[2], rv[2], u); u = fmaf(S[3], rv[3], u);
;               u += dppf<0xB1>(u); u += dppf<0x4E>(u); u += dppf<0x141>(u); u += dppf<0x140>(u);
;               ys[s * 32] = u;
;           }
	v_fmac_f32_e32 v112, v40, v136
	v_fmac_f32_e32 v113, v41, v136
	v_fmac_f32_e32 v114, v42, v136
	v_fmac_f32_e32 v115, v43, v136
	v_fmac_f32_e32 v116, v44, v136
	v_fmac_f32_e32 v117, v45, v136
	v_fmac_f32_e32 v118, v46, v136
	v_fmac_f32_e32 v119, v47, v136
	v_fma_f32 v122, v122, v32, v112
	v_fma_f32 v123, v123, v33, v113
	v_fma_f32 v124, v124, v34, v114
	v_fma_f32 v125, v125, v35, v115
	v_fma_f32 v126, v126, v36, v116
	v_fma_f32 v127, v127, v37, v117
	v_fma_f32 v128, v128, v38, v118
	v_fma_f32 v129, v129, v39, v119
	v_mul_f32_e32 v136, v122, v140
	v_mul_f32_e32 v138, v48, v122
	v_fmac_f32_e32 v136, v123, v141
	v_fmac_f32_e32 v138, v123, v49
	v_fmac_f32_e32 v136, v124, v142
	v_fmac_f32_e32 v138, v124, v50
	v_fmac_f32_e32 v136, v125, v143
	v_fmac_f32_e32 v138, v125, v51
	v_fmac_f32_e32 v136, v126, v144
	v_fmac_f32_e32 v138, v126, v52
	v_fmac_f32_e32 v136, v127, v145
	v_fmac_f32_e32 v138, v127, v53
	v_fmac_f32_e32 v136, v128, v146
	v_fmac_f32_e32 v138, v128, v54
	v_fmac_f32_e32 v136, v129, v147
	v_fmac_f32_e32 v138, v129, v55
	v_mul_f32_e32 v112, v148, v108
	v_mul_f32_e32 v113, v149, v108
	v_add_f32_dpp v136, v136, v136 quad_perm:[1,0,3,2] row_mask:0xf bank_mask:0xf bound_ctrl:1
	v_add_f32_dpp v139, v137, v137 row_half_mirror row_mask:0xf bank_mask:0xf bound_ctrl:1
	v_add_f32_dpp v139, v138, v138 row_half_mirror row_mask:0xf bank_mask:0xa
	v_add_f32_dpp v136, v136, v136 quad_perm:[2,3,0,1] row_mask:0xf bank_mask:0xf bound_ctrl:1
	v_mul_f32_e32 v114, v150, v108
	v_mul_f32_e32 v115, v151, v108
	v_add_f32_dpp v139, v139, v139 quad_perm:[2,3,0,1] row_mask:0xf bank_mask:0xf bound_ctrl:1
	v_add_f32_dpp v136, v136, v136 row_half_mirror row_mask:0xf bank_mask:0xf bound_ctrl:1
	v_mul_f32_e32 v116, v152, v108
	v_mul_f32_e32 v117, v153, v108
	v_add_f32_dpp v139, v139, v139 quad_perm:[1,0,3,2] row_mask:0xf bank_mask:0xf bound_ctrl:1
	v_mul_f32_e32 v118, v154, v108
	v_mul_f32_e32 v119, v155, v108
	ds_write_b32 v135, v139 offset:1536
	ds_read_b128 v[140:143], v133 offset:12288
	ds_read_b128 v[144:147], v133 offset:12304
	ds_read_b128 v[148:151], v133 offset:28672
	ds_read_b128 v[152:155], v133 offset:28688
	ds_read2st64_b32 v[106:107], v134 offset0:176 offset1:177
	ds_read_b128 v[32:35], v133 offset:3840
	ds_read_b128 v[36:39], v133 offset:3856
	ds_read_b128 v[40:43], v133 offset:20224
	ds_read_b128 v[44:47], v133 offset:20240
	ds_read_b128 v[48:51], v133 offset:36608
	ds_read_b128 v[52:55], v133 offset:36624
	s_waitcnt lgkmcnt(11)
	v_fmac_f32_e32 v112, v184, v136
	v_fmac_f32_e32 v113, v185, v136
	v_fmac_f32_e32 v114, v186, v136
	v_fmac_f32_e32 v115, v187, v136
	v_fmac_f32_e32 v116, v188, v136
	v_fmac_f32_e32 v117, v189, v136
	v_fmac_f32_e32 v118, v190, v136
	v_fmac_f32_e32 v119, v191, v136
	v_fma_f32 v122, v122, v176, v112
	v_fma_f32 v123, v123, v177, v113
	v_fma_f32 v124, v124, v178, v114
	v_fma_f32 v125, v125, v179, v115
	v_fma_f32 v126, v126, v180, v116
	v_fma_f32 v127, v127, v181, v117
	v_fma_f32 v128, v128, v182, v118
	v_fma_f32 v129, v129, v183, v119
	v_mul_f32_e32 v136, v122, v158
	v_mul_f32_e32 v137, v192, v122
	v_fmac_f32_e32 v136, v123, v159
	v_fmac_f32_e32 v137, v123, v193
	v_fmac_f32_e32 v136, v124, v160
	v_fmac_f32_e32 v137, v124, v194
	v_fmac_f32_e32 v136, v125, v161
	v_fmac_f32_e32 v137, v125, v195
	v_fmac_f32_e32 v136, v126, v162
	v_fmac_f32_e32 v137, v126, v196
	v_fmac_f32_e32 v136, v127, v163
	v_fmac_f32_e32 v137, v127, v197
	v_fmac_f32_e32 v136, v128, v164
	v_fmac_f32_e32 v137, v128, v198
	v_fmac_f32_e32 v136, v129, v165
	v_fmac_f32_e32 v137, v129, v199
	v_mul_f32_e32 v112, v166, v109
	v_mul_f32_e32 v113, v167, v109
	v_add_f32_dpp v136, v136, v136 quad_perm:[1,0,3,2] row_mask:0xf bank_mask:0xf bound_ctrl:1
	v_mul_f32_e32 v114, v168, v109
	v_mul_f32_e32 v115, v169, v109
	v_add_f32_dpp v136, v136, v136 quad_perm:[2,3,0,1] row_mask:0xf bank_mask:0xf bound_ctrl:1
	v_mul_f32_e32 v116, v170, v109
	v_mul_f32_e32 v117, v171, v109
	v_add_f32_dpp v136, v136, v136 row_half_mirror row_mask:0xf bank_mask:0xf bound_ctrl:1
	v_mul_f32_e32 v118, v172, v109
	v_mul_f32_e32 v119, v173, v109
	ds_read_b128 v[158:161], v133 offset:12544
	ds_read_b128 v[162:165], v133 offset:12560
	ds_read_b128 v[166:169], v133 offset:28928
	ds_read_b128 v[170:173], v133 offset:28944
	ds_read_b128 v[176:179], v133 offset:4096
	ds_read_b128 v[180:183], v133 offset:4112
	ds_read_b128 v[184:187], v133 offset:20480
	ds_read_b128 v[188:191], v133 offset:20496
	ds_read_b128 v[192:195], v133 offset:36864
	ds_read_b128 v[196:199], v133 offset:36880
	s_waitcnt lgkmcnt(10)
; template <int CTRL> __device__ __forceinline__ float dppf(float x) { return __builtin_bit_cast(float, __builtin_amdgcn_mov_dpp(__builtin_bit_cast(int, x), CTRL, 0xf, 0xf, true)); }
; #define LDOPS(s_) do { const float* p_ = bb + (s_) * 64; w4[(s_) % 3] = *(const f32x4*)(p_); a4[(s_) % 3] = *(const f32x4*)(p_ + 2048); b4[(s_) % 3] = *(const f32x4*)(p_ + 4096); k4[(s_) % 3] = *(const f32x4*)(p_ + 6144); \
;               r4[(s_) % 3] = *(const f32x4*)(p_ + 8192); vv[(s_) % 3] = vb[(s_) * 64]; } while (0)
; __device__ __forceinline__ void scan_block(unsigned char* shm, int sid, int half) {
;     ...
;           for (int s = 0; s < TS; ++s) {
;               const f32x4 a_ = a4[s % 3], w_ = w4[s % 3], b_ = b4[s % 3], k_ = k4[s % 3], r_ = r4[s % 3];
;               const float av[4] = {a_.x, a_.y, a_.z, a_.w}, wv[4] = {w_.x, w_.y, w_.z, w_.w}, bv[4] = {b_.x, b_.y, b_.z, b_.w}, kv[4] = {k_.x, k_.y, k_.z, k_.w}, rv[4] = {r_.x, r_.y, r_.z, r_.w};
;               const float v1 = vv[s % 3];
;               if (s + 2 < TS) LDOPS(s + 2);
;               float t = S[0] * av[0]; t = fmaf(S[1], av[1], t); t = fmaf(S[2], av[2], t); t = fmaf(S[3], av[3], t);
;               t += dppf<0xB1>(t); t += dppf<0x4E>(t); t += dppf<0x141>(t); t += dppf<0x140>(t);
; #pragma unroll
;               for (int q = 0; q < 4; ++q) S[q] = fmaf(S[q], wv[q], fmaf(bv[q], t, kv[q] * v1));
;               float u = S[0] * rv[0]; u = fmaf(S[1], rv[1], u); u = fmaf(S[2], rv[2], u); u = fmaf(S[3], rv[3], u);
;               u += dppf<0xB1>(u); u += dppf<0x4E>(u); u += dppf<0x141>(u); u += dppf<0x140>(u);
;               ys[s * 32] = u;
;           }
	v_fmac_f32_e32 v112, v40, v136
	v_fmac_f32_e32 v113, v41, v136
	v_fmac_f32_e32 v114, v42, v136
	v_fmac_f32_e32 v115, v43, v136
	v_fmac_f32_e32 v116, v44, v136
	v_fmac_f32_e32 v117, v45, v136
	v_fmac_f32_e32 v118, v46, v136
	v_fmac_f32_e32 v119, v47, v136
	v_fma_f32 v122, v122, v32, v112
	v_fma_f32 v123, v123, v33, v113
	v_fma_f32 v124, v124, v34, v114
	v_fma_f32 v125, v125, v35, v115
	v_fma_f32 v126, v126, v36, v116
	v_fma_f32 v127, v127, v37, v117
	v_fma_f32 v128, v128, v38, v118
	v_fma_f32 v129, v129, v39, v119
	v_mul_f32_e32 v136, v122, v140
	v_mul_f32_e32 v138, v48, v122
	v_fmac_f32_e32 v136, v123, v141
	v_fmac_f32_e32 v138, v123, v49
	v_fmac_f32_e32 v136, v124, v142
	v_fmac_f32_e32 v138, v124, v50
	v_fmac_f32_e32 v136, v125, v143
	v_fmac_f32_e32 v138, v125, v51
	v_fmac_f32_e32 v136, v126, v144
	v_fmac_f32_e32 v138, v126, v52
	v_fmac_f32_e32 v136, v127, v145
	v_fmac_f32_e32 v138, v127, v53
	v_fmac_f32_e32 v136, v128, v146
	v_fmac_f32_e32 v138, v128, v54
	v_fmac_f32_e32 v136, v129, v147
	v_fmac_f32_e32 v138, v129, v55
	v_mul_f32_e32 v112, v148, v106
	v_mul_f32_e32 v113, v149, v106
	v_add_f32_dpp v136, v136, v136 quad_perm:[1,0,3,2] row_mask:0xf bank_mask:0xf bound_ctrl:1
	v_add_f32_dpp v139, v137, v137 row_half_mirror row_mask:0xf bank_mask:0xf bound_ctrl:1
	v_add_f32_dpp v139, v138, v138 row_half_mirror row_mask:0xf bank_mask:0xa
	v_add_f32_dpp v136, v136, v136 quad_perm:[2,3,0,1] row_mask:0xf bank_mask:0xf bound_ctrl:1
	v_mul_f32_e32 v114, v150, v106
	v_mul_f32_e32 v115, v151, v106
	v_add_f32_dpp v139, v139, v139 quad_perm:[2,3,0,1] row_mask:0xf bank_mask:0xf bound_ctrl:1
	v_add_f32_dpp v136, v136, v136 row_half_mirror row_mask:0xf bank_mask:0xf bound_ctrl:1
	v_mul_f32_e32 v116, v152, v106
	v_mul_f32_e32 v117, v153, v106
	v_add_f32_dpp v139, v139, v139 quad_perm:[1,0,3,2] row_mask:0xf bank_mask:0xf bound_ctrl:1
	v_mul_f32_e32 v118, v154, v106
	v_mul_f32_e32 v119, v155, v106
	ds_write_b32 v135, v139 offset:1792
	ds_read_b128 v[140:143], v133 offset:12800
	ds_read_b128 v[144:147], v133 offset:12816
	ds_read_b128 v[148:151], v133 offset:29184
	ds_read_b128 v[152:155], v133 offset:29200
	ds_read2st64_b32 v[108:109], v134 offset0:178 offset1:179
	ds_read_b128 v[32:35], v133 offset:4352
	ds_read_b128 v[36:39], v133 offset:4368
	ds_read_b128 v[40:43], v133 offset:20736
	ds_read_b128 v[44:47], v133 offset:20752
	ds_read_b128 v[48:51], v133 offset:37120
	ds_read_b128 v[52:55], v133 offset:37136
	s_waitcnt lgkmcnt(11)
	v_fmac_f32_e32 v112, v184, v136
	v_fmac_f32_e32 v113, v185, v136
	v_fmac_f32_e32 v114, v186, v136
	v_fmac_f32_e32 v115, v187, v136
	v_fmac_f32_e32 v116, v188, v136
	v_fmac_f32_e32 v117, v189, v136
	v_fmac_f32_e32 v118, v190, v136
	v_fmac_f32_e32 v119, v191, v136
	v_fma_f32 v122, v122, v176, v112
	v_fma_f32 v123, v123, v177, v113
	v_fma_f32 v124, v124, v178, v114
	v_fma_f32 v125, v125, v179, v115
	v_fma_f32 v126, v126, v180, v116
	v_fma_f32 v127, v127, v181, v117
	v_fma_f32 v128, v128, v182, v118
	v_fma_f32 v129, v129, v183, v119
	v_mul_f32_e32 v136, v122, v158
	v_mul_f32_e32 v137, v192, v122
	v_fmac_f32_e32 v136, v123, v159
	v_fmac_f32_e32 v137, v123, v193
	v_fmac_f32_e32 v136, v124, v160
	v_fmac_f32_e32 v137, v124, v194
	v_fmac_f32_e32 v136, v125, v161
	v_fmac_f32_e32 v137, v125, v195
	v_fmac_f32_e32 v136, v126, v162
	v_fmac_f32_e32 v137, v126, v196
	v_fmac_f32_e32 v136, v127, v163
	v_fmac_f32_e32 v137, v127, v197
	v_fmac_f32_e32 v136, v128, v164
	v_fmac_f32_e32 v137, v128, v198
	v_fmac_f32_e32 v136, v129, v165
	v_fmac_f32_e32 v137, v129, v199
	v_mul_f32_e32 v112, v166, v107
	v_mul_f32_e32 v113, v167, v107
	v_add_f32_dpp v136, v136, v136 quad_perm:[1,0,3,2] row_mask:0xf bank_mask:0xf bound_ctrl:1
	v_mul_f32_e32 v114, v168, v107
	v_mul_f32_e32 v115, v169, v107
	v_add_f32_dpp v136, v136, v136 quad_perm:[2,3,0,1] row_mask:0xf bank_mask:0xf bound_ctrl:1
	v_mul_f32_e32 v116, v170, v107
	v_mul_f32_e32 v117, v171, v107
	v_add_f32_dpp v136, v136, v136 row_half_mirror row_mask:0xf bank_mask:0xf bound_ctrl:1
	v_mul_f32_e32 v118, v172, v107
	v_mul_f32_e32 v119, v173, v107
	ds_read_b128 v[158:161], v133 offset:13056
	ds_read_b128 v[162:165], v133 offset:13072
	ds_read_b128 v[166:169], v133 offset:29440
	ds_read_b128 v[170:173], v133 offset:29456
	ds_read_b128 v[176:179], v133 offset:4608
	ds_read_b128 v[180:183], v133 offset:4624
	ds_read_b128 v[184:187], v133 offset:20992
	ds_read_b128 v[188:191], v133 offset:21008
	ds_read_b128 v[192:195], v133 offset:37376
	ds_read_b128 v[196:199], v133 offset:37392
	s_waitcnt lgkmcnt(10)
; template <int CTRL> __device__ __forceinline__ float dppf(float x) { return __builtin_bit_cast(float, __builtin_amdgcn_mov_dpp(__builtin_bit_cast(int, x), CTRL, 0xf, 0xf, true)); }
; #define LDOPS(s_) do { const float* p_ = bb + (s_) * 64; w4[(s_) % 3] = *(const f32x4*)(p_); a4[(s_) % 3] = *(const f32x4*)(p_ + 2048); b4[(s_) % 3] = *(const f32x4*)(p_ + 4096); k4[(s_) % 3] = *(const f32x4*)(p_ + 6144); \
;               r4[(s_) % 3] = *(const f32x4*)(p_ + 8192); vv[(s_) % 3] = vb[(s_) * 64]; } while (0)
; __device__ __forceinline__ void scan_block(unsigned char* shm, int sid, int half) {
;     ...
;           for (int s = 0; s < TS; ++s) {
;               const f32x4 a_ = a4[s % 3], w_ = w4[s % 3], b_ = b4[s % 3], k_ = k4[s % 3], r_ = r4[s % 3];
;               const float av[4] = {a_.x, a_.y, a_.z, a_.w}, wv[4] = {w_.x, w_.y, w_.z, w_.w}, bv[4] = {b_.x, b_.y, b_.z, b_.w}, kv[4] = {k_.x, k_.y, k_.z, k_.w}, rv[4] = {r_.x, r_.y, r_.z, r_.w};
;               const float v1 = vv[s % 3];
;               if (s + 2 < TS) LDOPS(s + 2);
;               float t = S[0] * av[0]; t = fmaf(S[1], av[1], t); t = fmaf(S[2], av[2], t); t = fmaf(S[3], av[3], t);
;               t += dppf<0xB1>(t); t += dppf<0x4E>(t); t += dppf<0x141>(t); t += dppf<0x140>(t);
; #pragma unroll
;               for (int q = 0; q < 4; ++q) S[q] = fmaf(S[q], wv[q], fmaf(bv[q], t, kv[q] * v1));
;               float u = S[0] * rv[0]; u = fmaf(S[1], rv[1], u); u = fmaf(S[2], rv[2], u); u = fmaf(S[3], rv[3], u);
;               u += dppf<0xB1>(u); u += dppf<0x4E>(u); u += dppf<0x141>(u); u += dppf<0x140>(u);
;               ys[s * 32] = u;
;           }
	v_fmac_f32_e32 v112, v40, v136
	v_fmac_f32_e32 v113, v41, v136
	v_fmac_f32_e32 v114, v42, v136
	v_fmac_f32_e32 v115, v43, v136
	v_fmac_f32_e32 v116, v44, v136
	v_fmac_f32_e32 v117, v45, v136
	v_fmac_f32_e32 v118, v46, v136
	v_fmac_f32_e32 v119, v47, v136
	v_fma_f32 v122, v122, v32, v112
	v_fma_f32 v123, v123, v33, v113
	v_fma_f32 v124, v124, v34, v114
	v_fma_f32 v125, v125, v35, v115
	v_fma_f32 v126, v126, v36, v116
	v_fma_f32 v127, v127, v37, v117
	v_fma_f32 v128, v128, v38, v118
	v_fma_f32 v129, v129, v39, v119
	v_mul_f32_e32 v136, v122, v140
	v_mul_f32_e32 v138, v48, v122
	v_fmac_f32_e32 v136, v123, v141
	v_fmac_f32_e32 v138, v123, v49
	v_fmac_f32_e32 v136, v124, v142
	v_fmac_f32_e32 v138, v124, v50
	v_fmac_f32_e32 v136, v125, v143
	v_fmac_f32_e32 v138, v125, v51
	v_fmac_f32_e32 v136, v126, v144
	v_fmac_f32_e32 v138, v126, v52
	v_fmac_f32_e32 v136, v127, v145
	v_fmac_f32_e32 v138, v127, v53
	v_fmac_f32_e32 v136, v128, v146
	v_fmac_f32_e32 v138, v128, v54
	v_fmac_f32_e32 v136, v129, v147
	v_fmac_f32_e32 v138, v129, v55
	v_mul_f32_e32 v112, v148, v108
	v_mul_f32_e32 v113, v149, v108
	v_add_f32_dpp v136, v136, v136 quad_perm:[1,0,3,2] row_mask:0xf bank_mask:0xf bound_ctrl:1
	v_add_f32_dpp v139, v137, v137 row_half_mirror row_mask:0xf bank_mask:0xf bound_ctrl:1
	v_add_f32_dpp v139, v138, v138 row_half_mirror row_mask:0xf bank_mask:0xa
	v_add_f32_dpp v136, v136, v136 quad_perm:[2,3,0,1] row_mask:0xf bank_mask:0xf bound_ctrl:1
	v_mul_f32_e32 v114, v150, v108
	v_mul_f32_e32 v115, v151, v108
	v_add_f32_dpp v139, v139, v139 quad_perm:[2,3,0,1] row_mask:0xf bank_mask:0xf bound_ctrl:1
	v_add_f32_dpp v136, v136, v136 row_half_mirror row_mask:0xf bank_mask:0xf bound_ctrl:1
	v_mul_f32_e32 v116, v152, v108
	v_mul_f32_e32 v117, v153, v108
	v_add_f32_dpp v139, v139, v139 quad_perm:[1,0,3,2] row_mask:0xf bank_mask:0xf bound_ctrl:1
	v_mul_f32_e32 v118, v154, v108
	v_mul_f32_e32 v119, v155, v108
	ds_write_b32 v135, v139 offset:2048
	ds_read_b128 v[140:143], v133 offset:13312
	ds_read_b128 v[144:147], v133 offset:13328
	ds_read_b128 v[148:151], v133 offset:29696
	ds_read_b128 v[152:155], v133 offset:29712
	ds_read2st64_b32 v[106:107], v134 offset0:180 offset1:181
	ds_read_b128 v[32:35], v133 offset:4864
	ds_read_b128 v[36:39], v133 offset:4880
	ds_read_b128 v[40:43], v133 offset:21248
	ds_read_b128 v[44:47], v133 offset:21264
	ds_read_b128 v[48:51], v133 offset:37632
	ds_read_b128 v[52:55], v133 offset:37648
	s_waitcnt lgkmcnt(11)
	v_fmac_f32_e32 v112, v184, v136
	v_fmac_f32_e32 v113, v185, v136
	v_fmac_f32_e32 v114, v186, v136
	v_fmac_f32_e32 v115, v187, v136
	v_fmac_f32_e32 v116, v188, v136
	v_fmac_f32_e32 v117, v189, v136
	v_fmac_f32_e32 v118, v190, v136
	v_fmac_f32_e32 v119, v191, v136
	v_fma_f32 v122, v122, v176, v112
	v_fma_f32 v123, v123, v177, v113
	v_fma_f32 v124, v124, v178, v114
	v_fma_f32 v125, v125, v179, v115
	v_fma_f32 v126, v126, v180, v116
	v_fma_f32 v127, v127, v181, v117
	v_fma_f32 v128, v128, v182, v118
	v_fma_f32 v129, v129, v183, v119
	v_mul_f32_e32 v136, v122, v158
	v_mul_f32_e32 v137, v192, v122
	v_fmac_f32_e32 v136, v123, v159
	v_fmac_f32_e32 v137, v123, v193
	v_fmac_f32_e32 v136, v124, v160
	v_fmac_f32_e32 v137, v124, v194
	v_fmac_f32_e32 v136, v125, v161
	v_fmac_f32_e32 v137, v125, v195
	v_fmac_f32_e32 v136, v126, v162
	v_fmac_f32_e32 v137, v126, v196
	v_fmac_f32_e32 v136, v127, v163
	v_fmac_f32_e32 v137, v127, v197
	v_fmac_f32_e32 v136, v128, v164
	v_fmac_f32_e32 v137, v128, v198
	v_fmac_f32_e32 v136, v129, v165
	v_fmac_f32_e32 v137, v129, v199
	v_mul_f32_e32 v112, v166, v109
	v_mul_f32_e32 v113, v167, v109
	v_add_f32_dpp v136, v136, v136 quad_perm:[1,0,3,2] row_mask:0xf bank_mask:0xf bound_ctrl:1
	v_mul_f32_e32 v114, v168, v109
	v_mul_f32_e32 v115, v169, v109
	v_add_f32_dpp v136, v136, v136 quad_perm:[2,3,0,1] row_mask:0xf bank_mask:0xf bound_ctrl:1
	v_mul_f32_e32 v116, v170, v109
	v_mul_f32_e32 v117, v171, v109
	v_add_f32_dpp v136, v136, v136 row_half_mirror row_mask:0xf bank_mask:0xf bound_ctrl:1
	v_mul_f32_e32 v118, v172, v109
	v_mul_f32_e32 v119, v173, v109
	ds_read_b128 v[158:161], v133 offset:13568
	ds_read_b128 v[162:165], v133 offset:13584
	ds_read_b128 v[166:169], v133 offset:29952
	ds_read_b128 v[170:173], v133 offset:29968
	ds_read_b128 v[176:179], v133 offset:5120
	ds_read_b128 v[180:183], v133 offset:5136
	ds_read_b128 v[184:187], v133 offset:21504
	ds_read_b128 v[188:191], v133 offset:21520
	ds_read_b128 v[192:195], v133 offset:37888
	ds_read_b128 v[196:199], v133 offset:37904
	s_waitcnt lgkmcnt(10)
; template <int CTRL> __device__ __forceinline__ float dppf(float x) { return __builtin_bit_cast(float, __builtin_amdgcn_mov_dpp(__builtin_bit_cast(int, x), CTRL, 0xf, 0xf, true)); }
; #define LDOPS(s_) do { const float* p_ = bb + (s_) * 64; w4[(s_) % 3] = *(const f32x4*)(p_); a4[(s_) % 3] = *(const f32x4*)(p_ + 2048); b4[(s_) % 3] = *(const f32x4*)(p_ + 4096); k4[(s_) % 3] = *(const f32x4*)(p_ + 6144); \
;               r4[(s_) % 3] = *(const f32x4*)(p_ + 8192); vv[(s_) % 3] = vb[(s_) * 64]; } while (0)
; __device__ __forceinline__ void scan_block(unsigned char* shm, int sid, int half) {
;     ...
;           for (int s = 0; s < TS; ++s) {
;               const f32x4 a_ = a4[s % 3], w_ = w4[s % 3], b_ = b4[s % 3], k_ = k4[s % 3], r_ = r4[s % 3];
;               const float av[4] = {a_.x, a_.y, a_.z, a_.w}, wv[4] = {w_.x, w_.y, w_.z, w_.w}, bv[4] = {b_.x, b_.y, b_.z, b_.w}, kv[4] = {k_.x, k_.y, k_.z, k_.w}, rv[4] = {r_.x, r_.y, r_.z, r_.w};
;               const float v1 = vv[s % 3];
;               if (s + 2 < TS) LDOPS(s + 2);
;               float t = S[0] * av[0]; t = fmaf(S[1], av[1], t); t = fmaf(S[2], av[2], t); t = fmaf(S[3], av[3], t);
;               t += dppf<0xB1>(t); t += dppf<0x4E>(t); t += dppf<0x141>(t); t += dppf<0x140>(t);
; #pragma unroll
;               for (int q = 0; q < 4; ++q) S[q] = fmaf(S[q], wv[q], fmaf(bv[q], t, kv[q] * v1));
;               float u = S[0] * rv[0]; u = fmaf(S[1], rv[1], u); u = fmaf(S[2], rv[2], u); u = fmaf(S[3], rv[3], u);
;               u += dppf<0xB1>(u); u += dppf<0x4E>(u); u += dppf<0x141>(u); u += dppf<0x140>(u);
;               ys[s * 32] = u;
;           }
	v_fmac_f32_e32 v112, v40, v136
	v_fmac_f32_e32 v113, v41, v136
	v_fmac_f32_e32 v114, v42, v136
	v_fmac_f32_e32 v115, v43, v136
	v_fmac_f32_e32 v116, v44, v136
	v_fmac_f32_e32 v117, v45, v136
	v_fmac_f32_e32 v118, v46, v136
	v_fmac_f32_e32 v119, v47, v136
	v_fma_f32 v122, v122, v32, v112
	v_fma_f32 v123, v123, v33, v113
	v_fma_f32 v124, v124, v34, v114
	v_fma_f32 v125, v125, v35, v115
	v_fma_f32 v126, v126, v36, v116
	v_fma_f32 v127, v127, v37, v117
	v_fma_f32 v128, v128, v38, v118
	v_fma_f32 v129, v129, v39, v119
	v_mul_f32_e32 v136, v122, v140
	v_mul_f32_e32 v138, v48, v122
	v_fmac_f32_e32 v136, v123, v141
	v_fmac_f32_e32 v138, v123, v49
	v_fmac_f32_e32 v136, v124, v142
	v_fmac_f32_e32 v138, v124, v50
	v_fmac_f32_e32 v136, v125, v143
	v_fmac_f32_e32 v138, v125, v51
	v_fmac_f32_e32 v136, v126, v144
	v_fmac_f32_e32 v138, v126, v52
	v_fmac_f32_e32 v136, v127, v145
	v_fmac_f32_e32 v138, v127, v53
	v_fmac_f32_e32 v136, v128, v146
	v_fmac_f32_e32 v138, v128, v54
	v_fmac_f32_e32 v136, v129, v147
	v_fmac_f32_e32 v138, v129, v55
	v_mul_f32_e32 v112, v148, v106
	v_mul_f32_e32 v113, v149, v106
	v_add_f32_dpp v136, v136, v136 quad_perm:[1,0,3,2] row_mask:0xf bank_mask:0xf bound_ctrl:1
	v_add_f32_dpp v139, v137, v137 row_half_mirror row_mask:0xf bank_mask:0xf bound_ctrl:1
	v_add_f32_dpp v139, v138, v138 row_half_mirror row_mask:0xf bank_mask:0xa
	v_add_f32_dpp v136, v136, v136 quad_perm:[2,3,0,1] row_mask:0xf bank_mask:0xf bound_ctrl:1
	v_mul_f32_e32 v114, v150, v106
	v_mul_f32_e32 v115, v151, v106
	v_add_f32_dpp v139, v139, v139 quad_perm:[2,3,0,1] row_mask:0xf bank_mask:0xf bound_ctrl:1
	v_add_f32_dpp v136, v136, v136 row_half_mirror row_mask:0xf bank_mask:0xf bound_ctrl:1
	v_mul_f32_e32 v116, v152, v106
	v_mul_f32_e32 v117, v153, v106
	v_add_f32_dpp v139, v139, v139 quad_perm:[1,0,3,2] row_mask:0xf bank_mask:0xf bound_ctrl:1
	v_mul_f32_e32 v118, v154, v106
	v_mul_f32_e32 v119, v155, v106
	ds_write_b32 v135, v139 offset:2304
	ds_read_b128 v[140:143], v133 offset:13824
	ds_read_b128 v[144:147], v133 offset:13840
	ds_read_b128 v[148:151], v133 offset:30208
	ds_read_b128 v[152:155], v133 offset:30224
	ds_read2st64_b32 v[108:109], v134 offset0:182 offset1:183
	ds_read_b128 v[32:35], v133 offset:5376
	ds_read_b128 v[36:39], v133 offset:5392
	ds_read_b128 v[40:43], v133 offset:21760
	ds_read_b128 v[44:47], v133 offset:21776
	ds_read_b128 v[48:51], v133 offset:38144
	ds_read_b128 v[52:55], v133 offset:38160
	s_waitcnt lgkmcnt(11)
	v_fmac_f32_e32 v112, v184, v136
	v_fmac_f32_e32 v113, v185, v136
	v_fmac_f32_e32 v114, v186, v136
	v_fmac_f32_e32 v115, v187, v136
	v_fmac_f32_e32 v116, v188, v136
	v_fmac_f32_e32 v117, v189, v136
	v_fmac_f32_e32 v118, v190, v136
	v_fmac_f32_e32 v119, v191, v136
	v_fma_f32 v122, v122, v176, v112
	v_fma_f32 v123, v123, v177, v113
	v_fma_f32 v124, v124, v178, v114
	v_fma_f32 v125, v125, v179, v115
	v_fma_f32 v126, v126, v180, v116
	v_fma_f32 v127, v127, v181, v117
	v_fma_f32 v128, v128, v182, v118
	v_fma_f32 v129, v129, v183, v119
	v_mul_f32_e32 v136, v122, v158
	v_mul_f32_e32 v137, v192, v122
	v_fmac_f32_e32 v136, v123, v159
	v_fmac_f32_e32 v137, v123, v193
	v_fmac_f32_e32 v136, v124, v160
	v_fmac_f32_e32 v137, v124, v194
	v_fmac_f32_e32 v136, v125, v161
	v_fmac_f32_e32 v137, v125, v195
	v_fmac_f32_e32 v136, v126, v162
	v_fmac_f32_e32 v137, v126, v196
	v_fmac_f32_e32 v136, v127, v163
	v_fmac_f32_e32 v137, v127, v197
	v_fmac_f32_e32 v136, v128, v164
	v_fmac_f32_e32 v137, v128, v198
	v_fmac_f32_e32 v136, v129, v165
	v_fmac_f32_e32 v137, v129, v199
	v_mul_f32_e32 v112, v166, v107
	v_mul_f32_e32 v113, v167, v107
	v_add_f32_dpp v136, v136, v136 quad_perm:[1,0,3,2] row_mask:0xf bank_mask:0xf bound_ctrl:1
	v_mul_f32_e32 v114, v168, v107
	v_mul_f32_e32 v115, v169, v107
	v_add_f32_dpp v136, v136, v136 quad_perm:[2,3,0,1] row_mask:0xf bank_mask:0xf bound_ctrl:1
	v_mul_f32_e32 v116, v170, v107
	v_mul_f32_e32 v117, v171, v107
	v_add_f32_dpp v136, v136, v136 row_half_mirror row_mask:0xf bank_mask:0xf bound_ctrl:1
	v_mul_f32_e32 v118, v172, v107
	v_mul_f32_e32 v119, v173, v107
	ds_read_b128 v[158:161], v133 offset:14080
	ds_read_b128 v[162:165], v133 offset:14096
	ds_read_b128 v[166:169], v133 offset:30464
	ds_read_b128 v[170:173], v133 offset:30480
	ds_read_b128 v[176:179], v133 offset:5632
	ds_read_b128 v[180:183], v133 offset:5648
	ds_read_b128 v[184:187], v133 offset:22016
	ds_read_b128 v[188:191], v133 offset:22032
	ds_read_b128 v[192:195], v133 offset:38400
	ds_read_b128 v[196:199], v133 offset:38416
	s_waitcnt lgkmcnt(10)
; template <int CTRL> __device__ __forceinline__ float dppf(float x) { return __builtin_bit_cast(float, __builtin_amdgcn_mov_dpp(__builtin_bit_cast(int, x), CTRL, 0xf, 0xf, true)); }
; #define LDOPS(s_) do { const float* p_ = bb + (s_) * 64; w4[(s_) % 3] = *(const f32x4*)(p_); a4[(s_) % 3] = *(const f32x4*)(p_ + 2048); b4[(s_) % 3] = *(const f32x4*)(p_ + 4096); k4[(s_) % 3] = *(const f32x4*)(p_ + 6144); \
;               r4[(s_) % 3] = *(const f32x4*)(p_ + 8192); vv[(s_) % 3] = vb[(s_) * 64]; } while (0)
; __device__ __forceinline__ void scan_block(unsigned char* shm, int sid, int half) {
;     ...
;           for (int s = 0; s < TS; ++s) {
;               const f32x4 a_ = a4[s % 3], w_ = w4[s % 3], b_ = b4[s % 3], k_ = k4[s % 3], r_ = r4[s % 3];
;               const float av[4] = {a_.x, a_.y, a_.z, a_.w}, wv[4] = {w_.x, w_.y, w_.z, w_.w}, bv[4] = {b_.x, b_.y, b_.z, b_.w}, kv[4] = {k_.x, k_.y, k_.z, k_.w}, rv[4] = {r_.x, r_.y, r_.z, r_.w};
;               const float v1 = vv[s % 3];
;               if (s + 2 < TS) LDOPS(s + 2);
;               float t = S[0] * av[0]; t = fmaf(S[1], av[1], t); t = fmaf(S[2], av[2], t); t = fmaf(S[3], av[3], t);
;               t += dppf<0xB1>(t); t += dppf<0x4E>(t); t += dppf<0x141>(t); t += dppf<0x140>(t);
; #pragma unroll
;               for (int q = 0; q < 4; ++q) S[q] = fmaf(S[q], wv[q], fmaf(bv[q], t, kv[q] * v1));
;               float u = S[0] * rv[0]; u = fmaf(S[1], rv[1], u); u = fmaf(S[2], rv[2], u); u = fmaf(S[3], rv[3], u);
;               u += dppf<0xB1>(u); u += dppf<0x4E>(u); u += dppf<0x141>(u); u += dppf<0x140>(u);
;               ys[s * 32] = u;
;           }
	v_fmac_f32_e32 v112, v40, v136
	v_fmac_f32_e32 v113, v41, v136
	v_fmac_f32_e32 v114, v42, v136
	v_fmac_f32_e32 v115, v43, v136
	v_fmac_f32_e32 v116, v44, v136
	v_fmac_f32_e32 v117, v45, v136
	v_fmac_f32_e32 v118, v46, v136
	v_fmac_f32_e32 v119, v47, v136
	v_fma_f32 v122, v122, v32, v112
	v_fma_f32 v123, v123, v33, v113
	v_fma_f32 v124, v124, v34, v114
	v_fma_f32 v125, v125, v35, v115
	v_fma_f32 v126, v126, v36, v116
	v_fma_f32 v127, v127, v37, v117
	v_fma_f32 v128, v128, v38, v118
	v_fma_f32 v129, v129, v39, v119
	v_mul_f32_e32 v136, v122, v140
	v_mul_f32_e32 v138, v48, v122
	v_fmac_f32_e32 v136, v123, v141
	v_fmac_f32_e32 v138, v123, v49
	v_fmac_f32_e32 v136, v124, v142
	v_fmac_f32_e32 v138, v124, v50
	v_fmac_f32_e32 v136, v125, v143
	v_fmac_f32_e32 v138, v125, v51
	v_fmac_f32_e32 v136, v126, v144
	v_fmac_f32_e32 v138, v126, v52
	v_fmac_f32_e32 v136, v127, v145
	v_fmac_f32_e32 v138, v127, v53
	v_fmac_f32_e32 v136, v128, v146
	v_fmac_f32_e32 v138, v128, v54
	v_fmac_f32_e32 v136, v129, v147
	v_fmac_f32_e32 v138, v129, v55
	v_mul_f32_e32 v112, v148, v108
	v_mul_f32_e32 v113, v149, v108
	v_add_f32_dpp v136, v136, v136 quad_perm:[1,0,3,2] row_mask:0xf bank_mask:0xf bound_ctrl:1
	v_add_f32_dpp v139, v137, v137 row_half_mirror row_mask:0xf bank_mask:0xf bound_ctrl:1
	v_add_f32_dpp v139, v138, v138 row_half_mirror row_mask:0xf bank_mask:0xa
	v_add_f32_dpp v136, v136, v136 quad_perm:[2,3,0,1] row_mask:0xf bank_mask:0xf bound_ctrl:1
	v_mul_f32_e32 v114, v150, v108
	v_mul_f32_e32 v115, v151, v108
	v_add_f32_dpp v139, v139, v139 quad_perm:[2,3,0,1] row_mask:0xf bank_mask:0xf bound_ctrl:1
	v_add_f32_dpp v136, v136, v136 row_half_mirror row_mask:0xf bank_mask:0xf bound_ctrl:1
	v_mul_f32_e32 v116, v152, v108
	v_mul_f32_e32 v117, v153, v108
	v_add_f32_dpp v139, v139, v139 quad_perm:[1,0,3,2] row_mask:0xf bank_mask:0xf bound_ctrl:1
	v_mul_f32_e32 v118, v154, v108
	v_mul_f32_e32 v119, v155, v108
	ds_write_b32 v135, v139 offset:2560
	ds_read_b128 v[140:143], v133 offset:14336
	ds_read_b128 v[144:147], v133 offset:14352
	ds_read_b128 v[148:151], v133 offset:30720
	ds_read_b128 v[152:155], v133 offset:30736
	ds_read2st64_b32 v[106:107], v134 offset0:184 offset1:185
	ds_read_b128 v[32:35], v133 offset:5888
	ds_read_b128 v[36:39], v133 offset:5904
	ds_read_b128 v[40:43], v133 offset:22272
	ds_read_b128 v[44:47], v133 offset:22288
	ds_read_b128 v[48:51], v133 offset:38656
	ds_read_b128 v[52:55], v133 offset:38672
	s_waitcnt lgkmcnt(11)
	v_fmac_f32_e32 v112, v184, v136
	v_fmac_f32_e32 v113, v185, v136
	v_fmac_f32_e32 v114, v186, v136
	v_fmac_f32_e32 v115, v187, v136
	v_fmac_f32_e32 v116, v188, v136
	v_fmac_f32_e32 v117, v189, v136
	v_fmac_f32_e32 v118, v190, v136
	v_fmac_f32_e32 v119, v191, v136
	v_fma_f32 v122, v122, v176, v112
	v_fma_f32 v123, v123, v177, v113
	v_fma_f32 v124, v124, v178, v114
	v_fma_f32 v125, v125, v179, v115
	v_fma_f32 v126, v126, v180, v116
	v_fma_f32 v127, v127, v181, v117
	v_fma_f32 v128, v128, v182, v118
	v_fma_f32 v129, v129, v183, v119
	v_mul_f32_e32 v136, v122, v158
	v_mul_f32_e32 v137, v192, v122
	v_fmac_f32_e32 v136, v123, v159
	v_fmac_f32_e32 v137, v123, v193
	v_fmac_f32_e32 v136, v124, v160
	v_fmac_f32_e32 v137, v124, v194
	v_fmac_f32_e32 v136, v125, v161
	v_fmac_f32_e32 v137, v125, v195
	v_fmac_f32_e32 v136, v126, v162
	v_fmac_f32_e32 v137, v126, v196
	v_fmac_f32_e32 v136, v127, v163
	v_fmac_f32_e32 v137, v127, v197
	v_fmac_f32_e32 v136, v128, v164
	v_fmac_f32_e32 v137, v128, v198
	v_fmac_f32_e32 v136, v129, v165
	v_fmac_f32_e32 v137, v129, v199
	v_mul_f32_e32 v112, v166, v109
	v_mul_f32_e32 v113, v167, v109
	v_add_f32_dpp v136, v136, v136 quad_perm:[1,0,3,2] row_mask:0xf bank_mask:0xf bound_ctrl:1
	v_mul_f32_e32 v114, v168, v109
	v_mul_f32_e32 v115, v169, v109
	v_add_f32_dpp v136, v136, v136 quad_perm:[2,3,0,1] row_mask:0xf bank_mask:0xf bound_ctrl:1
	v_mul_f32_e32 v116, v170, v109
	v_mul_f32_e32 v117, v171, v109
	v_add_f32_dpp v136, v136, v136 row_half_mirror row_mask:0xf bank_mask:0xf bound_ctrl:1
	v_mul_f32_e32 v118, v172, v109
	v_mul_f32_e32 v119, v173, v109
	ds_read_b128 v[158:161], v133 offset:14592
	ds_read_b128 v[162:165], v133 offset:14608
	ds_read_b128 v[166:169], v133 offset:30976
	ds_read_b128 v[170:173], v133 offset:30992
	ds_read_b128 v[176:179], v133 offset:6144
	ds_read_b128 v[180:183], v133 offset:6160
	ds_read_b128 v[184:187], v133 offset:22528
	ds_read_b128 v[188:191], v133 offset:22544
	ds_read_b128 v[192:195], v133 offset:38912
	ds_read_b128 v[196:199], v133 offset:38928
	s_waitcnt lgkmcnt(10)
; template <int CTRL> __device__ __forceinline__ float dppf(float x) { return __builtin_bit_cast(float, __builtin_amdgcn_mov_dpp(__builtin_bit_cast(int, x), CTRL, 0xf, 0xf, true)); }
; #define LDOPS(s_) do { const float* p_ = bb + (s_) * 64; w4[(s_) % 3] = *(const f32x4*)(p_); a4[(s_) % 3] = *(const f32x4*)(p_ + 2048); b4[(s_) % 3] = *(const f32x4*)(p_ + 4096); k4[(s_) % 3] = *(const f32x4*)(p_ + 6144); \
;               r4[(s_) % 3] = *(const f32x4*)(p_ + 8192); vv[(s_) % 3] = vb[(s_) * 64]; } while (0)
; __device__ __forceinline__ void scan_block(unsigned char* shm, int sid, int half) {
;     ...
;           for (int s = 0; s < TS; ++s) {
;               const f32x4 a_ = a4[s % 3], w_ = w4[s % 3], b_ = b4[s % 3], k_ = k4[s % 3], r_ = r4[s % 3];
;               const float av[4] = {a_.x, a_.y, a_.z, a_.w}, wv[4] = {w_.x, w_.y, w_.z, w_.w}, bv[4] = {b_.x, b_.y, b_.z, b_.w}, kv[4] = {k_.x, k_.y, k_.z, k_.w}, rv[4] = {r_.x, r_.y, r_.z, r_.w};
;               const float v1 = vv[s % 3];
;               if (s + 2 < TS) LDOPS(s + 2);
;               float t = S[0] * av[0]; t = fmaf(S[1], av[1], t); t = fmaf(S[2], av[2], t); t = fmaf(S[3], av[3], t);
;               t += dppf<0xB1>(t); t += dppf<0x4E>(t); t += dppf<0x141>(t); t += dppf<0x140>(t);
; #pragma unroll
;               for (int q = 0; q < 4; ++q) S[q] = fmaf(S[q], wv[q], fmaf(bv[q], t, kv[q] * v1));
;               float u = S[0] * rv[0]; u = fmaf(S[1], rv[1], u); u = fmaf(S[2], rv[2], u); u = fmaf(S[3], rv[3], u);
;               u += dppf<0xB1>(u); u += dppf<0x4E>(u); u += dppf<0x141>(u); u += dppf<0x140>(u);
;               ys[s * 32] = u;
;           }
	v_fmac_f32_e32 v112, v40, v136
	v_fmac_f32_e32 v113, v41, v136
	v_fmac_f32_e32 v114, v42, v136
	v_fmac_f32_e32 v115, v43, v136
	v_fmac_f32_e32 v116, v44, v136
	v_fmac_f32_e32 v117, v45, v136
	v_fmac_f32_e32 v118, v46, v136
	v_fmac_f32_e32 v119, v47, v136
	v_fma_f32 v122, v122, v32, v112
	v_fma_f32 v123, v123, v33, v113
	v_fma_f32 v124, v124, v34, v114
	v_fma_f32 v125, v125, v35, v115
	v_fma_f32 v126, v126, v36, v116
	v_fma_f32 v127, v127, v37, v117
	v_fma_f32 v128, v128, v38, v118
	v_fma_f32 v129, v129, v39, v119
	v_mul_f32_e32 v136, v122, v140
	v_mul_f32_e32 v138, v48, v122
	v_fmac_f32_e32 v136, v123, v141
	v_fmac_f32_e32 v138, v123, v49
	v_fmac_f32_e32 v136, v124, v142
	v_fmac_f32_e32 v138, v124, v50
	v_fmac_f32_e32 v136, v125, v143
	v_fmac_f32_e32 v138, v125, v51
	v_fmac_f32_e32 v136, v126, v144
	v_fmac_f32_e32 v138, v126, v52
	v_fmac_f32_e32 v136, v127, v145
	v_fmac_f32_e32 v138, v127, v53
	v_fmac_f32_e32 v136, v128, v146
	v_fmac_f32_e32 v138, v128, v54
	v_fmac_f32_e32 v136, v129, v147
	v_fmac_f32_e32 v138, v129, v55
	v_mul_f32_e32 v112, v148, v106
	v_mul_f32_e32 v113, v149, v106
	v_add_f32_dpp v136, v136, v136 quad_perm:[1,0,3,2] row_mask:0xf bank_mask:0xf bound_ctrl:1
	v_add_f32_dpp v139, v137, v137 row_half_mirror row_mask:0xf bank_mask:0xf bound_ctrl:1
	v_add_f32_dpp v139, v138, v138 row_half_mirror row_mask:0xf bank_mask:0xa
	v_add_f32_dpp v136, v136, v136 quad_perm:[2,3,0,1] row_mask:0xf bank_mask:0xf bound_ctrl:1
	v_mul_f32_e32 v114, v150, v106
	v_mul_f32_e32 v115, v151, v106
	v_add_f32_dpp v139, v139, v139 quad_perm:[2,3,0,1] row_mask:0xf bank_mask:0xf bound_ctrl:1
	v_add_f32_dpp v136, v136, v136 row_half_mirror row_mask:0xf bank_mask:0xf bound_ctrl:1
	v_mul_f32_e32 v116, v152, v106
	v_mul_f32_e32 v117, v153, v106
	v_add_f32_dpp v139, v139, v139 quad_perm:[1,0,3,2] row_mask:0xf bank_mask:0xf bound_ctrl:1
	v_mul_f32_e32 v118, v154, v106
	v_mul_f32_e32 v119, v155, v106
	ds_write_b32 v135, v139 offset:2816
	ds_read_b128 v[140:143], v133 offset:14848
	ds_read_b128 v[144:147], v133 offset:14864
	ds_read_b128 v[148:151], v133 offset:31232
	ds_read_b128 v[152:155], v133 offset:31248
	ds_read2st64_b32 v[108:109], v134 offset0:186 offset1:187
	ds_read_b128 v[32:35], v133 offset:6400
	ds_read_b128 v[36:39], v133 offset:6416
	ds_read_b128 v[40:43], v133 offset:22784
	ds_read_b128 v[44:47], v133 offset:22800
	ds_read_b128 v[48:51], v133 offset:39168
	ds_read_b128 v[52:55], v133 offset:39184
	s_waitcnt lgkmcnt(11)
	v_fmac_f32_e32 v112, v184, v136
	v_fmac_f32_e32 v113, v185, v136
	v_fmac_f32_e32 v114, v186, v136
	v_fmac_f32_e32 v115, v187, v136
	v_fmac_f32_e32 v116, v188, v136
	v_fmac_f32_e32 v117, v189, v136
	v_fmac_f32_e32 v118, v190, v136
	v_fmac_f32_e32 v119, v191, v136
	v_fma_f32 v122, v122, v176, v112
	v_fma_f32 v123, v123, v177, v113
	v_fma_f32 v124, v124, v178, v114
	v_fma_f32 v125, v125, v179, v115
	v_fma_f32 v126, v126, v180, v116
	v_fma_f32 v127, v127, v181, v117
	v_fma_f32 v128, v128, v182, v118
	v_fma_f32 v129, v129, v183, v119
	v_mul_f32_e32 v136, v122, v158
	v_mul_f32_e32 v137, v192, v122
	v_fmac_f32_e32 v136, v123, v159
	v_fmac_f32_e32 v137, v123, v193
	v_fmac_f32_e32 v136, v124, v160
	v_fmac_f32_e32 v137, v124, v194
	v_fmac_f32_e32 v136, v125, v161
	v_fmac_f32_e32 v137, v125, v195
	v_fmac_f32_e32 v136, v126, v162
	v_fmac_f32_e32 v137, v126, v196
	v_fmac_f32_e32 v136, v127, v163
	v_fmac_f32_e32 v137, v127, v197
	v_fmac_f32_e32 v136, v128, v164
	v_fmac_f32_e32 v137, v128, v198
	v_fmac_f32_e32 v136, v129, v165
	v_fmac_f32_e32 v137, v129, v199
	v_mul_f32_e32 v112, v166, v107
	v_mul_f32_e32 v113, v167, v107
	v_add_f32_dpp v136, v136, v136 quad_perm:[1,0,3,2] row_mask:0xf bank_mask:0xf bound_ctrl:1
	v_mul_f32_e32 v114, v168, v107
	v_mul_f32_e32 v115, v169, v107
	v_add_f32_dpp v136, v136, v136 quad_perm:[2,3,0,1] row_mask:0xf bank_mask:0xf bound_ctrl:1
	v_mul_f32_e32 v116, v170, v107
	v_mul_f32_e32 v117, v171, v107
	v_add_f32_dpp v136, v136, v136 row_half_mirror row_mask:0xf bank_mask:0xf bound_ctrl:1
	v_mul_f32_e32 v118, v172, v107
	v_mul_f32_e32 v119, v173, v107
	ds_read_b128 v[158:161], v133 offset:15104
	ds_read_b128 v[162:165], v133 offset:15120
	ds_read_b128 v[166:169], v133 offset:31488
	ds_read_b128 v[170:173], v133 offset:31504
	ds_read_b128 v[176:179], v133 offset:6656
	ds_read_b128 v[180:183], v133 offset:6672
	ds_read_b128 v[184:187], v133 offset:23040
	ds_read_b128 v[188:191], v133 offset:23056
	ds_read_b128 v[192:195], v133 offset:39424
	ds_read_b128 v[196:199], v133 offset:39440
	s_waitcnt lgkmcnt(10)
; template <int CTRL> __device__ __forceinline__ float dppf(float x) { return __builtin_bit_cast(float, __builtin_amdgcn_mov_dpp(__builtin_bit_cast(int, x), CTRL, 0xf, 0xf, true)); }
; #define LDOPS(s_) do { const float* p_ = bb + (s_) * 64; w4[(s_) % 3] = *(const f32x4*)(p_); a4[(s_) % 3] = *(const f32x4*)(p_ + 2048); b4[(s_) % 3] = *(const f32x4*)(p_ + 4096); k4[(s_) % 3] = *(const f32x4*)(p_ + 6144); \
;               r4[(s_) % 3] = *(const f32x4*)(p_ + 8192); vv[(s_) % 3] = vb[(s_) * 64]; } while (0)
; __device__ __forceinline__ void scan_block(unsigned char* shm, int sid, int half) {
;     ...
;           for (int s = 0; s < TS; ++s) {
;               const f32x4 a_ = a4[s % 3], w_ = w4[s % 3], b_ = b4[s % 3], k_ = k4[s % 3], r_ = r4[s % 3];
;               const float av[4] = {a_.x, a_.y, a_.z, a_.w}, wv[4] = {w_.x, w_.y, w_.z, w_.w}, bv[4] = {b_.x, b_.y, b_.z, b_.w}, kv[4] = {k_.x, k_.y, k_.z, k_.w}, rv[4] = {r_.x, r_.y, r_.z, r_.w};
;               const float v1 = vv[s % 3];
;               if (s + 2 < TS) LDOPS(s + 2);
;               float t = S[0] * av[0]; t = fmaf(S[1], av[1], t); t = fmaf(S[2], av[2], t); t = fmaf(S[3], av[3], t);
;               t += dppf<0xB1>(t); t += dppf<0x4E>(t); t += dppf<0x141>(t); t += dppf<0x140>(t);
; #pragma unroll
;               for (int q = 0; q < 4; ++q) S[q] = fmaf(S[q], wv[q], fmaf(bv[q], t, kv[q] * v1));
;               float u = S[0] * rv[0]; u = fmaf(S[1], rv[1], u); u = fmaf(S[2], rv[2], u); u = fmaf(S[3], rv[3], u);
;               u += dppf<0xB1>(u); u += dppf<0x4E>(u); u += dppf<0x141>(u); u += dppf<0x140>(u);
;               ys[s * 32] = u;
;           }
	v_fmac_f32_e32 v112, v40, v136
	v_fmac_f32_e32 v113, v41, v136
	v_fmac_f32_e32 v114, v42, v136
	v_fmac_f32_e32 v115, v43, v136
	v_fmac_f32_e32 v116, v44, v136
	v_fmac_f32_e32 v117, v45, v136
	v_fmac_f32_e32 v118, v46, v136
	v_fmac_f32_e32 v119, v47, v136
	v_fma_f32 v122, v122, v32, v112
	v_fma_f32 v123, v123, v33, v113
	v_fma_f32 v124, v124, v34, v114
	v_fma_f32 v125, v125, v35, v115
	v_fma_f32 v126, v126, v36, v116
	v_fma_f32 v127, v127, v37, v117
	v_fma_f32 v128, v128, v38, v118
	v_fma_f32 v129, v129, v39, v119
	v_mul_f32_e32 v136, v122, v140
	v_mul_f32_e32 v138, v48, v122
	v_fmac_f32_e32 v136, v123, v141
	v_fmac_f32_e32 v138, v123, v49
	v_fmac_f32_e32 v136, v124, v142
	v_fmac_f32_e32 v138, v124, v50
	v_fmac_f32_e32 v136, v125, v143
	v_fmac_f32_e32 v138, v125, v51
	v_fmac_f32_e32 v136, v126, v144
	v_fmac_f32_e32 v138, v126, v52
	v_fmac_f32_e32 v136, v127, v145
	v_fmac_f32_e32 v138, v127, v53
	v_fmac_f32_e32 v136, v128, v146
	v_fmac_f32_e32 v138, v128, v54
	v_fmac_f32_e32 v136, v129, v147
	v_fmac_f32_e32 v138, v129, v55
	v_mul_f32_e32 v112, v148, v108
	v_mul_f32_e32 v113, v149, v108
	v_add_f32_dpp v136, v136, v136 quad_perm:[1,0,3,2] row_mask:0xf bank_mask:0xf bound_ctrl:1
	v_add_f32_dpp v139, v137, v137 row_half_mirror row_mask:0xf bank_mask:0xf bound_ctrl:1
	v_add_f32_dpp v139, v138, v138 row_half_mirror row_mask:0xf bank_mask:0xa
	v_add_f32_dpp v136, v136, v136 quad_perm:[2,3,0,1] row_mask:0xf bank_mask:0xf bound_ctrl:1
	v_mul_f32_e32 v114, v150, v108
	v_mul_f32_e32 v115, v151, v108
	v_add_f32_dpp v139, v139, v139 quad_perm:[2,3,0,1] row_mask:0xf bank_mask:0xf bound_ctrl:1
	v_add_f32_dpp v136, v136, v136 row_half_mirror row_mask:0xf bank_mask:0xf bound_ctrl:1
	v_mul_f32_e32 v116, v152, v108
	v_mul_f32_e32 v117, v153, v108
	v_add_f32_dpp v139, v139, v139 quad_perm:[1,0,3,2] row_mask:0xf bank_mask:0xf bound_ctrl:1
	v_mul_f32_e32 v118, v154, v108
	v_mul_f32_e32 v119, v155, v108
	ds_write_b32 v135, v139 offset:3072
	ds_read_b128 v[140:143], v133 offset:15360
	ds_read_b128 v[144:147], v133 offset:15376
	ds_read_b128 v[148:151], v133 offset:31744
	ds_read_b128 v[152:155], v133 offset:31760
	ds_read2st64_b32 v[106:107], v134 offset0:188 offset1:189
	ds_read_b128 v[32:35], v133 offset:6912
	ds_read_b128 v[36:39], v133 offset:6928
	ds_read_b128 v[40:43], v133 offset:23296
	ds_read_b128 v[44:47], v133 offset:23312
	ds_read_b128 v[48:51], v133 offset:39680
	ds_read_b128 v[52:55], v133 offset:39696
	s_waitcnt lgkmcnt(11)
	v_fmac_f32_e32 v112, v184, v136
	v_fmac_f32_e32 v113, v185, v136
	v_fmac_f32_e32 v114, v186, v136
	v_fmac_f32_e32 v115, v187, v136
	v_fmac_f32_e32 v116, v188, v136
	v_fmac_f32_e32 v117, v189, v136
	v_fmac_f32_e32 v118, v190, v136
	v_fmac_f32_e32 v119, v191, v136
	v_fma_f32 v122, v122, v176, v112
	v_fma_f32 v123, v123, v177, v113
	v_fma_f32 v124, v124, v178, v114
	v_fma_f32 v125, v125, v179, v115
	v_fma_f32 v126, v126, v180, v116
	v_fma_f32 v127, v127, v181, v117
	v_fma_f32 v128, v128, v182, v118
	v_fma_f32 v129, v129, v183, v119
	v_mul_f32_e32 v136, v122, v158
	v_mul_f32_e32 v137, v192, v122
	v_fmac_f32_e32 v136, v123, v159
	v_fmac_f32_e32 v137, v123, v193
	v_fmac_f32_e32 v136, v124, v160
	v_fmac_f32_e32 v137, v124, v194
	v_fmac_f32_e32 v136, v125, v161
	v_fmac_f32_e32 v137, v125, v195
	v_fmac_f32_e32 v136, v126, v162
	v_fmac_f32_e32 v137, v126, v196
	v_fmac_f32_e32 v136, v127, v163
	v_fmac_f32_e32 v137, v127, v197
	v_fmac_f32_e32 v136, v128, v164
	v_fmac_f32_e32 v137, v128, v198
	v_fmac_f32_e32 v136, v129, v165
	v_fmac_f32_e32 v137, v129, v199
	v_mul_f32_e32 v112, v166, v109
	v_mul_f32_e32 v113, v167, v109
	v_add_f32_dpp v136, v136, v136 quad_perm:[1,0,3,2] row_mask:0xf bank_mask:0xf bound_ctrl:1
	v_mul_f32_e32 v114, v168, v109
	v_mul_f32_e32 v115, v169, v109
	v_add_f32_dpp v136, v136, v136 quad_perm:[2,3,0,1] row_mask:0xf bank_mask:0xf bound_ctrl:1
	v_mul_f32_e32 v116, v170, v109
	v_mul_f32_e32 v117, v171, v109
	v_add_f32_dpp v136, v136, v136 row_half_mirror row_mask:0xf bank_mask:0xf bound_ctrl:1
	v_mul_f32_e32 v118, v172, v109
	v_mul_f32_e32 v119, v173, v109
	ds_read_b128 v[158:161], v133 offset:15616
	ds_read_b128 v[162:165], v133 offset:15632
	ds_read_b128 v[166:169], v133 offset:32000
	ds_read_b128 v[170:173], v133 offset:32016
	ds_read_b128 v[176:179], v133 offset:7168
	ds_read_b128 v[180:183], v133 offset:7184
	ds_read_b128 v[184:187], v133 offset:23552
	ds_read_b128 v[188:191], v133 offset:23568
	ds_read_b128 v[192:195], v133 offset:39936
	ds_read_b128 v[196:199], v133 offset:39952
	s_waitcnt lgkmcnt(10)
; template <int CTRL> __device__ __forceinline__ float dppf(float x) { return __builtin_bit_cast(float, __builtin_amdgcn_mov_dpp(__builtin_bit_cast(int, x), CTRL, 0xf, 0xf, true)); }
; #define LDOPS(s_) do { const float* p_ = bb + (s_) * 64; w4[(s_) % 3] = *(const f32x4*)(p_); a4[(s_) % 3] = *(const f32x4*)(p_ + 2048); b4[(s_) % 3] = *(const f32x4*)(p_ + 4096); k4[(s_) % 3] = *(const f32x4*)(p_ + 6144); \
;               r4[(s_) % 3] = *(const f32x4*)(p_ + 8192); vv[(s_) % 3] = vb[(s_) * 64]; } while (0)
; __device__ __forceinline__ void scan_block(unsigned char* shm, int sid, int half) {
;     ...
;           for (int s = 0; s < TS; ++s) {
;               const f32x4 a_ = a4[s % 3], w_ = w4[s % 3], b_ = b4[s % 3], k_ = k4[s % 3], r_ = r4[s % 3];
;               const float av[4] = {a_.x, a_.y, a_.z, a_.w}, wv[4] = {w_.x, w_.y, w_.z, w_.w}, bv[4] = {b_.x, b_.y, b_.z, b_.w}, kv[4] = {k_.x, k_.y, k_.z, k_.w}, rv[4] = {r_.x, r_.y, r_.z, r_.w};
;               const float v1 = vv[s % 3];
;               if (s + 2 < TS) LDOPS(s + 2);
;               float t = S[0] * av[0]; t = fmaf(S[1], av[1], t); t = fmaf(S[2], av[2], t); t = fmaf(S[3], av[3], t);
;               t += dppf<0xB1>(t); t += dppf<0x4E>(t); t += dppf<0x141>(t); t += dppf<0x140>(t);
; #pragma unroll
;               for (int q = 0; q < 4; ++q) S[q] = fmaf(S[q], wv[q], fmaf(bv[q], t, kv[q] * v1));
;               float u = S[0] * rv[0]; u = fmaf(S[1], rv[1], u); u = fmaf(S[2], rv[2], u); u = fmaf(S[3], rv[3], u);
;               u += dppf<0xB1>(u); u += dppf<0x4E>(u); u += dppf<0x141>(u); u += dppf<0x140>(u);
;               ys[s * 32] = u;
;           }
	v_fmac_f32_e32 v112, v40, v136
	v_fmac_f32_e32 v113, v41, v136
	v_fmac_f32_e32 v114, v42, v136
	v_fmac_f32_e32 v115, v43, v136
	v_fmac_f32_e32 v116, v44, v136
	v_fmac_f32_e32 v117, v45, v136
	v_fmac_f32_e32 v118, v46, v136
	v_fmac_f32_e32 v119, v47, v136
	v_fma_f32 v122, v122, v32, v112
	v_fma_f32 v123, v123, v33, v113
	v_fma_f32 v124, v124, v34, v114
	v_fma_f32 v125, v125, v35, v115
	v_fma_f32 v126, v126, v36, v116
	v_fma_f32 v127, v127, v37, v117
	v_fma_f32 v128, v128, v38, v118
	v_fma_f32 v129, v129, v39, v119
	v_mul_f32_e32 v136, v122, v140
	v_mul_f32_e32 v138, v48, v122
	v_fmac_f32_e32 v136, v123, v141
	v_fmac_f32_e32 v138, v123, v49
	v_fmac_f32_e32 v136, v124, v142
	v_fmac_f32_e32 v138, v124, v50
	v_fmac_f32_e32 v136, v125, v143
	v_fmac_f32_e32 v138, v125, v51
	v_fmac_f32_e32 v136, v126, v144
	v_fmac_f32_e32 v138, v126, v52
	v_fmac_f32_e32 v136, v127, v145
	v_fmac_f32_e32 v138, v127, v53
	v_fmac_f32_e32 v136, v128, v146
	v_fmac_f32_e32 v138, v128, v54
	v_fmac_f32_e32 v136, v129, v147
	v_fmac_f32_e32 v138, v129, v55
	v_mul_f32_e32 v112, v148, v106
	v_mul_f32_e32 v113, v149, v106
	v_add_f32_dpp v136, v136, v136 quad_perm:[1,0,3,2] row_mask:0xf bank_mask:0xf bound_ctrl:1
	v_add_f32_dpp v139, v137, v137 row_half_mirror row_mask:0xf bank_mask:0xf bound_ctrl:1
	v_add_f32_dpp v139, v138, v138 row_half_mirror row_mask:0xf bank_mask:0xa
	v_add_f32_dpp v136, v136, v136 quad_perm:[2,3,0,1] row_mask:0xf bank_mask:0xf bound_ctrl:1
	v_mul_f32_e32 v114, v150, v106
	v_mul_f32_e32 v115, v151, v106
	v_add_f32_dpp v139, v139, v139 quad_perm:[2,3,0,1] row_mask:0xf bank_mask:0xf bound_ctrl:1
	v_add_f32_dpp v136, v136, v136 row_half_mirror row_mask:0xf bank_mask:0xf bound_ctrl:1
	v_mul_f32_e32 v116, v152, v106
	v_mul_f32_e32 v117, v153, v106
	v_add_f32_dpp v139, v139, v139 quad_perm:[1,0,3,2] row_mask:0xf bank_mask:0xf bound_ctrl:1
	v_mul_f32_e32 v118, v154, v106
	v_mul_f32_e32 v119, v155, v106
	ds_write_b32 v135, v139 offset:3328
	ds_read_b128 v[140:143], v133 offset:15872
	ds_read_b128 v[144:147], v133 offset:15888
	ds_read_b128 v[148:151], v133 offset:32256
	ds_read_b128 v[152:155], v133 offset:32272
	ds_read2st64_b32 v[108:109], v134 offset0:190 offset1:191
	ds_read_b128 v[32:35], v133 offset:7424
	ds_read_b128 v[36:39], v133 offset:7440
	ds_read_b128 v[40:43], v133 offset:23808
	ds_read_b128 v[44:47], v133 offset:23824
	ds_read_b128 v[48:51], v133 offset:40192
	ds_read_b128 v[52:55], v133 offset:40208
	s_waitcnt lgkmcnt(11)
	v_fmac_f32_e32 v112, v184, v136
	v_fmac_f32_e32 v113, v185, v136
	v_fmac_f32_e32 v114, v186, v136
	v_fmac_f32_e32 v115, v187, v136
	v_fmac_f32_e32 v116, v188, v136
	v_fmac_f32_e32 v117, v189, v136
	v_fmac_f32_e32 v118, v190, v136
	v_fmac_f32_e32 v119, v191, v136
	v_fma_f32 v122, v122, v176, v112
	v_fma_f32 v123, v123, v177, v113
	v_fma_f32 v124, v124, v178, v114
	v_fma_f32 v125, v125, v179, v115
	v_fma_f32 v126, v126, v180, v116
	v_fma_f32 v127, v127, v181, v117
	v_fma_f32 v128, v128, v182, v118
	v_fma_f32 v129, v129, v183, v119
	v_mul_f32_e32 v136, v122, v158
	v_mul_f32_e32 v137, v192, v122
	v_fmac_f32_e32 v136, v123, v159
	v_fmac_f32_e32 v137, v123, v193
	v_fmac_f32_e32 v136, v124, v160
	v_fmac_f32_e32 v137, v124, v194
	v_fmac_f32_e32 v136, v125, v161
	v_fmac_f32_e32 v137, v125, v195
	v_fmac_f32_e32 v136, v126, v162
	v_fmac_f32_e32 v137, v126, v196
	v_fmac_f32_e32 v136, v127, v163
	v_fmac_f32_e32 v137, v127, v197
	v_fmac_f32_e32 v136, v128, v164
	v_fmac_f32_e32 v137, v128, v198
	v_fmac_f32_e32 v136, v129, v165
	v_fmac_f32_e32 v137, v129, v199
	v_mul_f32_e32 v112, v166, v107
	v_mul_f32_e32 v113, v167, v107
	v_add_f32_dpp v136, v136, v136 quad_perm:[1,0,3,2] row_mask:0xf bank_mask:0xf bound_ctrl:1
	v_mul_f32_e32 v114, v168, v107
	v_mul_f32_e32 v115, v169, v107
	v_add_f32_dpp v136, v136, v136 quad_perm:[2,3,0,1] row_mask:0xf bank_mask:0xf bound_ctrl:1
	v_mul_f32_e32 v116, v170, v107
	v_mul_f32_e32 v117, v171, v107
	v_add_f32_dpp v136, v136, v136 row_half_mirror row_mask:0xf bank_mask:0xf bound_ctrl:1
	v_mul_f32_e32 v118, v172, v107
	v_mul_f32_e32 v119, v173, v107
	ds_read_b128 v[158:161], v133 offset:16128
	ds_read_b128 v[162:165], v133 offset:16144
	ds_read_b128 v[166:169], v133 offset:32512
	ds_read_b128 v[170:173], v133 offset:32528
	ds_read_b128 v[176:179], v133 offset:7680
	ds_read_b128 v[180:183], v133 offset:7696
	ds_read_b128 v[184:187], v133 offset:24064
	ds_read_b128 v[188:191], v133 offset:24080
	ds_read_b128 v[192:195], v133 offset:40448
	ds_read_b128 v[196:199], v133 offset:40464
	s_waitcnt lgkmcnt(10)
; template <int CTRL> __device__ __forceinline__ float dppf(float x) { return __builtin_bit_cast(float, __builtin_amdgcn_mov_dpp(__builtin_bit_cast(int, x), CTRL, 0xf, 0xf, true)); }
; #define LDOPS(s_) do { const float* p_ = bb + (s_) * 64; w4[(s_) % 3] = *(const f32x4*)(p_); a4[(s_) % 3] = *(const f32x4*)(p_ + 2048); b4[(s_) % 3] = *(const f32x4*)(p_ + 4096); k4[(s_) % 3] = *(const f32x4*)(p_ + 6144); \
;               r4[(s_) % 3] = *(const f32x4*)(p_ + 8192); vv[(s_) % 3] = vb[(s_) * 64]; } while (0)
; #define c opq(blockIdx.x)
; __device__ __forceinline__ void transpose_item(const float* W, int K, int N, bf16_t* WT, float* scr, int item, int lane) {
;     const int nblk = N / 32, kb = item / nblk, nb = item % nblk, k0 = 64 * kb, n0 = 32 * nb;
;     const int r = lane >> 3, c4 = lane & 7;
;     f32x4 v[8];
; #pragma unroll
;     for (int i = 0; i < 8; ++i) v[i] = __builtin_nontemporal_load((const f32x4*)(W + (size_t)(k0 + 8 * i + r) * N + n0 + 4 * c4));
; __device__ __forceinline__ void scan_block(unsigned char* shm, int sid, int half) {
;     ...
;         { const float* bb = bufs + (c & 1) * 12288 + 4 * g; float* ys = yst + (c & 1) * 1024 + rowl; const float* vb = bufs + (c & 1) * 12288 + 5 * 2048 + half * 32 + rowl;
;           f32x4 w4[3], a4[3], b4[3], k4[3], r4[3]; float vv[3];
;     ...
;           LDOPS(0); LDOPS(1);
; #pragma unroll
;           for (int s = 0; s < TS; ++s) {
;               const f32x4 a_ = a4[s % 3], w_ = w4[s % 3], b_ = b4[s % 3], k_ = k4[s % 3], r_ = r4[s % 3];
;               const float av[4] = {a_.x, a_.y, a_.z, a_.w}, wv[4] = {w_.x, w_.y, w_.z, w_.w}, bv[4] = {b_.x, b_.y, b_.z, b_.w}, kv[4] = {k_.x, k_.y, k_.z, k_.w}, rv[4] = {r_.x, r_.y, r_.z, r_.w};
;               const float v1 = vv[s % 3];
;               if (s + 2 < TS) LDOPS(s + 2);
;               float t = S[0] * av[0]; t = fmaf(S[1], av[1], t); t = fmaf(S[2], av[2], t); t = fmaf(S[3], av[3], t);
;               t += dppf<0xB1>(t); t += dppf<0x4E>(t); t += dppf<0x141>(t); t += dppf<0x140>(t);
; #pragma unroll
;               for (int q = 0; q < 4; ++q) S[q] = fmaf(S[q], wv[q], fmaf(bv[q], t, kv[q] * v1));
;               float u = S[0] * rv[0]; u = fmaf(S[1], rv[1], u); u = fmaf(S[2], rv[2], u); u = fmaf(S[3], rv[3], u);
;               u += dppf<0xB1>(u); u += dppf<0x4E>(u); u += dppf<0x141>(u); u += dppf<0x140>(u);
;               ys[s * 32] = u;
;           }
	v_fmac_f32_e32 v112, v40, v136
	v_fmac_f32_e32 v113, v41, v136
	v_fmac_f32_e32 v114, v42, v136
	v_fmac_f32_e32 v115, v43, v136
	v_fmac_f32_e32 v116, v44, v136
	v_fmac_f32_e32 v117, v45, v136
	v_fmac_f32_e32 v118, v46, v136
	v_fmac_f32_e32 v119, v47, v136
	v_fma_f32 v122, v122, v32, v112
	v_fma_f32 v123, v123, v33, v113
	v_fma_f32 v124, v124, v34, v114
	v_fma_f32 v125, v125, v35, v115
	v_fma_f32 v126, v126, v36, v116
	v_fma_f32 v127, v127, v37, v117
	v_fma_f32 v128, v128, v38, v118
	v_fma_f32 v129, v129, v39, v119
	v_mul_f32_e32 v136, v122, v140
	v_mul_f32_e32 v138, v48, v122
	v_fmac_f32_e32 v136, v123, v141
	v_fmac_f32_e32 v138, v123, v49
	v_fmac_f32_e32 v136, v124, v142
	v_fmac_f32_e32 v138, v124, v50
	v_fmac_f32_e32 v136, v125, v143
	v_fmac_f32_e32 v138, v125, v51
	v_fmac_f32_e32 v136, v126, v144
	v_fmac_f32_e32 v138, v126, v52
	v_fmac_f32_e32 v136, v127, v145
	v_fmac_f32_e32 v138, v127, v53
	v_fmac_f32_e32 v136, v128, v146
	v_fmac_f32_e32 v138, v128, v54
	v_fmac_f32_e32 v136, v129, v147
	v_fmac_f32_e32 v138, v129, v55
	v_mul_f32_e32 v112, v148, v108
	v_mul_f32_e32 v113, v149, v108
	v_add_f32_dpp v136, v136, v136 quad_perm:[1,0,3,2] row_mask:0xf bank_mask:0xf bound_ctrl:1
	v_add_f32_dpp v139, v137, v137 row_half_mirror row_mask:0xf bank_mask:0xf bound_ctrl:1
	v_add_f32_dpp v139, v138, v138 row_half_mirror row_mask:0xf bank_mask:0xa
	v_add_f32_dpp v136, v136, v136 quad_perm:[2,3,0,1] row_mask:0xf bank_mask:0xf bound_ctrl:1
	v_mul_f32_e32 v114, v150, v108
	v_mul_f32_e32 v115, v151, v108
	v_add_f32_dpp v139, v139, v139 quad_perm:[2,3,0,1] row_mask:0xf bank_mask:0xf bound_ctrl:1
	v_add_f32_dpp v136, v136, v136 row_half_mirror row_mask:0xf bank_mask:0xf bound_ctrl:1
	v_mul_f32_e32 v116, v152, v108
	v_mul_f32_e32 v117, v153, v108
	v_add_f32_dpp v139, v139, v139 quad_perm:[1,0,3,2] row_mask:0xf bank_mask:0xf bound_ctrl:1
	v_mul_f32_e32 v118, v154, v108
	v_mul_f32_e32 v119, v155, v108
	ds_write_b32 v135, v139 offset:3584
	ds_read_b128 v[32:35], v133 offset:7936
	ds_read_b128 v[36:39], v133 offset:7952
	ds_read_b128 v[40:43], v133 offset:24320
	ds_read_b128 v[44:47], v133 offset:24336
	ds_read_b128 v[48:51], v133 offset:40704
	ds_read_b128 v[52:55], v133 offset:40720
	s_waitcnt lgkmcnt(6)
	v_fmac_f32_e32 v112, v184, v136
	v_fmac_f32_e32 v113, v185, v136
	v_fmac_f32_e32 v114, v186, v136
	v_fmac_f32_e32 v115, v187, v136
	v_fmac_f32_e32 v116, v188, v136
	v_fmac_f32_e32 v117, v189, v136
	v_fmac_f32_e32 v118, v190, v136
	v_fmac_f32_e32 v119, v191, v136
	v_fma_f32 v122, v122, v176, v112
	v_fma_f32 v123, v123, v177, v113
	v_fma_f32 v124, v124, v178, v114
	v_fma_f32 v125, v125, v179, v115
	v_fma_f32 v126, v126, v180, v116
	v_fma_f32 v127, v127, v181, v117
	v_fma_f32 v128, v128, v182, v118
	v_fma_f32 v129, v129, v183, v119
	v_mul_f32_e32 v136, v122, v158
	v_mul_f32_e32 v137, v192, v122
	v_fmac_f32_e32 v136, v123, v159
	v_fmac_f32_e32 v137, v123, v193
	v_fmac_f32_e32 v136, v124, v160
	v_fmac_f32_e32 v137, v124, v194
	v_fmac_f32_e32 v136, v125, v161
	v_fmac_f32_e32 v137, v125, v195
	v_fmac_f32_e32 v136, v126, v162
	v_fmac_f32_e32 v137, v126, v196
	v_fmac_f32_e32 v136, v127, v163
	v_fmac_f32_e32 v137, v127, v197
	v_fmac_f32_e32 v136, v128, v164
	v_fmac_f32_e32 v137, v128, v198
	v_fmac_f32_e32 v136, v129, v165
	v_fmac_f32_e32 v137, v129, v199
	v_mul_f32_e32 v112, v166, v109
	v_mul_f32_e32 v113, v167, v109
	v_add_f32_dpp v136, v136, v136 quad_perm:[1,0,3,2] row_mask:0xf bank_mask:0xf bound_ctrl:1
	v_mul_f32_e32 v114, v168, v109
	v_mul_f32_e32 v115, v169, v109
	v_add_f32_dpp v136, v136, v136 quad_perm:[2,3,0,1] row_mask:0xf bank_mask:0xf bound_ctrl:1
	v_mul_f32_e32 v116, v170, v109
	v_mul_f32_e32 v117, v171, v109
	v_add_f32_dpp v136, v136, v136 row_half_mirror row_mask:0xf bank_mask:0xf bound_ctrl:1
	v_mul_f32_e32 v118, v172, v109
	v_mul_f32_e32 v119, v173, v109
	s_waitcnt lgkmcnt(0)
	v_fmac_f32_e32 v112, v40, v136
	v_fmac_f32_e32 v113, v41, v136
	v_fmac_f32_e32 v114, v42, v136
	v_fmac_f32_e32 v115, v43, v136
	v_fmac_f32_e32 v116, v44, v136
	v_fmac_f32_e32 v117, v45, v136
	v_fmac_f32_e32 v118, v46, v136
	v_fmac_f32_e32 v119, v47, v136
	v_fma_f32 v122, v122, v32, v112
	v_fma_f32 v123, v123, v33, v113
	v_fma_f32 v124, v124, v34, v114
	v_fma_f32 v125, v125, v35, v115
	v_fma_f32 v126, v126, v36, v116
	v_fma_f32 v127, v127, v37, v117
	v_fma_f32 v128, v128, v38, v118
	v_fma_f32 v129, v129, v39, v119
	v_mul_f32_e32 v138, v48, v122
	v_fmac_f32_e32 v138, v123, v49
	v_fmac_f32_e32 v138, v124, v50
	v_fmac_f32_e32 v138, v125, v51
	v_fmac_f32_e32 v138, v126, v52
	v_fmac_f32_e32 v138, v127, v53
	v_fmac_f32_e32 v138, v128, v54
	v_fmac_f32_e32 v138, v129, v55
	v_add_f32_dpp v139, v137, v137 row_half_mirror row_mask:0xf bank_mask:0xf bound_ctrl:1
	s_nop 0
	v_add_f32_dpp v139, v138, v138 row_half_mirror row_mask:0xf bank_mask:0xa
	s_nop 1
	v_add_f32_dpp v139, v139, v139 quad_perm:[2,3,0,1] row_mask:0xf bank_mask:0xf bound_ctrl:1
	s_nop 1
	v_add_f32_dpp v139, v139, v139 quad_perm:[1,0,3,2] row_mask:0xf bank_mask:0xf bound_ctrl:1
	ds_write_b32 v135, v139 offset:3840
	s_branch .Lscan_idle
.Ltr_loads:
	s_cmp_lg_u32 s45, 0
	s_cbranch_scc0 .Lscan_idle
	s_cmp_gt_i32 s16, 0xfffff000
	s_cbranch_scc0 .Lscan_idle
	global_load_dword v106, v[210:211], off
	global_load_dword v114, v[210:211], off offset:32
	v_lshl_add_u64 v[210:211], v[210:211], 0, s[54:55]
	global_load_dword v107, v[210:211], off
	global_load_dword v115, v[210:211], off offset:32
	v_lshl_add_u64 v[210:211], v[210:211], 0, s[54:55]
	global_load_dword v108, v[210:211], off
	global_load_dword v116, v[210:211], off offset:32
	v_lshl_add_u64 v[210:211], v[210:211], 0, s[54:55]
	global_load_dword v109, v[210:211], off
	global_load_dword v117, v[210:211], off offset:32
	v_lshl_add_u64 v[210:211], v[210:211], 0, s[54:55]
	global_load_dword v110, v[210:211], off
	global_load_dword v118, v[210:211], off offset:32
	v_lshl_add_u64 v[210:211], v[210:211], 0, s[54:55]
	global_load_dword v111, v[210:211], off
	global_load_dword v119, v[210:211], off offset:32
	v_lshl_add_u64 v[210:211], v[210:211], 0, s[54:55]
	global_load_dword v112, v[210:211], off
	global_load_dword v120, v[210:211], off offset:32
	v_lshl_add_u64 v[210:211], v[210:211], 0, s[54:55]
	global_load_dword v113, v[210:211], off
	global_load_dword v121, v[210:211], off offset:32
	v_lshl_add_u64 v[210:211], v[210:211], 0, s[58:59]

; __device__ __forceinline__ unsigned pk2(float lo, float hi) { return f2bf(lo) | (f2bf(hi) << 16); }
; #define c opq(blockIdx.x)
; __device__ __forceinline__ void transpose_item(const float* W, int K, int N, bf16_t* WT, float* scr, int item, int lane) {
;     ...
;     const int c = lane & 7;
; #pragma unroll
;     for (int j = 0; j < 4; ++j) { const int n = (lane >> 3) + 8 * j; const float* s = scr + (8 * c) * 33 + n;
;         u32x4 o; o.x = pk2(s[0 * 33], s[1 * 33]); o.y = pk2(s[2 * 33], s[3 * 33]); o.z = pk2(s[4 * 33], s[5 * 33]); o.w = pk2(s[6 * 33], s[7 * 33]);
;         *(u32x4*)(WT + (size_t)(n0 + n) * K + k0 + 8 * c) = o; }
; __device__ __forceinline__ void scan_block(unsigned char* shm, int sid, int half) {
;     ...
;         { const f32x2 yv = *(const f32x2*)(yst + (c & 1) * 1024 + ss * 32 + 2 * part); const int row_ = SCAN_ROW(c * TS + ss);
;           *(unsigned*)(Y + (size_t)row_ * 1024 + h * 64 + half * 32 + 2 * part) = pk2(yv.x, yv.y); }
.LBB0_796:
	v_add3_u32 v4, s8, v98, v101
	s_waitcnt lgkmcnt(0)
	s_barrier
	s_cmp_lg_u32 s45, 0
	s_cbranch_scc0 .Ltr_nostore
	s_cmp_gt_i32 s16, 0xfffff000
	s_cbranch_scc0 .Ltr_nostore
	s_waitcnt vmcnt(0)
	v_cvt_pk_bf16_f32 v140, v106, v107
	v_cvt_pk_bf16_f32 v141, v108, v109
	v_cvt_pk_bf16_f32 v142, v110, v111
	v_cvt_pk_bf16_f32 v143, v112, v113
	v_cvt_pk_bf16_f32 v144, v114, v115
	v_cvt_pk_bf16_f32 v145, v116, v117
	v_cvt_pk_bf16_f32 v146, v118, v119
	v_cvt_pk_bf16_f32 v147, v120, v121
	global_store_dwordx4 v[212:213], v[140:143], off
	v_lshl_add_u64 v[212:213], v[212:213], 0, s[56:57]
	global_store_dwordx4 v[212:213], v[144:147], off
	v_lshl_add_u64 v[212:213], v[212:213], 0, s[56:57]
.Ltr_nostore:
	ds_read_b64 v[4:5], v4
	v_cmp_lt_i32_e32 vcc, s0, v95
	v_add_u32_e32 v7, s16, v99
	s_and_saveexec_b64 s[8:9], vcc
	s_xor_b64 s[8:9], exec, s[8:9]
	v_add_u32_e32 v6, 0x10ff, v7
	v_add_u32_e32 v7, 0xffffff00, v95
	v_cndmask_b32_e64 v6, v6, v7, s[38:39]
	v_add_u32_e32 v6, v6, v94
	s_andn2_saveexec_b64 s[8:9], s[8:9]
	s_cbranch_execz .LBB0_787
	v_add_u32_e32 v6, 0xff, v7
	v_cndmask_b32_e64 v6, v6, v95, s[38:39]
	v_add_u32_e32 v6, v6, v67
	s_branch .LBB0_787

; template<int THRL> __device__ __forceinline__ void attn_unit_p(const bf16*Qu,int QP,const bf16*__restrict__ Kh,const bf16*__restrict__ Vh,int KP,int NT,bf16*Ou,int OP,char*shm){
;   const int tid=tidx(),lane=tid&63,r32=lane&31,hi=lane>>5; const int wid=__builtin_amdgcn_readfirstlane(tid>>6);
;   const bf16*Qw=Qu+(long)(wid*QBLK)*QP;
;   const unsigned lds0=(unsigned)(uintptr_t)shm;
;   float*wsf=(float*)(shm+LDS_WS)+wid*64;
;   const bf16*ksrc=Kh+(long)lane*KP+wid*8;
;   const bf16*vsrc=Vh+(long)(16*(wid&3)+(lane>>2))*KP+(wid>>2)*32+(lane&3)*8;
;   const unsigned kdst=lds0+LDS_K+wid*1024, vdst=lds0+LDS_V+wid*1024;
;     ...
;   const int vb0=(int)(lds0+LDS_V)+((lane>>4)&1)*32+(lane&3)*8+(4*hi+((lane&15)>>2))*64;
;   const char*Kbase=shm+LDS_K; bf16x8 kf[8];
; __device__ __forceinline__ void phase_mix0(unsigned char* shm, int ctrw) {
;     ...
;     for (;;) {
;         if (tidx() == 0) *(volatile unsigned*)(shm + AT_Q) = atomicAdd(ctr, 1u);
;         __syncthreads();
;         const unsigned u = *(volatile unsigned*)(shm + AT_Q);
;         __syncthreads();
;         if (u >= 1088u + (unsigned)(TQ_ITEMS / 64)) break;
;         if (u >= 1088u) { const int base = (int)(u - 1088u) * 64; float* scr = (float*)(shm + wid * 8448); const int lane = tidx() & 63;
;             for (int e = 0; e < 8; ++e) transpose_deferred(base + e * 8 + wid, scr, lane);
;             __syncthreads(); continue; }
;         if (u < 1024u) { const int b = u >> 8, hq = (u >> 4) & 15, qb = u & 15, kvh = hq >> 2; const size_t qrow = (size_t)b * SEQ + qb * 256 + wid * 32;
;             att::attn_unit_p<8>((const att::bf16*)(Q0 + (qrow - wid * 32) * 1024 + hq * 64), 1024, (const att::bf16*)(KALL + (size_t)(b * 4 + kvh) * KVLEN * 64), (const att::bf16*)(VALL + (size_t)(b * 4 + kvh) * KVLEN * 64), 64, KVLEN / 64, (att::bf16*)(OC + (qrow - wid * 32) * 2048 + hq * 64), 2048, (char*)shm); }
;         else { const int cu = u - 1024, b = cu >> 4, hq = cu & 15, kvh = hq >> 2; const size_t qrow = (size_t)NLAT + b * CTX + wid * 32;
;             att::attn_unit_p<8>((const att::bf16*)(Q0 + (qrow - wid * 32) * 1024 + hq * 64), 1024, (const att::bf16*)(KALL + ((size_t)(b * 4 + kvh) * KVLEN + SEQ) * 64), (const att::bf16*)(VALL + ((size_t)(b * 4 + kvh) * KVLEN + SEQ) * 64), 64, CTX / 64, (att::bf16*)(OC + (qrow - wid * 32) * 2048 + hq * 64), 2048, (char*)shm); }
.LBB0_808:
	s_or_b64 exec, exec, s[2:3]
	s_cmp_lg_u32 s20, -1
	s_cselect_b32 s0, s20, 0
	s_cselect_b32 s1, s41, 0
	v_mov_b32_e32 v0, s0
	v_mov_b32_e32 v1, s1
	s_waitcnt lgkmcnt(0)
	s_barrier
	flat_load_dword v0, v[0:1] sc0 sc1
	s_waitcnt vmcnt(0)
	s_movk_i32 s0, 0x6e0
	s_cmpk_eq_i32 s76, 0x100
	s_cselect_b32 s0, 0x440, s0
	s_mov_b64 s[2:3], -1
	s_waitcnt lgkmcnt(0)
	s_barrier
	v_cmp_gt_u32_e32 vcc, s0, v0
	s_and_saveexec_b64 s[68:69], vcc
	s_cbranch_execz .LBB0_803
	s_movk_i32 s0, 0x440
	v_cmp_gt_u32_e32 vcc, s0, v0
	s_and_saveexec_b64 s[0:1], vcc
	s_xor_b64 s[2:3], exec, s[0:1]
	s_cbranch_execz .LBB0_858
	s_movk_i32 s0, 0x3ff
	v_cmp_lt_u32_e32 vcc, s0, v0
	s_and_saveexec_b64 s[0:1], vcc
	s_xor_b64 s[4:5], exec, s[0:1]
	s_cbranch_execz .LBB0_823
	v_add_u32_e32 v1, 0xfffffc00, v0
	v_lshrrev_b32_e32 v4, 4, v1
	v_lshl_add_u32 v188, v4, 8, v200
	v_and_b32_e32 v186, 15, v0
	v_bfe_u32 v5, v0, 2, 2
	v_lshlrev_b64 v[0:1], 11, v[188:189]
	v_lshl_add_u64 v[0:1], s[44:45], 0, v[0:1]
	v_lshlrev_b32_e32 v2, 7, v186
	v_mov_b32_e32 v3, v189
	v_lshl_add_u64 v[0:1], v[0:1], 0, v[2:3]
	v_lshl_or_b32 v2, v4, 2, v5
	s_mov_b32 s0, 0x88000
	v_mad_u64_u32 v[2:3], s[0:1], v2, s0, v[190:191]
	v_mov_b32_e32 v42, v219
	v_lshl_add_u64 v[4:5], s[46:47], 0, v[2:3]
	v_readfirstlane_b32 s1, v42
	s_ashr_i32 s0, s1, 6
	s_lshl_b32 s12, s0, 5
	v_and_b32_e32 v182, 63, v42
	s_ashr_i32 s13, s12, 31
	s_lshl_b64 s[6:7], s[12:13], 11
	v_lshlrev_b32_e32 v6, 7, v182
	v_mov_b32_e32 v7, v189
	s_lshl_b32 s8, s0, 3
	v_lshl_add_u64 v[0:1], v[0:1], 0, s[6:7]
	s_and_b32 s6, s1, 0x3fffffc0
	v_lshl_add_u64 v[4:5], v[4:5], 0, v[6:7]
	s_ashr_i32 s9, s8, 31
	s_ashr_i32 s1, s1, 3
	v_lshl_add_u64 v[32:33], s[8:9], 1, v[4:5]
	s_lshl_b32 s7, s0, 4
	v_bfe_u32 v4, v42, 2, 4
	s_and_b32 s8, s1, 0xffffffe0
	v_and_or_b32 v4, s7, 48, v4
	s_ashr_i32 s9, s8, 31
	s_lshl_b32 s1, s0, 10
	v_lshl_add_u64 v[2:3], s[48:49], 0, v[2:3]
	v_lshlrev_b32_e32 v4, 7, v4
	v_mov_b32_e32 v5, v189
	v_lshlrev_b32_e32 v183, 3, v42
	s_cmp_lg_u32 0, -1
	v_lshl_add_u64 v[2:3], v[2:3], 0, v[4:5]
	v_and_b32_e32 v187, 24, v183
	s_cselect_b32 s7, 0, 0
	v_lshl_add_u64 v[2:3], s[8:9], 1, v[2:3]
	v_lshlrev_b32_e32 v4, 1, v187
	s_add_i32 s7, s7, s1
	s_mov_b32 s8, m0
	s_mov_b32 m0, s7
	s_nop 0
	global_load_lds_dwordx4 v[32:33], off
	s_mov_b32 m0, s8
	v_and_b32_e32 v184, 31, v42
	v_lshl_add_u64 v[180:181], v[2:3], 0, v[4:5]
	s_add_i32 s1, s7, 0x6000
	s_mov_b32 s8, m0
	s_mov_b32 m0, s1
	s_nop 0
	global_load_lds_dwordx4 v[180:181], off
	s_mov_b32 m0, s8
	v_lshl_add_u64 v[2:3], v[32:33], 0, s[54:55]
	v_bfe_u32 v185, v42, 5, 1
	s_add_i32 s8, s7, 0x2000
	s_mov_b32 s9, m0
	s_mov_b32 m0, s8
	s_nop 0
	global_load_lds_dwordx4 v[2:3], off
	s_mov_b32 m0, s9
	v_lshlrev_b32_e32 v2, 11, v184
	v_lshl_or_b32 v2, v185, 4, v2
	v_mov_b32_e32 v3, v189
	v_lshl_add_u64 v[0:1], v[0:1], 0, v[2:3]
	global_load_dwordx4 v[140:143], v[0:1], off
	global_load_dwordx4 v[136:139], v[0:1], off offset:32
	global_load_dwordx4 v[128:131], v[0:1], off offset:64
	global_load_dwordx4 v[112:115], v[0:1], off offset:96
	v_lshlrev_b32_e32 v2, 4, v184
	v_lshl_add_u32 v0, v185, 10, 0
	v_add_u32_e32 v202, v0, v2
	v_mov_b32_e32 v0, v189
	v_mov_b32_e32 v1, v189
	v_mov_b32_e32 v2, v189
	v_mov_b32_e32 v4, v189
	v_mov_b32_e32 v6, v189
	v_mov_b32_e32 v8, v189
	v_mov_b32_e32 v9, v189
	v_mov_b32_e32 v10, v189
	v_mov_b32_e32 v11, v189
	v_mov_b32_e32 v12, v189
	v_mov_b32_e32 v13, v189
	v_mov_b32_e32 v14, v189
	v_mov_b32_e32 v15, v189
	v_lshl_add_u64 v[16:17], v[32:33], 0, s[56:57]
	s_add_i32 s8, s7, 0x4000
	s_mov_b32 s9, m0
	s_mov_b32 m0, s8
	s_nop 0
	global_load_lds_dwordx4 v[16:17], off
	s_mov_b32 m0, s9
	s_waitcnt vmcnt(3) lgkmcnt(0)
	s_barrier
	ds_read_b128 v[34:37], v202
	ds_read_b128 v[38:41], v202 offset:512
	s_lshl_b32 s6, s6, 2
	s_add_i32 s6, s6, 0
	v_cmp_gt_u32_e64 s[38:39], 32, v182
	v_lshl_add_u32 v195, v184, 2, s6
	s_waitcnt vmcnt(3) lgkmcnt(1)
	v_mfma_f32_32x32x16_bf16 v[16:31], v[34:37], v[140:143], v[0:15]
	s_waitcnt lgkmcnt(0)
	v_mfma_f32_32x32x16_bf16 v[0:15], v[38:41], v[140:143], v[0:15]
	ds_read_b128 v[34:37], v202 offset:2048
	ds_read_b128 v[38:41], v202 offset:2560
	s_waitcnt vmcnt(2) lgkmcnt(1)
	v_mfma_f32_32x32x16_bf16 v[16:31], v[34:37], v[136:139], v[16:31]
	s_waitcnt lgkmcnt(0)
	v_mfma_f32_32x32x16_bf16 v[0:15], v[38:41], v[136:139], v[0:15]
	ds_read_b128 v[34:37], v202 offset:4096
	ds_read_b128 v[38:41], v202 offset:4608
	s_waitcnt vmcnt(1) lgkmcnt(1)
	v_mfma_f32_32x32x16_bf16 v[16:31], v[34:37], v[128:131], v[16:31]
	s_waitcnt lgkmcnt(0)
	v_mfma_f32_32x32x16_bf16 v[0:15], v[38:41], v[128:131], v[0:15]
	ds_read_b128 v[34:37], v202 offset:6144
	ds_read_b128 v[38:41], v202 offset:6656
	s_waitcnt vmcnt(0) lgkmcnt(1)
	v_mfma_f32_32x32x16_bf16 v[16:31], v[34:37], v[112:115], v[16:31]
	v_lshlrev_b32_e32 v34, 1, v42
	v_lshlrev_b32_e32 v35, 4, v42
	v_and_b32_e32 v192, 32, v34
	v_and_b32_e32 v34, 0xc0, v35
	v_lshl_or_b32 v194, v185, 8, v34
	v_add3_u32 v34, 0, v192, v187
	v_add_u32_e32 v201, v34, v194
	s_waitcnt lgkmcnt(0)
; #define WAIT_BAR(N) asm volatile("s_waitcnt vmcnt(" #N ") lgkmcnt(0)\n\ts_barrier":::"memory")
;   #define DMA_K(t,slot) glds16(ksrc+(long)(t)*KVBLK*KP,(unsigned)__builtin_amdgcn_readfirstlane(kdst+(slot)))
;   #define DMA_V(t,slot) glds16(vsrc+(long)(t)*KVBLK*KP,(unsigned)__builtin_amdgcn_readfirstlane(vdst+(slot)))
;   #define CMASK(P0,P1,t) do{}while(0)
;   #define START(P0,P1) do{ const float rm=rowmax(P0,P1); resc=false; \
;     { const float dl=rm; mhat=fadd_s(mhat,dl); \
;       _Pragma("unroll") for(int r=0;r<16;++r){P0[r]=fsub_s(P0[r],dl);P1[r]=fsub_s(P1[r],dl);} \
;       _Pragma("unroll") for(int r=0;r<16;++r)negm[r]=-mhat; asm volatile("":"+v"(negm)); } \
;     _Pragma("unroll") for(int r=0;r<16;++r)P0[r]=__builtin_amdgcn_exp2f(P0[r]); }while(0)
;   #define ROT() do{sl_prev=sl_cur;sl_cur=sl_next;sl_next=(sl_next==(NSLOT-1)*SLOTB)?0:sl_next+SLOTB;}while(0)
;   #define CMASK(P0,P1,t) do{}while(0)
;   #define CMASK(P0,P1,t) do{}while(0)
;   #define DMA_K(t,slot) glds16(ksrc+NA_TOFF(t)*KP,(unsigned)__builtin_amdgcn_readfirstlane(kdst+(slot)))
;   #define DMA_V(t,slot) glds16(vsrc+NA_TOFF(t)*KP,(unsigned)__builtin_amdgcn_readfirstlane(vdst+(slot)))
;   #define CMASK(P0,P1,t) NA_MASK(P0,P1,t)
;   #define START(P0,P1) do{ const float rm=rowmax(P0,P1); resc=false; \
;     { const float dl=rm; mhat=fadd_s(mhat,dl); \
;       _Pragma("unroll") for(int r=0;r<16;++r){P0[r]=fsub_s(P0[r],dl);P1[r]=fsub_s(P1[r],dl);} \
;       } \
;     _Pragma("unroll") for(int r=0;r<16;++r)P0[r]=__builtin_amdgcn_exp2f(P0[r]); }while(0)
;   #define ROT() do{sl_prev=sl_cur;sl_cur=sl_next;sl_next=(sl_next==(NSLOT-1)*SLOTB)?0:sl_next+SLOTB;}while(0)
;   #define CMASK(P0,P1,t) NA_MASK(P0,P1,t)
;   #define CMASK(P0,P1,t) NA_MASK(P0,P1,t)
; template<int THRL> __device__ __forceinline__ void attn_unit_p(const bf16*Qu,int QP,const bf16*__restrict__ Kh,const bf16*__restrict__ Vh,int KP,int NT,bf16*Ou,int OP,char*shm){
;     ...
;   f32x16 pA0,pA1,pB0,pB1;
;   int sl_prev=0,sl_cur=0,sl_next=SLOTB;
;     ...
;   DMA_K(2,2*SLOTB);
;   WAIT_BAR(3);
;   qkt(pA0,pA1,Kbase,qr,negm,r32,hi);asm volatile("s_nop 15\n\ts_nop 7":"+v"(pA0),"+v"(pA1));CMASK(pA0,pA1,0);
;   START(pA0,pA1);
;   _Pragma("unroll") for(int r=0;r<16;++r)pA1[r]=__builtin_amdgcn_exp2f(pA1[r]);
;   WAIT_BAR(0);
;   DMA_K(3,0);DMA_V(1,SLOTB);
;   ROT();
;   kload8(kf,kp0+sl_cur);
;   WAIT_BAR(2);
	v_mfma_f32_32x32x16_bf16 v[0:15], v[38:41], v[112:115], v[0:15]
	s_nop 15
	s_nop 7
	s_nop 0
	v_max3_f32 v35, v16, v17, v0
	v_max3_f32 v36, v18, v19, v1
	s_nop 0
	v_max3_f32 v35, v35, v2, v3
	v_max3_f32 v36, v36, v22, v23
	s_nop 0
	v_max3_f32 v35, v35, v20, v21
	v_max3_f32 v36, v36, v6, v7
	s_nop 0
	v_max3_f32 v35, v35, v4, v5
	v_max3_f32 v36, v36, v26, v27
	s_nop 0
	v_max3_f32 v35, v35, v24, v25
	v_max3_f32 v36, v36, v10, v11
	s_nop 0
	v_max3_f32 v35, v35, v8, v9
	v_max3_f32 v36, v36, v30, v31
	s_nop 0
	v_max3_f32 v35, v35, v28, v29
	v_max3_f32 v36, v36, v14, v15
	s_nop 0
	v_max3_f32 v35, v35, v12, v13
	s_nop 0
	v_max_f32_e32 v35, v35, v36
	s_nop 0
	v_mov_b32_e32 v36, v35
	s_nop 1
	v_permlane32_swap_b32_e32 v35, v36
	v_max_f32_e32 v35, v35, v36
	s_nop 0
	v_add_f32_e32 v196, v189, v35
	v_sub_f32_e32 v36, v0, v35
	v_sub_f32_e32 v16, v16, v35
	v_sub_f32_e32 v17, v17, v35
	v_sub_f32_e32 v37, v1, v35
	v_sub_f32_e32 v18, v18, v35
	s_nop 0
	v_xor_b32_e32 v0, 0x80000000, v196
	v_sub_f32_e32 v38, v2, v35
	v_sub_f32_e32 v19, v19, v35
	v_sub_f32_e32 v39, v3, v35
	v_sub_f32_e32 v20, v20, v35
	v_sub_f32_e32 v40, v4, v35
	v_sub_f32_e32 v21, v21, v35
	v_sub_f32_e32 v41, v5, v35
	v_sub_f32_e32 v22, v22, v35
	v_sub_f32_e32 v42, v6, v35
	v_sub_f32_e32 v23, v23, v35
	v_sub_f32_e32 v43, v7, v35
	v_sub_f32_e32 v24, v24, v35
	v_sub_f32_e32 v44, v8, v35
	v_sub_f32_e32 v25, v25, v35
	v_sub_f32_e32 v45, v9, v35
	v_sub_f32_e32 v26, v26, v35
	v_sub_f32_e32 v46, v10, v35
	v_sub_f32_e32 v27, v27, v35
	v_sub_f32_e32 v47, v11, v35
	v_sub_f32_e32 v28, v28, v35
	v_sub_f32_e32 v48, v12, v35
	v_sub_f32_e32 v29, v29, v35
	v_sub_f32_e32 v49, v13, v35
	v_sub_f32_e32 v30, v30, v35
	v_sub_f32_e32 v50, v14, v35
	v_sub_f32_e32 v31, v31, v35
	v_sub_f32_e32 v35, v15, v35
	v_mov_b32_e32 v1, v0
	v_mov_b32_e32 v2, v0
	v_mov_b32_e32 v3, v0
	v_mov_b32_e32 v4, v0
	v_mov_b32_e32 v5, v0
	v_mov_b32_e32 v6, v0
	v_mov_b32_e32 v7, v0
	v_mov_b32_e32 v8, v0
	v_mov_b32_e32 v9, v0
	v_mov_b32_e32 v10, v0
	v_mov_b32_e32 v11, v0
	v_mov_b32_e32 v12, v0
	v_mov_b32_e32 v13, v0
	v_mov_b32_e32 v14, v0
	v_mov_b32_e32 v15, v0
	s_waitcnt vmcnt(0) lgkmcnt(0)
	s_barrier
	v_exp_f32_e32 v51, v16
	v_exp_f32_e32 v52, v17
	v_lshl_add_u64 v[16:17], v[32:33], 0, s[58:59]
	s_mov_b32 s8, m0
	s_mov_b32 m0, s7
	s_nop 0
	global_load_lds_dwordx4 v[16:17], off
	s_mov_b32 m0, s8
	v_lshl_add_u64 v[16:17], v[180:181], 0, s[54:55]
	s_add_i32 s8, s7, 0x8000
	s_mov_b32 s9, m0
	s_mov_b32 m0, s8
	s_nop 0
	global_load_lds_dwordx4 v[16:17], off
	s_mov_b32 m0, s9
	v_exp_f32_e32 v55, v20
	v_exp_f32_e32 v56, v21
	v_exp_f32_e32 v57, v22
	v_exp_f32_e32 v58, v23
	v_exp_f32_e32 v59, v24
	v_exp_f32_e32 v60, v25
	v_exp_f32_e32 v61, v26
	v_exp_f32_e32 v62, v27
	v_exp_f32_e32 v63, v28
	v_exp_f32_e32 v80, v29
	v_exp_f32_e32 v81, v30
	v_exp_f32_e32 v82, v31
	v_exp_f32_e32 v83, v36
	v_exp_f32_e32 v92, v37
	v_exp_f32_e32 v93, v38
	v_exp_f32_e32 v94, v39
	v_exp_f32_e32 v95, v40
	v_exp_f32_e32 v132, v41
	v_exp_f32_e32 v133, v42
	v_exp_f32_e32 v134, v43
	v_exp_f32_e32 v135, v44
	v_exp_f32_e32 v144, v45
	v_exp_f32_e32 v145, v46
	v_exp_f32_e32 v146, v47
	ds_read_b128 v[20:23], v202 offset:8192
	ds_read_b128 v[24:27], v202 offset:8704
	ds_read_b128 v[28:31], v202 offset:10240
	ds_read_b128 v[36:39], v202 offset:10752
	ds_read_b128 v[40:43], v202 offset:12288
	ds_read_b128 v[44:47], v202 offset:12800
	ds_read_b128 v[84:87], v202 offset:14336
	ds_read_b128 v[88:91], v202 offset:14848
	v_exp_f32_e32 v53, v18
	v_exp_f32_e32 v54, v19
	s_waitcnt vmcnt(2) lgkmcnt(0)
	s_barrier
	v_exp_f32_e32 v147, v48
	v_exp_f32_e32 v148, v49
	v_exp_f32_e32 v149, v50
	v_exp_f32_e32 v150, v35
	ds_read_b64_tr_b16 v[16:17], v201 offset:24576
	ds_read_b64_tr_b16 v[18:19], v201 offset:25088
	s_waitcnt lgkmcnt(9)
	v_mfma_f32_32x32x16_bf16 v[96:111], v[20:23], v[140:143], v[0:15]
	v_add_f32_e32 v32, v51, v52
	v_add_f32_e32 v32, v32, v53
	v_add_f32_e32 v32, v32, v54
	v_add_f32_e32 v32, v32, v55
	v_add_f32_e32 v48, v32, v56
	v_cvt_pk_bf16_f32 v120, v51, v52
	v_cvt_pk_bf16_f32 v121, v53, v54
	ds_read_b64_tr_b16 v[32:33], v201 offset:28672
	ds_read_b64_tr_b16 v[34:35], v201 offset:29184
	s_waitcnt lgkmcnt(10)
	v_mfma_f32_32x32x16_bf16 v[64:79], v[24:27], v[140:143], v[0:15]
	v_add_f32_e32 v20, v57, v48
	v_add_f32_e32 v20, v58, v20
	v_add_f32_e32 v20, v59, v20
	v_add_f32_e32 v20, v60, v20
	v_cvt_pk_bf16_f32 v122, v55, v56
	v_cvt_pk_bf16_f32 v123, v57, v58
	ds_read_b64_tr_b16 v[48:49], v201 offset:25600
	ds_read_b64_tr_b16 v[50:51], v201 offset:26112
	s_waitcnt lgkmcnt(11)
	v_mfma_f32_32x32x16_bf16 v[96:111], v[28:31], v[136:139], v[96:111]
	v_add_f32_e32 v20, v61, v20
	v_add_f32_e32 v20, v62, v20
	v_add_f32_e32 v20, v63, v20
	v_add_f32_e32 v20, v80, v20
	v_cvt_pk_bf16_f32 v116, v59, v60
	v_cvt_pk_bf16_f32 v117, v61, v62
	ds_read_b64_tr_b16 v[52:53], v201 offset:29696
	ds_read_b64_tr_b16 v[54:55], v201 offset:30208
	s_waitcnt lgkmcnt(12)
	v_mfma_f32_32x32x16_bf16 v[64:79], v[36:39], v[136:139], v[64:79]
	v_add_f32_e32 v20, v81, v20
	v_add_f32_e32 v20, v82, v20
	v_add_f32_e32 v20, v83, v20
	v_add_f32_e32 v20, v92, v20
	v_cvt_pk_bf16_f32 v118, v63, v80
	v_cvt_pk_bf16_f32 v119, v81, v82
	ds_read_b64_tr_b16 v[56:57], v201 offset:26624
	ds_read_b64_tr_b16 v[58:59], v201 offset:27136
	s_waitcnt lgkmcnt(13)
	v_mfma_f32_32x32x16_bf16 v[96:111], v[40:43], v[128:131], v[96:111]
	v_add_f32_e32 v20, v93, v20
	v_add_f32_e32 v20, v94, v20
	v_add_f32_e32 v20, v95, v20
	v_add_f32_e32 v20, v132, v20
	v_cvt_pk_bf16_f32 v124, v83, v92
	v_cvt_pk_bf16_f32 v125, v93, v94
	ds_read_b64_tr_b16 v[60:61], v201 offset:30720
	ds_read_b64_tr_b16 v[62:63], v201 offset:31232
	s_waitcnt lgkmcnt(14)
	v_mfma_f32_32x32x16_bf16 v[64:79], v[44:47], v[128:131], v[64:79]
	v_add_f32_e32 v20, v133, v20
	v_add_f32_e32 v20, v134, v20
	v_add_f32_e32 v20, v135, v20
	v_add_f32_e32 v20, v144, v20
	v_cvt_pk_bf16_f32 v126, v95, v132
	v_cvt_pk_bf16_f32 v127, v133, v134
	ds_read_b64_tr_b16 v[80:81], v201 offset:27648
	ds_read_b64_tr_b16 v[82:83], v201 offset:28160
	s_waitcnt lgkmcnt(14)
	v_mfma_f32_32x32x16_bf16 v[96:111], v[84:87], v[112:115], v[96:111]
	v_add_f32_e32 v20, v145, v20
	v_add_f32_e32 v20, v146, v20
	v_add_f32_e32 v20, v147, v20
	v_add_f32_e32 v20, v148, v20
	v_cvt_pk_bf16_f32 v132, v135, v144
	v_cvt_pk_bf16_f32 v133, v145, v146
	ds_read_b64_tr_b16 v[84:85], v201 offset:31744
	ds_read_b64_tr_b16 v[86:87], v201 offset:32256
	v_mfma_f32_32x32x16_bf16 v[64:79], v[88:91], v[112:115], v[64:79]
	v_add_f32_e32 v20, v149, v20
	v_add_f32_e32 v20, v150, v20
	v_add_f32_e32 v20, 0, v20
	v_cvt_pk_bf16_f32 v134, v147, v148
	v_cvt_pk_bf16_f32 v135, v149, v150
	s_nop 0
	v_add_f32_e32 v203, 0, v20
	v_lshl_add_u64 v[20:21], v[180:181], 0, s[56:57]
	s_add_i32 s7, s7, 0xa000
	s_mov_b32 s8, m0
	s_mov_b32 m0, s7
	s_nop 0
	global_load_lds_dwordx4 v[20:21], off
	s_mov_b32 m0, s8
	v_max_f32_e32 v20, v97, v97
	v_max_f32_e32 v21, v96, v96
	v_max_f32_e32 v20, v21, v20
	v_max3_f32 v21, v98, v99, v65
	v_max3_f32 v20, v20, v64, v66
	v_max3_f32 v20, v20, v67, v100
	v_max3_f32 v21, v21, v102, v103
	v_max3_f32 v20, v20, v101, v68
	v_max3_f32 v21, v21, v70, v71
	v_max3_f32 v20, v20, v69, v104
	v_max3_f32 v21, v21, v106, v107
	v_max3_f32 v20, v20, v105, v72
	v_max3_f32 v21, v21, v74, v75
	v_max3_f32 v20, v20, v73, v108
	v_max3_f32 v21, v21, v110, v111
	v_max3_f32 v20, v20, v109, v76
	v_max3_f32 v21, v21, v78, v79
	v_max3_f32 v20, v20, v77, v21
	v_mov_b32_e32 v21, v20
	s_nop 1
	v_permlane32_swap_b32_e32 v20, v21
	v_max_f32_e32 v21, v21, v21
	v_max_f32_e32 v20, v20, v20
	v_max_f32_e32 v20, v20, v21
	v_cmp_lt_f32_e32 vcc, s21, v20
	s_cmp_lg_u64 vcc, 0
	s_cselect_b64 s[8:9], -1, 0
	s_cbranch_vccnz .LBB0_885
